# back-to-back s_setprio 0/1 pairs in the middle of the 32-MFMA blocks removed (priority stays raised through the block)
# speedup vs baseline: 1.0068x; 1.0068x over previous
; #define PG8_STAGE(bufoff, gbase, voff) do { _Pragma("unroll") for (int _i = 0; _i < 2; ++_i) \
;         __builtin_amdgcn_global_load_lds((const unsigned*)((const char*)(gbase) + (voff)[_i]), (PG8_LAS unsigned*)(lds + (bufoff) + ldsw + _i * 8192), 16, 0, 0); } while (0)
; #define PG8_LDA(dst, b, h) do { _Pragma("unroll") for (int m = 0; m < 4; ++m) _Pragma("unroll") for (int k = 0; k < 2; ++k) dst[m][k] = *(const PG8_LAS bf16x8*)(lds + PG8_SA(b, h) + aoff + m * 2048 + k * 1024); } while (0)
; #define PG8_LDB(dst, b, h) do { _Pragma("unroll") for (int n = 0; n < 2; ++n) _Pragma("unroll") for (int k = 0; k < 2; ++k) dst[n][k] = *(const PG8_LAS bf16x8*)(lds + PG8_SB(b, h) + boff + n * 2048 + k * 1024); } while (0)
; #define PG8_MMA(ai, bj, At, Bt) do { __builtin_amdgcn_s_setprio(1); _Pragma("unroll") for (int m = 0; m < 4; ++m) _Pragma("unroll") for (int n = 0; n < 2; ++n) _Pragma("unroll") for (int k = 0; k < 2; ++k) \
;         acc[ai][bj][m][n] = __builtin_amdgcn_mfma_f32_16x16x32_bf16(Bt[n][k], At[m][k], acc[ai][bj][m][n], 0, 0, 0); __builtin_amdgcn_s_setprio(0); } while (0)
; #define PG8_WAIT_V(n) asm volatile("s_waitcnt vmcnt(" #n ")" ::: "memory")
; #define PG8_WAIT_L(n) asm volatile("s_waitcnt lgkmcnt(" #n ")" ::: "memory")
; #define PG8_BAR __builtin_amdgcn_s_barrier()
; #define PG8_SCHED __builtin_amdgcn_sched_barrier(0)
; template <class Epi, class Sched, bool ALIGN_EPI = false, bool SP2 = false>
; __device__ __forceinline__ void gemm_phase(PG8_LAS unsigned char* lds, const Gemm g, const Sched& S, const Epi& E) {
;     ...
;             PG8_LDB(B0, 0, 0); PG8_LDB(B1, 0, 1); PG8_SCHED; PG8_LDA(At, 0, 0); PG8_STAGE(PG8_SA(1, 1), a1 + hstep, voffA);
;             PG8_WAIT_V(8); PG8_WAIT_L(0); PG8_BAR; PG8_MMA(0, 0, At, B0); PG8_MMA(0, 1, At, B1); PG8_BAR; PG8_SCHED;
;             PG8_LDA(At, 0, 1); PG8_STAGE(PG8_SB(0, 0), b2, voffB); PG8_STAGE(PG8_SB(0, 1), b2 + hstep, voffB); PG8_STAGE(PG8_SA(0, 0), a2, voffA);
;             PG8_WAIT_V(8); PG8_WAIT_L(0); PG8_BAR; PG8_MMA(1, 0, At, B0); PG8_MMA(1, 1, At, B1); PG8_BAR; PG8_SCHED;
;             PG8_LDB(B0, 1, 0); PG8_LDB(B1, 1, 1); PG8_SCHED; PG8_LDA(At, 1, 0); PG8_STAGE(PG8_SA(0, 1), a2 + hstep, voffA);
;             PG8_WAIT_V(8); PG8_WAIT_L(0); PG8_BAR; PG8_MMA(0, 0, At, B0); PG8_MMA(0, 1, At, B1); PG8_BAR; PG8_SCHED;
.LBB0_96:
	ds_read_b128 v[128:131], v178
	ds_read_b128 v[132:135], v178 offset:1024
	ds_read_b128 v[136:139], v178 offset:2048
	ds_read_b128 v[140:143], v178 offset:3072
	ds_read_b128 v[166:169], v179
	ds_read_b128 v[170:173], v179 offset:1024
	ds_read_b128 v[190:193], v179 offset:2048
	ds_read_b128 v[194:197], v179 offset:3072
	s_add_u32 s36, s80, 0xfffc0080
	s_addc_u32 s37, s81, -1
	s_cmp_eq_u32 s35, 12
	s_cselect_b32 s87, s8, s37
	s_cselect_b32 s86, s55, s36
	s_cselect_b32 s83, s49, s34
	s_cselect_b32 s82, vcc_lo, vcc_hi
	s_add_i32 m0, s93, 0xc000
	ds_read_b128 v[198:201], v181
	ds_read_b128 v[202:205], v181 offset:1024
	ds_read_b128 v[206:209], v181 offset:2048
	ds_read_b128 v[210:213], v181 offset:3072
	ds_read_b128 v[214:217], v181 offset:4096
	ds_read_b128 v[218:221], v181 offset:5120
	ds_read_b128 v[222:225], v181 offset:6144
	ds_read_b128 v[226:229], v181 offset:7168
	global_load_lds_dwordx4 v158, s[80:81]
	s_add_i32 m0, s93, 0xe000
	s_nop 0
	global_load_lds_dwordx4 v160, s[80:81]
	s_waitcnt vmcnt(8)
	s_waitcnt lgkmcnt(0)
	s_barrier
	s_setprio 1
	s_waitcnt lgkmcnt(0)
	v_mfma_f32_16x16x32_bf16 v[124:127], v[128:131], v[198:201], v[124:127]
	v_mfma_f32_16x16x32_bf16 v[120:123], v[136:139], v[198:201], v[120:123]
	v_mfma_f32_16x16x32_bf16 v[108:111], v[128:131], v[206:209], v[108:111]
	v_mfma_f32_16x16x32_bf16 v[104:107], v[136:139], v[206:209], v[104:107]
	v_mfma_f32_16x16x32_bf16 v[92:95], v[128:131], v[214:217], v[92:95]
	v_mfma_f32_16x16x32_bf16 v[88:91], v[136:139], v[214:217], v[88:91]
	v_mfma_f32_16x16x32_bf16 v[76:79], v[128:131], v[222:225], v[76:79]
	v_mfma_f32_16x16x32_bf16 v[72:75], v[136:139], v[222:225], v[72:75]
	v_mfma_f32_16x16x32_bf16 v[124:127], v[132:135], v[202:205], v[124:127]
	v_mfma_f32_16x16x32_bf16 v[120:123], v[140:143], v[202:205], v[120:123]
	v_mfma_f32_16x16x32_bf16 v[108:111], v[132:135], v[210:213], v[108:111]
	v_mfma_f32_16x16x32_bf16 v[104:107], v[140:143], v[210:213], v[104:107]
	v_mfma_f32_16x16x32_bf16 v[92:95], v[132:135], v[218:221], v[92:95]
	v_mfma_f32_16x16x32_bf16 v[88:91], v[140:143], v[218:221], v[88:91]
	v_mfma_f32_16x16x32_bf16 v[76:79], v[132:135], v[226:229], v[76:79]
	v_mfma_f32_16x16x32_bf16 v[72:75], v[140:143], v[226:229], v[72:75]
	v_mfma_f32_16x16x32_bf16 v[116:119], v[166:169], v[198:201], v[116:119]
	v_mfma_f32_16x16x32_bf16 v[112:115], v[190:193], v[198:201], v[112:115]
	v_mfma_f32_16x16x32_bf16 v[100:103], v[166:169], v[206:209], v[100:103]
	v_mfma_f32_16x16x32_bf16 v[96:99], v[190:193], v[206:209], v[96:99]
	v_mfma_f32_16x16x32_bf16 v[84:87], v[166:169], v[214:217], v[84:87]
	v_mfma_f32_16x16x32_bf16 v[80:83], v[190:193], v[214:217], v[80:83]
	v_mfma_f32_16x16x32_bf16 v[68:71], v[166:169], v[222:225], v[68:71]
	v_mfma_f32_16x16x32_bf16 v[64:67], v[190:193], v[222:225], v[64:67]
	v_mfma_f32_16x16x32_bf16 v[116:119], v[170:173], v[202:205], v[116:119]
	v_mfma_f32_16x16x32_bf16 v[112:115], v[194:197], v[202:205], v[112:115]
	v_mfma_f32_16x16x32_bf16 v[100:103], v[170:173], v[210:213], v[100:103]
	v_mfma_f32_16x16x32_bf16 v[96:99], v[194:197], v[210:213], v[96:99]
	v_mfma_f32_16x16x32_bf16 v[84:87], v[170:173], v[218:221], v[84:87]
	v_mfma_f32_16x16x32_bf16 v[80:83], v[194:197], v[218:221], v[80:83]
	v_mfma_f32_16x16x32_bf16 v[68:71], v[170:173], v[226:229], v[68:71]
	v_mfma_f32_16x16x32_bf16 v[64:67], v[194:197], v[226:229], v[64:67]
	s_setprio 0
	s_barrier
	s_add_i32 s36, s23, s90
	v_lshl_add_u64 v[174:175], s[82:83], 0, v[148:149]
	s_mov_b32 m0, s36
	ds_read_b128 v[198:201], v181 offset:16384
	ds_read_b128 v[202:205], v181 offset:17408
	ds_read_b128 v[206:209], v181 offset:18432
	ds_read_b128 v[210:213], v181 offset:19456
	ds_read_b128 v[214:217], v181 offset:20480
	ds_read_b128 v[218:221], v181 offset:21504
	ds_read_b128 v[222:225], v181 offset:22528
	ds_read_b128 v[226:229], v181 offset:23552
	global_load_lds_dwordx4 v[174:175], off
	s_add_i32 m0, s36, 0x2000
	s_add_u32 s36, s82, 0x40000
	v_lshl_add_u64 v[186:187], s[82:83], 0, v[144:145]
	s_addc_u32 s37, s83, 0
	s_add_i32 s20, s41, s90
	global_load_lds_dwordx4 v[186:187], off
	s_mov_b32 m0, s20
	v_lshl_add_u64 v[232:233], s[86:87], 0, v[146:147]
	global_load_lds_dwordx4 v148, s[36:37]
	s_add_i32 m0, s20, 0x2000
	s_nop 0
	global_load_lds_dwordx4 v144, s[36:37]
	v_lshl_add_u64 v[230:231], s[86:87], 0, v[150:151]
	s_mov_b32 m0, s93
	s_nop 0
	global_load_lds_dwordx4 v[230:231], off
	s_mov_b32 m0, s94
	s_nop 0
	global_load_lds_dwordx4 v[232:233], off
	s_waitcnt vmcnt(8)
	s_waitcnt lgkmcnt(0)
	s_barrier
	s_setprio 1
	s_waitcnt lgkmcnt(0)
	v_mfma_f32_16x16x32_bf16 v[60:63], v[128:131], v[198:201], v[60:63]
	v_mfma_f32_16x16x32_bf16 v[56:59], v[136:139], v[198:201], v[56:59]
	v_mfma_f32_16x16x32_bf16 v[44:47], v[128:131], v[206:209], v[44:47]
	v_mfma_f32_16x16x32_bf16 v[40:43], v[136:139], v[206:209], v[40:43]
	v_mfma_f32_16x16x32_bf16 v[28:31], v[128:131], v[214:217], v[28:31]
	v_mfma_f32_16x16x32_bf16 v[24:27], v[136:139], v[214:217], v[24:27]
	v_mfma_f32_16x16x32_bf16 v[12:15], v[128:131], v[222:225], v[12:15]
	v_mfma_f32_16x16x32_bf16 v[8:11], v[136:139], v[222:225], v[8:11]
	v_mfma_f32_16x16x32_bf16 v[60:63], v[132:135], v[202:205], v[60:63]
	v_mfma_f32_16x16x32_bf16 v[56:59], v[140:143], v[202:205], v[56:59]
	v_mfma_f32_16x16x32_bf16 v[44:47], v[132:135], v[210:213], v[44:47]
	v_mfma_f32_16x16x32_bf16 v[40:43], v[140:143], v[210:213], v[40:43]
	v_mfma_f32_16x16x32_bf16 v[28:31], v[132:135], v[218:221], v[28:31]
	v_mfma_f32_16x16x32_bf16 v[24:27], v[140:143], v[218:221], v[24:27]
	v_mfma_f32_16x16x32_bf16 v[12:15], v[132:135], v[226:229], v[12:15]
	v_mfma_f32_16x16x32_bf16 v[8:11], v[140:143], v[226:229], v[8:11]
	v_mfma_f32_16x16x32_bf16 v[52:55], v[166:169], v[198:201], v[52:55]
	v_mfma_f32_16x16x32_bf16 v[48:51], v[190:193], v[198:201], v[48:51]
	v_mfma_f32_16x16x32_bf16 v[36:39], v[166:169], v[206:209], v[36:39]
	v_mfma_f32_16x16x32_bf16 v[32:35], v[190:193], v[206:209], v[32:35]
	v_mfma_f32_16x16x32_bf16 v[20:23], v[166:169], v[214:217], v[20:23]
	v_mfma_f32_16x16x32_bf16 v[16:19], v[190:193], v[214:217], v[16:19]
	v_mfma_f32_16x16x32_bf16 v[4:7], v[166:169], v[222:225], v[4:7]
	v_mfma_f32_16x16x32_bf16 v[0:3], v[190:193], v[222:225], v[0:3]
	v_mfma_f32_16x16x32_bf16 v[52:55], v[170:173], v[202:205], v[52:55]
	v_mfma_f32_16x16x32_bf16 v[48:51], v[194:197], v[202:205], v[48:51]
	v_mfma_f32_16x16x32_bf16 v[36:39], v[170:173], v[210:213], v[36:39]
	v_mfma_f32_16x16x32_bf16 v[32:35], v[194:197], v[210:213], v[32:35]
	v_mfma_f32_16x16x32_bf16 v[20:23], v[170:173], v[218:221], v[20:23]
	v_mfma_f32_16x16x32_bf16 v[16:19], v[194:197], v[218:221], v[16:19]
	v_mfma_f32_16x16x32_bf16 v[4:7], v[170:173], v[226:229], v[4:7]
	v_mfma_f32_16x16x32_bf16 v[0:3], v[194:197], v[226:229], v[0:3]
	s_setprio 0
	s_barrier
; #define PG8_STAGE(bufoff, gbase, voff) do { _Pragma("unroll") for (int _i = 0; _i < 2; ++_i) \
;         __builtin_amdgcn_global_load_lds((const unsigned*)((const char*)(gbase) + (voff)[_i]), (PG8_LAS unsigned*)(lds + (bufoff) + ldsw + _i * 8192), 16, 0, 0); } while (0)
; #define PG8_LDA(dst, b, h) do { _Pragma("unroll") for (int m = 0; m < 4; ++m) _Pragma("unroll") for (int k = 0; k < 2; ++k) dst[m][k] = *(const PG8_LAS bf16x8*)(lds + PG8_SA(b, h) + aoff + m * 2048 + k * 1024); } while (0)
; #define PG8_LDB(dst, b, h) do { _Pragma("unroll") for (int n = 0; n < 2; ++n) _Pragma("unroll") for (int k = 0; k < 2; ++k) dst[n][k] = *(const PG8_LAS bf16x8*)(lds + PG8_SB(b, h) + boff + n * 2048 + k * 1024); } while (0)
; #define PG8_MMA(ai, bj, At, Bt) do { __builtin_amdgcn_s_setprio(1); _Pragma("unroll") for (int m = 0; m < 4; ++m) _Pragma("unroll") for (int n = 0; n < 2; ++n) _Pragma("unroll") for (int k = 0; k < 2; ++k) \
;         acc[ai][bj][m][n] = __builtin_amdgcn_mfma_f32_16x16x32_bf16(Bt[n][k], At[m][k], acc[ai][bj][m][n], 0, 0, 0); __builtin_amdgcn_s_setprio(0); } while (0)
; #define PG8_WAIT_V(n) asm volatile("s_waitcnt vmcnt(" #n ")" ::: "memory")
; #define PG8_WAIT_L(n) asm volatile("s_waitcnt lgkmcnt(" #n ")" ::: "memory")
; #define PG8_BAR __builtin_amdgcn_s_barrier()
; #define PG8_SCHED __builtin_amdgcn_sched_barrier(0)
; template <class Epi, class Sched, bool ALIGN_EPI = false, bool SP2 = false>
; __device__ __forceinline__ void gemm_phase(PG8_LAS unsigned char* lds, const Gemm g, const Sched& S, const Epi& E) {
;     ...
;             PG8_LDB(B0, 1, 0); PG8_LDB(B1, 1, 1); PG8_SCHED; PG8_LDA(At, 1, 0); PG8_STAGE(PG8_SA(0, 1), a2 + hstep, voffA);
;             PG8_WAIT_V(8); PG8_WAIT_L(0); PG8_BAR; PG8_MMA(0, 0, At, B0); PG8_MMA(0, 1, At, B1); PG8_BAR; PG8_SCHED;
;             PG8_LDA(At, 1, 1); PG8_STAGE(PG8_SB(1, 0), b3, voffB); PG8_STAGE(PG8_SB(1, 1), b3 + hstep, voffB); PG8_STAGE(PG8_SA(1, 0), a3, voffA);
;             PG8_WAIT_V(8); PG8_WAIT_L(0); PG8_BAR; PG8_MMA(1, 0, At, B0); PG8_MMA(1, 1, At, B1); PG8_BAR; PG8_SCHED;
	s_add_i32 s20, 0, 0x18000
	s_add_i32 s21, 0, 0x1c000
	v_add_u32_e32 v140, s20, v176
	v_add_u32_e32 v152, s21, v176
	ds_read_b128 v[128:131], v140
	ds_read_b128 v[132:135], v140 offset:1024
	ds_read_b128 v[136:139], v140 offset:2048
	ds_read_b128 v[140:143], v140 offset:3072
	ds_read_b128 v[166:169], v152
	ds_read_b128 v[170:173], v152 offset:1024
	ds_read_b128 v[190:193], v152 offset:2048
	ds_read_b128 v[194:197], v152 offset:3072
	s_add_u32 s36, s86, 0x40000
	s_addc_u32 s37, s87, 0
	s_mov_b32 m0, s95
	ds_read_b128 v[198:201], v181 offset:32768
	ds_read_b128 v[202:205], v181 offset:33792
	ds_read_b128 v[206:209], v181 offset:34816
	ds_read_b128 v[210:213], v181 offset:35840
	ds_read_b128 v[214:217], v181 offset:36864
	ds_read_b128 v[218:221], v181 offset:37888
	ds_read_b128 v[222:225], v181 offset:38912
	ds_read_b128 v[226:229], v181 offset:39936
	global_load_lds_dwordx4 v150, s[36:37]
	s_mov_b32 m0, s97
	s_nop 0
	global_load_lds_dwordx4 v146, s[36:37]
	s_waitcnt vmcnt(8)
	s_waitcnt lgkmcnt(0)
	s_barrier
	s_setprio 1
	s_waitcnt lgkmcnt(0)
	v_mfma_f32_16x16x32_bf16 v[124:127], v[128:131], v[198:201], v[124:127]
	v_mfma_f32_16x16x32_bf16 v[120:123], v[136:139], v[198:201], v[120:123]
	v_mfma_f32_16x16x32_bf16 v[108:111], v[128:131], v[206:209], v[108:111]
	v_mfma_f32_16x16x32_bf16 v[104:107], v[136:139], v[206:209], v[104:107]
	v_mfma_f32_16x16x32_bf16 v[92:95], v[128:131], v[214:217], v[92:95]
	v_mfma_f32_16x16x32_bf16 v[88:91], v[136:139], v[214:217], v[88:91]
	v_mfma_f32_16x16x32_bf16 v[76:79], v[128:131], v[222:225], v[76:79]
	v_mfma_f32_16x16x32_bf16 v[72:75], v[136:139], v[222:225], v[72:75]
	v_mfma_f32_16x16x32_bf16 v[124:127], v[132:135], v[202:205], v[124:127]
	v_mfma_f32_16x16x32_bf16 v[120:123], v[140:143], v[202:205], v[120:123]
	v_mfma_f32_16x16x32_bf16 v[108:111], v[132:135], v[210:213], v[108:111]
	v_mfma_f32_16x16x32_bf16 v[104:107], v[140:143], v[210:213], v[104:107]
	v_mfma_f32_16x16x32_bf16 v[92:95], v[132:135], v[218:221], v[92:95]
	v_mfma_f32_16x16x32_bf16 v[88:91], v[140:143], v[218:221], v[88:91]
	v_mfma_f32_16x16x32_bf16 v[76:79], v[132:135], v[226:229], v[76:79]
	v_mfma_f32_16x16x32_bf16 v[72:75], v[140:143], v[226:229], v[72:75]
	v_mfma_f32_16x16x32_bf16 v[116:119], v[166:169], v[198:201], v[116:119]
	v_mfma_f32_16x16x32_bf16 v[112:115], v[190:193], v[198:201], v[112:115]
	v_mfma_f32_16x16x32_bf16 v[100:103], v[166:169], v[206:209], v[100:103]
	v_mfma_f32_16x16x32_bf16 v[96:99], v[190:193], v[206:209], v[96:99]
	v_mfma_f32_16x16x32_bf16 v[84:87], v[166:169], v[214:217], v[84:87]
	v_mfma_f32_16x16x32_bf16 v[80:83], v[190:193], v[214:217], v[80:83]
	v_mfma_f32_16x16x32_bf16 v[68:71], v[166:169], v[222:225], v[68:71]
	v_mfma_f32_16x16x32_bf16 v[64:67], v[190:193], v[222:225], v[64:67]
	v_mfma_f32_16x16x32_bf16 v[116:119], v[170:173], v[202:205], v[116:119]
	v_mfma_f32_16x16x32_bf16 v[112:115], v[194:197], v[202:205], v[112:115]
	v_mfma_f32_16x16x32_bf16 v[100:103], v[170:173], v[210:213], v[100:103]
	v_mfma_f32_16x16x32_bf16 v[96:99], v[194:197], v[210:213], v[96:99]
	v_mfma_f32_16x16x32_bf16 v[84:87], v[170:173], v[218:221], v[84:87]
	v_mfma_f32_16x16x32_bf16 v[80:83], v[194:197], v[218:221], v[80:83]
	v_mfma_f32_16x16x32_bf16 v[68:71], v[170:173], v[226:229], v[68:71]
	v_mfma_f32_16x16x32_bf16 v[64:67], v[194:197], v[226:229], v[64:67]
	s_setprio 0
	s_barrier
	s_add_i32 s20, s20, s90
	v_lshl_add_u64 v[174:175], v[174:175], 0, s[26:27]
	s_mov_b32 m0, s20
	ds_read_b128 v[198:201], v181 offset:49152
	ds_read_b128 v[202:205], v181 offset:50176
	ds_read_b128 v[206:209], v181 offset:51200
	ds_read_b128 v[210:213], v181 offset:52224
	ds_read_b128 v[214:217], v181 offset:53248
	ds_read_b128 v[218:221], v181 offset:54272
	ds_read_b128 v[222:225], v181 offset:55296
	ds_read_b128 v[226:229], v181 offset:56320
	global_load_lds_dwordx4 v[174:175], off
	s_add_i32 m0, s20, 0x2000
	s_add_u32 s36, s82, 0x40080
	v_lshl_add_u64 v[174:175], v[186:187], 0, s[26:27]
	s_addc_u32 s37, s83, 0
	s_add_i32 s20, s21, s90
	global_load_lds_dwordx4 v[174:175], off
	s_mov_b32 m0, s20
	s_nop 0
	global_load_lds_dwordx4 v148, s[36:37]
	s_add_i32 m0, s20, 0x2000
	s_nop 0
	global_load_lds_dwordx4 v144, s[36:37]
	v_lshl_add_u64 v[174:175], v[230:231], 0, s[26:27]
	s_mov_b32 m0, s42
	s_nop 0
	global_load_lds_dwordx4 v[174:175], off
	v_lshl_add_u64 v[174:175], v[232:233], 0, s[26:27]
	s_mov_b32 m0, s43
	s_nop 0
	global_load_lds_dwordx4 v[174:175], off
	s_waitcnt vmcnt(8)
	s_waitcnt lgkmcnt(0)
	s_barrier
	s_setprio 1
	s_waitcnt lgkmcnt(0)
	v_mfma_f32_16x16x32_bf16 v[60:63], v[128:131], v[198:201], v[60:63]
	v_mfma_f32_16x16x32_bf16 v[56:59], v[136:139], v[198:201], v[56:59]
	v_mfma_f32_16x16x32_bf16 v[44:47], v[128:131], v[206:209], v[44:47]
	v_mfma_f32_16x16x32_bf16 v[40:43], v[136:139], v[206:209], v[40:43]
	v_mfma_f32_16x16x32_bf16 v[28:31], v[128:131], v[214:217], v[28:31]
	v_mfma_f32_16x16x32_bf16 v[24:27], v[136:139], v[214:217], v[24:27]
	v_mfma_f32_16x16x32_bf16 v[12:15], v[128:131], v[222:225], v[12:15]
	v_mfma_f32_16x16x32_bf16 v[8:11], v[136:139], v[222:225], v[8:11]
	v_mfma_f32_16x16x32_bf16 v[60:63], v[132:135], v[202:205], v[60:63]
	v_mfma_f32_16x16x32_bf16 v[56:59], v[140:143], v[202:205], v[56:59]
	v_mfma_f32_16x16x32_bf16 v[44:47], v[132:135], v[210:213], v[44:47]
	v_mfma_f32_16x16x32_bf16 v[40:43], v[140:143], v[210:213], v[40:43]
	v_mfma_f32_16x16x32_bf16 v[28:31], v[132:135], v[218:221], v[28:31]
	v_mfma_f32_16x16x32_bf16 v[24:27], v[140:143], v[218:221], v[24:27]
	v_mfma_f32_16x16x32_bf16 v[12:15], v[132:135], v[226:229], v[12:15]
	v_mfma_f32_16x16x32_bf16 v[8:11], v[140:143], v[226:229], v[8:11]
	v_mfma_f32_16x16x32_bf16 v[52:55], v[166:169], v[198:201], v[52:55]
	v_mfma_f32_16x16x32_bf16 v[48:51], v[190:193], v[198:201], v[48:51]
	v_mfma_f32_16x16x32_bf16 v[36:39], v[166:169], v[206:209], v[36:39]
	v_mfma_f32_16x16x32_bf16 v[32:35], v[190:193], v[206:209], v[32:35]
	v_mfma_f32_16x16x32_bf16 v[20:23], v[166:169], v[214:217], v[20:23]
	v_mfma_f32_16x16x32_bf16 v[16:19], v[190:193], v[214:217], v[16:19]
	v_mfma_f32_16x16x32_bf16 v[4:7], v[166:169], v[222:225], v[4:7]
	v_mfma_f32_16x16x32_bf16 v[0:3], v[190:193], v[222:225], v[0:3]
	v_mfma_f32_16x16x32_bf16 v[52:55], v[170:173], v[202:205], v[52:55]
	v_mfma_f32_16x16x32_bf16 v[48:51], v[194:197], v[202:205], v[48:51]
	v_mfma_f32_16x16x32_bf16 v[36:39], v[170:173], v[210:213], v[36:39]
	v_mfma_f32_16x16x32_bf16 v[32:35], v[194:197], v[210:213], v[32:35]
	v_mfma_f32_16x16x32_bf16 v[20:23], v[170:173], v[218:221], v[20:23]
	v_mfma_f32_16x16x32_bf16 v[16:19], v[194:197], v[218:221], v[16:19]
	v_mfma_f32_16x16x32_bf16 v[4:7], v[170:173], v[226:229], v[4:7]
	v_mfma_f32_16x16x32_bf16 v[0:3], v[194:197], v[226:229], v[0:3]
	s_setprio 0
	s_barrier
	s_add_i32 s35, s35, 2
	s_add_u32 s80, s80, 0x100
	s_addc_u32 s81, s81, 0
	s_add_u32 vcc_hi, vcc_hi, 0x100
	s_addc_u32 s34, s34, 0
	s_cmp_gt_u32 s35, 13
	s_cbranch_scc0 .LBB0_96
	s_and_b64 vcc, exec, s[28:29]
	s_cbranch_vccz .LBB0_99
	s_barrier

; #define PG8_STAGE(bufoff, gbase, voff) do { _Pragma("unroll") for (int _i = 0; _i < 2; ++_i) \
;         __builtin_amdgcn_global_load_lds((const unsigned*)((const char*)(gbase) + (voff)[_i]), (PG8_LAS unsigned*)(lds + (bufoff) + ldsw + _i * 8192), 16, 0, 0); } while (0)
; #define PG8_LDA(dst, b, h) do { _Pragma("unroll") for (int m = 0; m < 4; ++m) _Pragma("unroll") for (int k = 0; k < 2; ++k) dst[m][k] = *(const PG8_LAS bf16x8*)(lds + PG8_SA(b, h) + aoff + m * 2048 + k * 1024); } while (0)
; #define PG8_LDB(dst, b, h) do { _Pragma("unroll") for (int n = 0; n < 2; ++n) _Pragma("unroll") for (int k = 0; k < 2; ++k) dst[n][k] = *(const PG8_LAS bf16x8*)(lds + PG8_SB(b, h) + boff + n * 2048 + k * 1024); } while (0)
; #define PG8_MMA(ai, bj, At, Bt) do { __builtin_amdgcn_s_setprio(1); _Pragma("unroll") for (int m = 0; m < 4; ++m) _Pragma("unroll") for (int n = 0; n < 2; ++n) _Pragma("unroll") for (int k = 0; k < 2; ++k) \
;         acc[ai][bj][m][n] = __builtin_amdgcn_mfma_f32_16x16x32_bf16(Bt[n][k], At[m][k], acc[ai][bj][m][n], 0, 0, 0); __builtin_amdgcn_s_setprio(0); } while (0)
; #define PG8_WAIT_V(n) asm volatile("s_waitcnt vmcnt(" #n ")" ::: "memory")
; #define PG8_WAIT_L(n) asm volatile("s_waitcnt lgkmcnt(" #n ")" ::: "memory")
; #define PG8_BAR __builtin_amdgcn_s_barrier()
; #define PG8_SCHED __builtin_amdgcn_sched_barrier(0)
; template <class Epi, class Sched, bool ALIGN_EPI = false, bool SP2 = false>
; __device__ __forceinline__ void gemm_phase(PG8_LAS unsigned char* lds, const Gemm g, const Sched& S, const Epi& E) {
;     ...
;             PG8_LDB(B0, 0, 0); PG8_LDB(B1, 0, 1); PG8_SCHED; PG8_LDA(At, 0, 0); PG8_STAGE(PG8_SA(1, 1), a1 + hstep, voffA);
;             PG8_WAIT_V(8); PG8_WAIT_L(0); PG8_BAR; PG8_MMA(0, 0, At, B0); PG8_MMA(0, 1, At, B1); PG8_BAR; PG8_SCHED;
;             PG8_LDA(At, 0, 1); PG8_STAGE(PG8_SB(0, 0), b2, voffB); PG8_STAGE(PG8_SB(0, 1), b2 + hstep, voffB); PG8_STAGE(PG8_SA(0, 0), a2, voffA);
;             PG8_WAIT_V(8); PG8_WAIT_L(0); PG8_BAR; PG8_MMA(1, 0, At, B0); PG8_MMA(1, 1, At, B1); PG8_BAR; PG8_SCHED;
.LBB0_150:
	s_add_u32 s24, s22, 0xfffc0080
	s_addc_u32 s25, s23, -1
	s_waitcnt lgkmcnt(0)
	s_add_i32 s54, 0, 0x10000
	v_add_u32_e32 v147, s54, v152
	ds_read_b128 v[156:159], v147
	ds_read_b128 v[160:163], v147 offset:1024
	ds_read_b128 v[164:167], v147 offset:2048
	ds_read_b128 v[168:171], v147 offset:3072
	ds_read_b128 v[172:175], v154
	ds_read_b128 v[176:179], v154 offset:1024
	ds_read_b128 v[182:185], v154 offset:2048
	ds_read_b128 v[190:193], v154 offset:3072
	s_cmp_eq_u32 s49, 12
	s_cselect_b32 s27, s17, s25
	s_cselect_b32 s26, s45, s24
	s_cselect_b32 s25, s15, s48
	s_cselect_b32 s24, s46, s47
	s_add_i32 m0, s13, 0xc000
	ds_read_b128 v[194:197], v155
	ds_read_b128 v[198:201], v155 offset:1024
	ds_read_b128 v[202:205], v155 offset:2048
	ds_read_b128 v[206:209], v155 offset:3072
	ds_read_b128 v[210:213], v155 offset:4096
	ds_read_b128 v[214:217], v155 offset:5120
	ds_read_b128 v[218:221], v155 offset:6144
	ds_read_b128 v[222:225], v155 offset:7168
	global_load_lds_dwordx4 v138, s[22:23]
	s_add_i32 m0, s13, 0xe000
	s_nop 0
	global_load_lds_dwordx4 v140, s[22:23]
	s_waitcnt vmcnt(8)
	s_waitcnt lgkmcnt(0)
	s_barrier
	s_setprio 1
	s_waitcnt lgkmcnt(0)
	v_mfma_f32_16x16x32_bf16 v[124:127], v[156:159], v[194:197], v[124:127]
	v_mfma_f32_16x16x32_bf16 v[120:123], v[164:167], v[194:197], v[120:123]
	v_mfma_f32_16x16x32_bf16 v[116:119], v[156:159], v[202:205], v[116:119]
	v_mfma_f32_16x16x32_bf16 v[112:115], v[164:167], v[202:205], v[112:115]
	v_mfma_f32_16x16x32_bf16 v[100:103], v[156:159], v[210:213], v[100:103]
	v_mfma_f32_16x16x32_bf16 v[96:99], v[164:167], v[210:213], v[96:99]
	v_mfma_f32_16x16x32_bf16 v[84:87], v[156:159], v[218:221], v[84:87]
	v_mfma_f32_16x16x32_bf16 v[80:83], v[164:167], v[218:221], v[80:83]
	v_mfma_f32_16x16x32_bf16 v[124:127], v[160:163], v[198:201], v[124:127]
	v_mfma_f32_16x16x32_bf16 v[120:123], v[168:171], v[198:201], v[120:123]
	v_mfma_f32_16x16x32_bf16 v[116:119], v[160:163], v[206:209], v[116:119]
	v_mfma_f32_16x16x32_bf16 v[112:115], v[168:171], v[206:209], v[112:115]
	v_mfma_f32_16x16x32_bf16 v[100:103], v[160:163], v[214:217], v[100:103]
	v_mfma_f32_16x16x32_bf16 v[96:99], v[168:171], v[214:217], v[96:99]
	v_mfma_f32_16x16x32_bf16 v[84:87], v[160:163], v[222:225], v[84:87]
	v_mfma_f32_16x16x32_bf16 v[80:83], v[168:171], v[222:225], v[80:83]
	v_mfma_f32_16x16x32_bf16 v[108:111], v[172:175], v[194:197], v[108:111]
	v_mfma_f32_16x16x32_bf16 v[104:107], v[182:185], v[194:197], v[104:107]
	v_mfma_f32_16x16x32_bf16 v[92:95], v[172:175], v[202:205], v[92:95]
	v_mfma_f32_16x16x32_bf16 v[88:91], v[182:185], v[202:205], v[88:91]
	v_mfma_f32_16x16x32_bf16 v[76:79], v[172:175], v[210:213], v[76:79]
	v_mfma_f32_16x16x32_bf16 v[72:75], v[182:185], v[210:213], v[72:75]
	v_mfma_f32_16x16x32_bf16 v[68:71], v[172:175], v[218:221], v[68:71]
	v_mfma_f32_16x16x32_bf16 v[64:67], v[182:185], v[218:221], v[64:67]
	v_mfma_f32_16x16x32_bf16 v[108:111], v[176:179], v[198:201], v[108:111]
	v_mfma_f32_16x16x32_bf16 v[104:107], v[190:193], v[198:201], v[104:107]
	v_mfma_f32_16x16x32_bf16 v[92:95], v[176:179], v[206:209], v[92:95]
	v_mfma_f32_16x16x32_bf16 v[88:91], v[190:193], v[206:209], v[88:91]
	v_mfma_f32_16x16x32_bf16 v[76:79], v[176:179], v[214:217], v[76:79]
	v_mfma_f32_16x16x32_bf16 v[72:75], v[190:193], v[214:217], v[72:75]
	v_mfma_f32_16x16x32_bf16 v[68:71], v[176:179], v[222:225], v[68:71]
	v_mfma_f32_16x16x32_bf16 v[64:67], v[190:193], v[222:225], v[64:67]
	s_setprio 0
	s_barrier
	s_add_i32 s54, s54, s31
	v_lshl_add_u64 v[186:187], s[24:25], 0, v[130:131]
	s_mov_b32 m0, s54
	ds_read_b128 v[194:197], v155 offset:16384
	ds_read_b128 v[198:201], v155 offset:17408
	ds_read_b128 v[202:205], v155 offset:18432
	ds_read_b128 v[206:209], v155 offset:19456
	ds_read_b128 v[210:213], v155 offset:20480
	ds_read_b128 v[214:217], v155 offset:21504
	ds_read_b128 v[218:221], v155 offset:22528
	ds_read_b128 v[222:225], v155 offset:23552
	global_load_lds_dwordx4 v[186:187], off
	s_add_i32 m0, s54, 0x2000
	s_add_u32 s54, s24, 0x40000
	v_lshl_add_u64 v[226:227], s[24:25], 0, v[134:135]
	s_addc_u32 s55, s25, 0
	s_add_i32 s76, s43, s31
	global_load_lds_dwordx4 v[226:227], off
	s_mov_b32 m0, s76
	v_lshl_add_u64 v[230:231], s[26:27], 0, v[132:133]
	global_load_lds_dwordx4 v130, s[54:55]
	s_add_i32 m0, s76, 0x2000
	s_nop 0
	global_load_lds_dwordx4 v134, s[54:55]
	v_lshl_add_u64 v[228:229], s[26:27], 0, v[128:129]
	s_mov_b32 m0, s13
	s_nop 0
	global_load_lds_dwordx4 v[228:229], off
	s_mov_b32 m0, s34
	s_nop 0
	global_load_lds_dwordx4 v[230:231], off
	s_waitcnt vmcnt(8)
	s_waitcnt lgkmcnt(0)
	s_barrier
; #define PG8_STAGE(bufoff, gbase, voff) do { _Pragma("unroll") for (int _i = 0; _i < 2; ++_i) \
;         __builtin_amdgcn_global_load_lds((const unsigned*)((const char*)(gbase) + (voff)[_i]), (PG8_LAS unsigned*)(lds + (bufoff) + ldsw + _i * 8192), 16, 0, 0); } while (0)
; #define PG8_LDA(dst, b, h) do { _Pragma("unroll") for (int m = 0; m < 4; ++m) _Pragma("unroll") for (int k = 0; k < 2; ++k) dst[m][k] = *(const PG8_LAS bf16x8*)(lds + PG8_SA(b, h) + aoff + m * 2048 + k * 1024); } while (0)
; #define PG8_LDB(dst, b, h) do { _Pragma("unroll") for (int n = 0; n < 2; ++n) _Pragma("unroll") for (int k = 0; k < 2; ++k) dst[n][k] = *(const PG8_LAS bf16x8*)(lds + PG8_SB(b, h) + boff + n * 2048 + k * 1024); } while (0)
; #define PG8_MMA(ai, bj, At, Bt) do { __builtin_amdgcn_s_setprio(1); _Pragma("unroll") for (int m = 0; m < 4; ++m) _Pragma("unroll") for (int n = 0; n < 2; ++n) _Pragma("unroll") for (int k = 0; k < 2; ++k) \
;         acc[ai][bj][m][n] = __builtin_amdgcn_mfma_f32_16x16x32_bf16(Bt[n][k], At[m][k], acc[ai][bj][m][n], 0, 0, 0); __builtin_amdgcn_s_setprio(0); } while (0)
; #define PG8_WAIT_V(n) asm volatile("s_waitcnt vmcnt(" #n ")" ::: "memory")
; #define PG8_WAIT_L(n) asm volatile("s_waitcnt lgkmcnt(" #n ")" ::: "memory")
; #define PG8_BAR __builtin_amdgcn_s_barrier()
; #define PG8_SCHED __builtin_amdgcn_sched_barrier(0)
; template <class Epi, class Sched, bool ALIGN_EPI = false, bool SP2 = false>
; __device__ __forceinline__ void gemm_phase(PG8_LAS unsigned char* lds, const Gemm g, const Sched& S, const Epi& E) {
;     ...
;             PG8_WAIT_V(8); PG8_WAIT_L(0); PG8_BAR; PG8_MMA(1, 0, At, B0); PG8_MMA(1, 1, At, B1); PG8_BAR; PG8_SCHED;
;             PG8_LDB(B0, 1, 0); PG8_LDB(B1, 1, 1); PG8_SCHED; PG8_LDA(At, 1, 0); PG8_STAGE(PG8_SA(0, 1), a2 + hstep, voffA);
;             PG8_WAIT_V(8); PG8_WAIT_L(0); PG8_BAR; PG8_MMA(0, 0, At, B0); PG8_MMA(0, 1, At, B1); PG8_BAR; PG8_SCHED;
;             PG8_LDA(At, 1, 1); PG8_STAGE(PG8_SB(1, 0), b3, voffB); PG8_STAGE(PG8_SB(1, 1), b3 + hstep, voffB); PG8_STAGE(PG8_SA(1, 0), a3, voffA);
	s_setprio 1
	s_waitcnt lgkmcnt(0)
	v_mfma_f32_16x16x32_bf16 v[60:63], v[156:159], v[194:197], v[60:63]
	v_mfma_f32_16x16x32_bf16 v[56:59], v[164:167], v[194:197], v[56:59]
	v_mfma_f32_16x16x32_bf16 v[52:55], v[156:159], v[202:205], v[52:55]
	v_mfma_f32_16x16x32_bf16 v[48:51], v[164:167], v[202:205], v[48:51]
	v_mfma_f32_16x16x32_bf16 v[36:39], v[156:159], v[210:213], v[36:39]
	v_mfma_f32_16x16x32_bf16 v[32:35], v[164:167], v[210:213], v[32:35]
	v_mfma_f32_16x16x32_bf16 v[20:23], v[156:159], v[218:221], v[20:23]
	v_mfma_f32_16x16x32_bf16 v[16:19], v[164:167], v[218:221], v[16:19]
	v_mfma_f32_16x16x32_bf16 v[60:63], v[160:163], v[198:201], v[60:63]
	v_mfma_f32_16x16x32_bf16 v[56:59], v[168:171], v[198:201], v[56:59]
	v_mfma_f32_16x16x32_bf16 v[52:55], v[160:163], v[206:209], v[52:55]
	v_mfma_f32_16x16x32_bf16 v[48:51], v[168:171], v[206:209], v[48:51]
	v_mfma_f32_16x16x32_bf16 v[36:39], v[160:163], v[214:217], v[36:39]
	v_mfma_f32_16x16x32_bf16 v[32:35], v[168:171], v[214:217], v[32:35]
	v_mfma_f32_16x16x32_bf16 v[20:23], v[160:163], v[222:225], v[20:23]
	v_mfma_f32_16x16x32_bf16 v[16:19], v[168:171], v[222:225], v[16:19]
	v_mfma_f32_16x16x32_bf16 v[44:47], v[172:175], v[194:197], v[44:47]
	v_mfma_f32_16x16x32_bf16 v[40:43], v[182:185], v[194:197], v[40:43]
	v_mfma_f32_16x16x32_bf16 v[28:31], v[172:175], v[202:205], v[28:31]
	v_mfma_f32_16x16x32_bf16 v[24:27], v[182:185], v[202:205], v[24:27]
	v_mfma_f32_16x16x32_bf16 v[12:15], v[172:175], v[210:213], v[12:15]
	v_mfma_f32_16x16x32_bf16 v[8:11], v[182:185], v[210:213], v[8:11]
	v_mfma_f32_16x16x32_bf16 v[4:7], v[172:175], v[218:221], v[4:7]
	v_mfma_f32_16x16x32_bf16 v[0:3], v[182:185], v[218:221], v[0:3]
	v_mfma_f32_16x16x32_bf16 v[44:47], v[176:179], v[198:201], v[44:47]
	v_mfma_f32_16x16x32_bf16 v[40:43], v[190:193], v[198:201], v[40:43]
	v_mfma_f32_16x16x32_bf16 v[28:31], v[176:179], v[206:209], v[28:31]
	v_mfma_f32_16x16x32_bf16 v[24:27], v[190:193], v[206:209], v[24:27]
	v_mfma_f32_16x16x32_bf16 v[12:15], v[176:179], v[214:217], v[12:15]
	v_mfma_f32_16x16x32_bf16 v[8:11], v[190:193], v[214:217], v[8:11]
	v_mfma_f32_16x16x32_bf16 v[4:7], v[176:179], v[222:225], v[4:7]
	v_mfma_f32_16x16x32_bf16 v[0:3], v[190:193], v[222:225], v[0:3]
	s_setprio 0
	s_barrier
	s_add_i32 s54, 0, 0x18000
	v_add_u32_e32 v147, s54, v152
	s_add_i32 s55, 0, 0x1c000
	ds_read_b128 v[156:159], v147
	ds_read_b128 v[160:163], v147 offset:1024
	ds_read_b128 v[164:167], v147 offset:2048
	ds_read_b128 v[168:171], v147 offset:3072
	v_add_u32_e32 v147, s55, v152
	ds_read_b128 v[172:175], v147
	ds_read_b128 v[176:179], v147 offset:1024
	ds_read_b128 v[182:185], v147 offset:2048
	ds_read_b128 v[190:193], v147 offset:3072
	s_add_u32 s26, s26, 0x40000
	s_addc_u32 s27, s27, 0
	s_mov_b32 m0, s35
	ds_read_b128 v[194:197], v155 offset:32768
	ds_read_b128 v[198:201], v155 offset:33792
	ds_read_b128 v[202:205], v155 offset:34816
	ds_read_b128 v[206:209], v155 offset:35840
	ds_read_b128 v[210:213], v155 offset:36864
	ds_read_b128 v[214:217], v155 offset:37888
	ds_read_b128 v[218:221], v155 offset:38912
	ds_read_b128 v[222:225], v155 offset:39936
	global_load_lds_dwordx4 v128, s[26:27]
	s_mov_b32 m0, s36
	s_nop 0
	global_load_lds_dwordx4 v132, s[26:27]
	s_waitcnt vmcnt(8)
	s_waitcnt lgkmcnt(0)
	s_barrier
	s_setprio 1
	s_waitcnt lgkmcnt(0)
	v_mfma_f32_16x16x32_bf16 v[124:127], v[156:159], v[194:197], v[124:127]
	v_mfma_f32_16x16x32_bf16 v[120:123], v[164:167], v[194:197], v[120:123]
	v_mfma_f32_16x16x32_bf16 v[116:119], v[156:159], v[202:205], v[116:119]
	v_mfma_f32_16x16x32_bf16 v[112:115], v[164:167], v[202:205], v[112:115]
	v_mfma_f32_16x16x32_bf16 v[100:103], v[156:159], v[210:213], v[100:103]
	v_mfma_f32_16x16x32_bf16 v[96:99], v[164:167], v[210:213], v[96:99]
	v_mfma_f32_16x16x32_bf16 v[84:87], v[156:159], v[218:221], v[84:87]
	v_mfma_f32_16x16x32_bf16 v[80:83], v[164:167], v[218:221], v[80:83]
	v_mfma_f32_16x16x32_bf16 v[124:127], v[160:163], v[198:201], v[124:127]
	v_mfma_f32_16x16x32_bf16 v[120:123], v[168:171], v[198:201], v[120:123]
	v_mfma_f32_16x16x32_bf16 v[116:119], v[160:163], v[206:209], v[116:119]
	v_mfma_f32_16x16x32_bf16 v[112:115], v[168:171], v[206:209], v[112:115]
	v_mfma_f32_16x16x32_bf16 v[100:103], v[160:163], v[214:217], v[100:103]
	v_mfma_f32_16x16x32_bf16 v[96:99], v[168:171], v[214:217], v[96:99]
	v_mfma_f32_16x16x32_bf16 v[84:87], v[160:163], v[222:225], v[84:87]
	v_mfma_f32_16x16x32_bf16 v[80:83], v[168:171], v[222:225], v[80:83]
	v_mfma_f32_16x16x32_bf16 v[108:111], v[172:175], v[194:197], v[108:111]
	v_mfma_f32_16x16x32_bf16 v[104:107], v[182:185], v[194:197], v[104:107]
	v_mfma_f32_16x16x32_bf16 v[92:95], v[172:175], v[202:205], v[92:95]
	v_mfma_f32_16x16x32_bf16 v[88:91], v[182:185], v[202:205], v[88:91]
	v_mfma_f32_16x16x32_bf16 v[76:79], v[172:175], v[210:213], v[76:79]
	v_mfma_f32_16x16x32_bf16 v[72:75], v[182:185], v[210:213], v[72:75]
	v_mfma_f32_16x16x32_bf16 v[68:71], v[172:175], v[218:221], v[68:71]
	v_mfma_f32_16x16x32_bf16 v[64:67], v[182:185], v[218:221], v[64:67]
	v_mfma_f32_16x16x32_bf16 v[108:111], v[176:179], v[198:201], v[108:111]
	v_mfma_f32_16x16x32_bf16 v[104:107], v[190:193], v[198:201], v[104:107]
	v_mfma_f32_16x16x32_bf16 v[92:95], v[176:179], v[206:209], v[92:95]
	v_mfma_f32_16x16x32_bf16 v[88:91], v[190:193], v[206:209], v[88:91]
	v_mfma_f32_16x16x32_bf16 v[76:79], v[176:179], v[214:217], v[76:79]
	v_mfma_f32_16x16x32_bf16 v[72:75], v[190:193], v[214:217], v[72:75]
	v_mfma_f32_16x16x32_bf16 v[68:71], v[176:179], v[222:225], v[68:71]
	v_mfma_f32_16x16x32_bf16 v[64:67], v[190:193], v[222:225], v[64:67]
	s_setprio 0
	s_barrier
; #define PG8_STAGE(bufoff, gbase, voff) do { _Pragma("unroll") for (int _i = 0; _i < 2; ++_i) \
;         __builtin_amdgcn_global_load_lds((const unsigned*)((const char*)(gbase) + (voff)[_i]), (PG8_LAS unsigned*)(lds + (bufoff) + ldsw + _i * 8192), 16, 0, 0); } while (0)
; #define PG8_LDA(dst, b, h) do { _Pragma("unroll") for (int m = 0; m < 4; ++m) _Pragma("unroll") for (int k = 0; k < 2; ++k) dst[m][k] = *(const PG8_LAS bf16x8*)(lds + PG8_SA(b, h) + aoff + m * 2048 + k * 1024); } while (0)
; #define PG8_MMA(ai, bj, At, Bt) do { __builtin_amdgcn_s_setprio(1); _Pragma("unroll") for (int m = 0; m < 4; ++m) _Pragma("unroll") for (int n = 0; n < 2; ++n) _Pragma("unroll") for (int k = 0; k < 2; ++k) \
;         acc[ai][bj][m][n] = __builtin_amdgcn_mfma_f32_16x16x32_bf16(Bt[n][k], At[m][k], acc[ai][bj][m][n], 0, 0, 0); __builtin_amdgcn_s_setprio(0); } while (0)
; #define PG8_WAIT_V(n) asm volatile("s_waitcnt vmcnt(" #n ")" ::: "memory")
; #define PG8_WAIT_L(n) asm volatile("s_waitcnt lgkmcnt(" #n ")" ::: "memory")
; #define PG8_BAR __builtin_amdgcn_s_barrier()
; #define PG8_SCHED __builtin_amdgcn_sched_barrier(0)
; template <class Epi, class Sched, bool ALIGN_EPI = false, bool SP2 = false>
; __device__ __forceinline__ void gemm_phase(PG8_LAS unsigned char* lds, const Gemm g, const Sched& S, const Epi& E) {
;     ...
;             PG8_LDA(At, 1, 1); PG8_STAGE(PG8_SB(1, 0), b3, voffB); PG8_STAGE(PG8_SB(1, 1), b3 + hstep, voffB); PG8_STAGE(PG8_SA(1, 0), a3, voffA);
;             PG8_WAIT_V(8); PG8_WAIT_L(0); PG8_BAR; PG8_MMA(1, 0, At, B0); PG8_MMA(1, 1, At, B1); PG8_BAR; PG8_SCHED;
	s_add_i32 s26, s54, s31
	v_lshl_add_u64 v[186:187], v[186:187], 0, s[8:9]
	s_mov_b32 m0, s26
	ds_read_b128 v[194:197], v155 offset:49152
	ds_read_b128 v[198:201], v155 offset:50176
	ds_read_b128 v[202:205], v155 offset:51200
	ds_read_b128 v[206:209], v155 offset:52224
	ds_read_b128 v[210:213], v155 offset:53248
	ds_read_b128 v[214:217], v155 offset:54272
	ds_read_b128 v[218:221], v155 offset:55296
	ds_read_b128 v[222:225], v155 offset:56320
	global_load_lds_dwordx4 v[186:187], off
	s_add_i32 m0, s26, 0x2000
	s_add_u32 s24, s24, 0x40080
	v_lshl_add_u64 v[186:187], v[226:227], 0, s[8:9]
	s_addc_u32 s25, s25, 0
	s_add_i32 s26, s55, s31
	global_load_lds_dwordx4 v[186:187], off
	s_mov_b32 m0, s26
	s_nop 0
	global_load_lds_dwordx4 v130, s[24:25]
	s_add_i32 m0, s26, 0x2000
	s_nop 0
	global_load_lds_dwordx4 v134, s[24:25]
	v_lshl_add_u64 v[186:187], v[228:229], 0, s[8:9]
	s_mov_b32 m0, s39
	s_nop 0
	global_load_lds_dwordx4 v[186:187], off
	v_lshl_add_u64 v[186:187], v[230:231], 0, s[8:9]
	s_mov_b32 m0, s40
	s_nop 0
	global_load_lds_dwordx4 v[186:187], off
	s_waitcnt vmcnt(8)
	s_waitcnt lgkmcnt(0)
	s_barrier
	s_setprio 1
	s_waitcnt lgkmcnt(0)
	v_mfma_f32_16x16x32_bf16 v[60:63], v[156:159], v[194:197], v[60:63]
	v_mfma_f32_16x16x32_bf16 v[56:59], v[164:167], v[194:197], v[56:59]
	v_mfma_f32_16x16x32_bf16 v[52:55], v[156:159], v[202:205], v[52:55]
	v_mfma_f32_16x16x32_bf16 v[48:51], v[164:167], v[202:205], v[48:51]
	v_mfma_f32_16x16x32_bf16 v[36:39], v[156:159], v[210:213], v[36:39]
	v_mfma_f32_16x16x32_bf16 v[32:35], v[164:167], v[210:213], v[32:35]
	v_mfma_f32_16x16x32_bf16 v[20:23], v[156:159], v[218:221], v[20:23]
	v_mfma_f32_16x16x32_bf16 v[16:19], v[164:167], v[218:221], v[16:19]
	v_mfma_f32_16x16x32_bf16 v[60:63], v[160:163], v[198:201], v[60:63]
	v_mfma_f32_16x16x32_bf16 v[56:59], v[168:171], v[198:201], v[56:59]
	v_mfma_f32_16x16x32_bf16 v[52:55], v[160:163], v[206:209], v[52:55]
	v_mfma_f32_16x16x32_bf16 v[48:51], v[168:171], v[206:209], v[48:51]
	v_mfma_f32_16x16x32_bf16 v[36:39], v[160:163], v[214:217], v[36:39]
	v_mfma_f32_16x16x32_bf16 v[32:35], v[168:171], v[214:217], v[32:35]
	v_mfma_f32_16x16x32_bf16 v[20:23], v[160:163], v[222:225], v[20:23]
	v_mfma_f32_16x16x32_bf16 v[16:19], v[168:171], v[222:225], v[16:19]
	v_mfma_f32_16x16x32_bf16 v[44:47], v[172:175], v[194:197], v[44:47]
	v_mfma_f32_16x16x32_bf16 v[40:43], v[182:185], v[194:197], v[40:43]
	v_mfma_f32_16x16x32_bf16 v[28:31], v[172:175], v[202:205], v[28:31]
	v_mfma_f32_16x16x32_bf16 v[24:27], v[182:185], v[202:205], v[24:27]
	v_mfma_f32_16x16x32_bf16 v[12:15], v[172:175], v[210:213], v[12:15]
	v_mfma_f32_16x16x32_bf16 v[8:11], v[182:185], v[210:213], v[8:11]
	v_mfma_f32_16x16x32_bf16 v[4:7], v[172:175], v[218:221], v[4:7]
	v_mfma_f32_16x16x32_bf16 v[0:3], v[182:185], v[218:221], v[0:3]
	v_mfma_f32_16x16x32_bf16 v[44:47], v[176:179], v[198:201], v[44:47]
	v_mfma_f32_16x16x32_bf16 v[40:43], v[190:193], v[198:201], v[40:43]
	v_mfma_f32_16x16x32_bf16 v[28:31], v[176:179], v[206:209], v[28:31]
	v_mfma_f32_16x16x32_bf16 v[24:27], v[190:193], v[206:209], v[24:27]
	v_mfma_f32_16x16x32_bf16 v[12:15], v[176:179], v[214:217], v[12:15]
	v_mfma_f32_16x16x32_bf16 v[8:11], v[190:193], v[214:217], v[8:11]
	v_mfma_f32_16x16x32_bf16 v[4:7], v[176:179], v[222:225], v[4:7]
	v_mfma_f32_16x16x32_bf16 v[0:3], v[190:193], v[222:225], v[0:3]
	s_setprio 0
	s_barrier
	s_add_i32 s49, s49, 2
	s_add_u32 s22, s22, 0x100
	s_addc_u32 s23, s23, 0
	s_add_u32 s47, s47, 0x100
	s_addc_u32 s48, s48, 0
	s_cmp_gt_u32 s49, 13
	s_cbranch_scc0 .LBB0_150
	s_and_b64 vcc, exec, s[10:11]
	s_cbranch_vccz .LBB0_153
	s_barrier

; #define PG8_STAGE(bufoff, gbase, voff) do { _Pragma("unroll") for (int _i = 0; _i < 2; ++_i) \
;         __builtin_amdgcn_global_load_lds((const unsigned*)((const char*)(gbase) + (voff)[_i]), (PG8_LAS unsigned*)(lds + (bufoff) + ldsw + _i * 8192), 16, 0, 0); } while (0)
; #define PG8_LDA(dst, b, h) do { _Pragma("unroll") for (int m = 0; m < 4; ++m) _Pragma("unroll") for (int k = 0; k < 2; ++k) dst[m][k] = *(const PG8_LAS bf16x8*)(lds + PG8_SA(b, h) + aoff + m * 2048 + k * 1024); } while (0)
; #define PG8_LDB(dst, b, h) do { _Pragma("unroll") for (int n = 0; n < 2; ++n) _Pragma("unroll") for (int k = 0; k < 2; ++k) dst[n][k] = *(const PG8_LAS bf16x8*)(lds + PG8_SB(b, h) + boff + n * 2048 + k * 1024); } while (0)
; #define PG8_MMA(ai, bj, At, Bt) do { __builtin_amdgcn_s_setprio(1); _Pragma("unroll") for (int m = 0; m < 4; ++m) _Pragma("unroll") for (int n = 0; n < 2; ++n) _Pragma("unroll") for (int k = 0; k < 2; ++k) \
;         acc[ai][bj][m][n] = __builtin_amdgcn_mfma_f32_16x16x32_bf16(Bt[n][k], At[m][k], acc[ai][bj][m][n], 0, 0, 0); __builtin_amdgcn_s_setprio(0); } while (0)
; #define PG8_WAIT_V(n) asm volatile("s_waitcnt vmcnt(" #n ")" ::: "memory")
; #define PG8_WAIT_L(n) asm volatile("s_waitcnt lgkmcnt(" #n ")" ::: "memory")
; #define PG8_BAR __builtin_amdgcn_s_barrier()
; #define PG8_SCHED __builtin_amdgcn_sched_barrier(0)
; template <class Epi, class Sched, bool ALIGN_EPI = false, bool SP2 = false>
; __device__ __forceinline__ void gemm_phase(PG8_LAS unsigned char* lds, const Gemm g, const Sched& S, const Epi& E) {
;     ...
;             PG8_LDB(B0, 0, 0); PG8_LDB(B1, 0, 1); PG8_SCHED; PG8_LDA(At, 0, 0); PG8_STAGE(PG8_SA(1, 1), a1 + hstep, voffA);
;             PG8_WAIT_V(8); PG8_WAIT_L(0); PG8_BAR; PG8_MMA(0, 0, At, B0); PG8_MMA(0, 1, At, B1); PG8_BAR; PG8_SCHED;
;             PG8_LDA(At, 0, 1); PG8_STAGE(PG8_SB(0, 0), b2, voffB); PG8_STAGE(PG8_SB(0, 1), b2 + hstep, voffB); PG8_STAGE(PG8_SA(0, 0), a2, voffA);
;             PG8_WAIT_V(8); PG8_WAIT_L(0); PG8_BAR; PG8_MMA(1, 0, At, B0); PG8_MMA(1, 1, At, B1); PG8_BAR; PG8_SCHED;
.LBB0_358:
	ds_read_b128 v[128:131], v178
	ds_read_b128 v[132:135], v178 offset:1024
	ds_read_b128 v[136:139], v178 offset:2048
	ds_read_b128 v[140:143], v178 offset:3072
	ds_read_b128 v[166:169], v179
	ds_read_b128 v[170:173], v179 offset:1024
	ds_read_b128 v[190:193], v179 offset:2048
	ds_read_b128 v[194:197], v179 offset:3072
	s_add_u32 s42, s40, 0xfffc0080
	s_addc_u32 s43, s41, -1
	s_cmp_eq_u32 s25, 12
	s_cselect_b32 s45, s1, s43
	s_cselect_b32 s44, s35, s42
	s_cselect_b32 s43, s31, s24
	s_cselect_b32 s42, vcc_lo, vcc_hi
	v_lshl_add_u64 v[174:175], s[40:41], 0, v[158:159]
	s_add_i32 m0, s47, 0xc000
	ds_read_b128 v[198:201], v181
	ds_read_b128 v[202:205], v181 offset:1024
	ds_read_b128 v[206:209], v181 offset:2048
	ds_read_b128 v[210:213], v181 offset:3072
	ds_read_b128 v[214:217], v181 offset:4096
	ds_read_b128 v[218:221], v181 offset:5120
	ds_read_b128 v[222:225], v181 offset:6144
	ds_read_b128 v[226:229], v181 offset:7168
	global_load_lds_dwordx4 v[174:175], off
	v_lshl_add_u64 v[174:175], s[40:41], 0, v[160:161]
	s_add_i32 m0, s47, 0xe000
	s_nop 0
	global_load_lds_dwordx4 v[174:175], off
	s_waitcnt vmcnt(8)
	s_waitcnt lgkmcnt(0)
	s_barrier
	s_setprio 1
	s_waitcnt lgkmcnt(0)
	v_mfma_f32_16x16x32_bf16 v[124:127], v[128:131], v[198:201], v[124:127]
	v_mfma_f32_16x16x32_bf16 v[120:123], v[136:139], v[198:201], v[120:123]
	v_mfma_f32_16x16x32_bf16 v[108:111], v[128:131], v[206:209], v[108:111]
	v_mfma_f32_16x16x32_bf16 v[104:107], v[136:139], v[206:209], v[104:107]
	v_mfma_f32_16x16x32_bf16 v[92:95], v[128:131], v[214:217], v[92:95]
	v_mfma_f32_16x16x32_bf16 v[88:91], v[136:139], v[214:217], v[88:91]
	v_mfma_f32_16x16x32_bf16 v[76:79], v[128:131], v[222:225], v[76:79]
	v_mfma_f32_16x16x32_bf16 v[72:75], v[136:139], v[222:225], v[72:75]
	v_mfma_f32_16x16x32_bf16 v[124:127], v[132:135], v[202:205], v[124:127]
	v_mfma_f32_16x16x32_bf16 v[120:123], v[140:143], v[202:205], v[120:123]
	v_mfma_f32_16x16x32_bf16 v[108:111], v[132:135], v[210:213], v[108:111]
	v_mfma_f32_16x16x32_bf16 v[104:107], v[140:143], v[210:213], v[104:107]
	v_mfma_f32_16x16x32_bf16 v[92:95], v[132:135], v[218:221], v[92:95]
	v_mfma_f32_16x16x32_bf16 v[88:91], v[140:143], v[218:221], v[88:91]
	v_mfma_f32_16x16x32_bf16 v[76:79], v[132:135], v[226:229], v[76:79]
	v_mfma_f32_16x16x32_bf16 v[72:75], v[140:143], v[226:229], v[72:75]
	v_mfma_f32_16x16x32_bf16 v[116:119], v[166:169], v[198:201], v[116:119]
	v_mfma_f32_16x16x32_bf16 v[112:115], v[190:193], v[198:201], v[112:115]
	v_mfma_f32_16x16x32_bf16 v[100:103], v[166:169], v[206:209], v[100:103]
	v_mfma_f32_16x16x32_bf16 v[96:99], v[190:193], v[206:209], v[96:99]
	v_mfma_f32_16x16x32_bf16 v[84:87], v[166:169], v[214:217], v[84:87]
	v_mfma_f32_16x16x32_bf16 v[80:83], v[190:193], v[214:217], v[80:83]
	v_mfma_f32_16x16x32_bf16 v[68:71], v[166:169], v[222:225], v[68:71]
	v_mfma_f32_16x16x32_bf16 v[64:67], v[190:193], v[222:225], v[64:67]
	v_mfma_f32_16x16x32_bf16 v[116:119], v[170:173], v[202:205], v[116:119]
	v_mfma_f32_16x16x32_bf16 v[112:115], v[194:197], v[202:205], v[112:115]
	v_mfma_f32_16x16x32_bf16 v[100:103], v[170:173], v[210:213], v[100:103]
	v_mfma_f32_16x16x32_bf16 v[96:99], v[194:197], v[210:213], v[96:99]
	v_mfma_f32_16x16x32_bf16 v[84:87], v[170:173], v[218:221], v[84:87]
	v_mfma_f32_16x16x32_bf16 v[80:83], v[194:197], v[218:221], v[80:83]
	v_mfma_f32_16x16x32_bf16 v[68:71], v[170:173], v[226:229], v[68:71]
	v_mfma_f32_16x16x32_bf16 v[64:67], v[194:197], v[226:229], v[64:67]
	s_setprio 0
	s_barrier
	s_add_i32 s54, s93, s46
	v_lshl_add_u64 v[174:175], s[42:43], 0, v[146:147]
	s_mov_b32 m0, s54
	ds_read_b128 v[198:201], v181 offset:16384
	ds_read_b128 v[202:205], v181 offset:17408
	ds_read_b128 v[206:209], v181 offset:18432
	ds_read_b128 v[210:213], v181 offset:19456
	ds_read_b128 v[214:217], v181 offset:20480
	ds_read_b128 v[218:221], v181 offset:21504
	ds_read_b128 v[222:225], v181 offset:22528
	ds_read_b128 v[226:229], v181 offset:23552
	global_load_lds_dwordx4 v[174:175], off
	s_add_i32 m0, s54, 0x2000
	s_add_u32 s54, s42, 0x40000
	v_lshl_add_u64 v[186:187], s[42:43], 0, v[150:151]
	s_addc_u32 s55, s43, 0
	s_add_i32 s23, s94, s46
	global_load_lds_dwordx4 v[186:187], off
	v_lshl_add_u64 v[230:231], s[54:55], 0, v[146:147]
	s_mov_b32 m0, s23
	v_lshl_add_u64 v[232:233], s[44:45], 0, v[148:149]
	global_load_lds_dwordx4 v[230:231], off
	v_lshl_add_u64 v[230:231], s[54:55], 0, v[150:151]
	s_add_i32 m0, s23, 0x2000
	s_nop 0
	global_load_lds_dwordx4 v[230:231], off
	v_lshl_add_u64 v[230:231], s[44:45], 0, v[144:145]
	s_mov_b32 m0, s47
	s_nop 0
	global_load_lds_dwordx4 v[230:231], off
	s_mov_b32 m0, s48
	s_nop 0
	global_load_lds_dwordx4 v[232:233], off
	s_waitcnt vmcnt(8)
	s_waitcnt lgkmcnt(0)
	s_barrier
; #define PG8_STAGE(bufoff, gbase, voff) do { _Pragma("unroll") for (int _i = 0; _i < 2; ++_i) \
;         __builtin_amdgcn_global_load_lds((const unsigned*)((const char*)(gbase) + (voff)[_i]), (PG8_LAS unsigned*)(lds + (bufoff) + ldsw + _i * 8192), 16, 0, 0); } while (0)
; #define PG8_LDA(dst, b, h) do { _Pragma("unroll") for (int m = 0; m < 4; ++m) _Pragma("unroll") for (int k = 0; k < 2; ++k) dst[m][k] = *(const PG8_LAS bf16x8*)(lds + PG8_SA(b, h) + aoff + m * 2048 + k * 1024); } while (0)
; #define PG8_LDB(dst, b, h) do { _Pragma("unroll") for (int n = 0; n < 2; ++n) _Pragma("unroll") for (int k = 0; k < 2; ++k) dst[n][k] = *(const PG8_LAS bf16x8*)(lds + PG8_SB(b, h) + boff + n * 2048 + k * 1024); } while (0)
; #define PG8_MMA(ai, bj, At, Bt) do { __builtin_amdgcn_s_setprio(1); _Pragma("unroll") for (int m = 0; m < 4; ++m) _Pragma("unroll") for (int n = 0; n < 2; ++n) _Pragma("unroll") for (int k = 0; k < 2; ++k) \
;         acc[ai][bj][m][n] = __builtin_amdgcn_mfma_f32_16x16x32_bf16(Bt[n][k], At[m][k], acc[ai][bj][m][n], 0, 0, 0); __builtin_amdgcn_s_setprio(0); } while (0)
; #define PG8_WAIT_V(n) asm volatile("s_waitcnt vmcnt(" #n ")" ::: "memory")
; #define PG8_WAIT_L(n) asm volatile("s_waitcnt lgkmcnt(" #n ")" ::: "memory")
; #define PG8_BAR __builtin_amdgcn_s_barrier()
; #define PG8_SCHED __builtin_amdgcn_sched_barrier(0)
; template <class Epi, class Sched, bool ALIGN_EPI = false, bool SP2 = false>
; __device__ __forceinline__ void gemm_phase(PG8_LAS unsigned char* lds, const Gemm g, const Sched& S, const Epi& E) {
;     ...
;             PG8_WAIT_V(8); PG8_WAIT_L(0); PG8_BAR; PG8_MMA(1, 0, At, B0); PG8_MMA(1, 1, At, B1); PG8_BAR; PG8_SCHED;
;             PG8_LDB(B0, 1, 0); PG8_LDB(B1, 1, 1); PG8_SCHED; PG8_LDA(At, 1, 0); PG8_STAGE(PG8_SA(0, 1), a2 + hstep, voffA);
;             PG8_WAIT_V(8); PG8_WAIT_L(0); PG8_BAR; PG8_MMA(0, 0, At, B0); PG8_MMA(0, 1, At, B1); PG8_BAR; PG8_SCHED;
	s_setprio 1
	s_waitcnt lgkmcnt(0)
	v_mfma_f32_16x16x32_bf16 v[60:63], v[128:131], v[198:201], v[60:63]
	v_mfma_f32_16x16x32_bf16 v[56:59], v[136:139], v[198:201], v[56:59]
	v_mfma_f32_16x16x32_bf16 v[44:47], v[128:131], v[206:209], v[44:47]
	v_mfma_f32_16x16x32_bf16 v[40:43], v[136:139], v[206:209], v[40:43]
	v_mfma_f32_16x16x32_bf16 v[28:31], v[128:131], v[214:217], v[28:31]
	v_mfma_f32_16x16x32_bf16 v[24:27], v[136:139], v[214:217], v[24:27]
	v_mfma_f32_16x16x32_bf16 v[12:15], v[128:131], v[222:225], v[12:15]
	v_mfma_f32_16x16x32_bf16 v[8:11], v[136:139], v[222:225], v[8:11]
	v_mfma_f32_16x16x32_bf16 v[60:63], v[132:135], v[202:205], v[60:63]
	v_mfma_f32_16x16x32_bf16 v[56:59], v[140:143], v[202:205], v[56:59]
	v_mfma_f32_16x16x32_bf16 v[44:47], v[132:135], v[210:213], v[44:47]
	v_mfma_f32_16x16x32_bf16 v[40:43], v[140:143], v[210:213], v[40:43]
	v_mfma_f32_16x16x32_bf16 v[28:31], v[132:135], v[218:221], v[28:31]
	v_mfma_f32_16x16x32_bf16 v[24:27], v[140:143], v[218:221], v[24:27]
	v_mfma_f32_16x16x32_bf16 v[12:15], v[132:135], v[226:229], v[12:15]
	v_mfma_f32_16x16x32_bf16 v[8:11], v[140:143], v[226:229], v[8:11]
	v_mfma_f32_16x16x32_bf16 v[52:55], v[166:169], v[198:201], v[52:55]
	v_mfma_f32_16x16x32_bf16 v[48:51], v[190:193], v[198:201], v[48:51]
	v_mfma_f32_16x16x32_bf16 v[36:39], v[166:169], v[206:209], v[36:39]
	v_mfma_f32_16x16x32_bf16 v[32:35], v[190:193], v[206:209], v[32:35]
	v_mfma_f32_16x16x32_bf16 v[20:23], v[166:169], v[214:217], v[20:23]
	v_mfma_f32_16x16x32_bf16 v[16:19], v[190:193], v[214:217], v[16:19]
	v_mfma_f32_16x16x32_bf16 v[4:7], v[166:169], v[222:225], v[4:7]
	v_mfma_f32_16x16x32_bf16 v[0:3], v[190:193], v[222:225], v[0:3]
	v_mfma_f32_16x16x32_bf16 v[52:55], v[170:173], v[202:205], v[52:55]
	v_mfma_f32_16x16x32_bf16 v[48:51], v[194:197], v[202:205], v[48:51]
	v_mfma_f32_16x16x32_bf16 v[36:39], v[170:173], v[210:213], v[36:39]
	v_mfma_f32_16x16x32_bf16 v[32:35], v[194:197], v[210:213], v[32:35]
	v_mfma_f32_16x16x32_bf16 v[20:23], v[170:173], v[218:221], v[20:23]
	v_mfma_f32_16x16x32_bf16 v[16:19], v[194:197], v[218:221], v[16:19]
	v_mfma_f32_16x16x32_bf16 v[4:7], v[170:173], v[226:229], v[4:7]
	v_mfma_f32_16x16x32_bf16 v[0:3], v[194:197], v[226:229], v[0:3]
	s_setprio 0
	s_barrier
	s_add_i32 s23, 0, 0x18000
	s_add_i32 s54, 0, 0x1c000
	v_add_u32_e32 v140, s23, v176
	v_add_u32_e32 v152, s54, v176
	ds_read_b128 v[128:131], v140
	ds_read_b128 v[132:135], v140 offset:1024
	ds_read_b128 v[136:139], v140 offset:2048
	ds_read_b128 v[140:143], v140 offset:3072
	ds_read_b128 v[166:169], v152
	ds_read_b128 v[170:173], v152 offset:1024
	ds_read_b128 v[190:193], v152 offset:2048
	ds_read_b128 v[194:197], v152 offset:3072
	s_add_u32 s44, s44, 0x40000
	s_addc_u32 s45, s45, 0
	s_mov_b32 m0, s49
	v_lshl_add_u64 v[234:235], s[44:45], 0, v[144:145]
	ds_read_b128 v[198:201], v181 offset:32768
	ds_read_b128 v[202:205], v181 offset:33792
	ds_read_b128 v[206:209], v181 offset:34816
	ds_read_b128 v[210:213], v181 offset:35840
	ds_read_b128 v[214:217], v181 offset:36864
	ds_read_b128 v[218:221], v181 offset:37888
	ds_read_b128 v[222:225], v181 offset:38912
	ds_read_b128 v[226:229], v181 offset:39936
	global_load_lds_dwordx4 v[234:235], off
	v_lshl_add_u64 v[234:235], s[44:45], 0, v[148:149]
	s_mov_b32 m0, s51
	s_nop 0
	global_load_lds_dwordx4 v[234:235], off
	s_waitcnt vmcnt(8)
	s_waitcnt lgkmcnt(0)
	s_barrier
	s_setprio 1
	s_waitcnt lgkmcnt(0)
	v_mfma_f32_16x16x32_bf16 v[124:127], v[128:131], v[198:201], v[124:127]
	v_mfma_f32_16x16x32_bf16 v[120:123], v[136:139], v[198:201], v[120:123]
	v_mfma_f32_16x16x32_bf16 v[108:111], v[128:131], v[206:209], v[108:111]
	v_mfma_f32_16x16x32_bf16 v[104:107], v[136:139], v[206:209], v[104:107]
	v_mfma_f32_16x16x32_bf16 v[92:95], v[128:131], v[214:217], v[92:95]
	v_mfma_f32_16x16x32_bf16 v[88:91], v[136:139], v[214:217], v[88:91]
	v_mfma_f32_16x16x32_bf16 v[76:79], v[128:131], v[222:225], v[76:79]
	v_mfma_f32_16x16x32_bf16 v[72:75], v[136:139], v[222:225], v[72:75]
	v_mfma_f32_16x16x32_bf16 v[124:127], v[132:135], v[202:205], v[124:127]
	v_mfma_f32_16x16x32_bf16 v[120:123], v[140:143], v[202:205], v[120:123]
	v_mfma_f32_16x16x32_bf16 v[108:111], v[132:135], v[210:213], v[108:111]
	v_mfma_f32_16x16x32_bf16 v[104:107], v[140:143], v[210:213], v[104:107]
	v_mfma_f32_16x16x32_bf16 v[92:95], v[132:135], v[218:221], v[92:95]
	v_mfma_f32_16x16x32_bf16 v[88:91], v[140:143], v[218:221], v[88:91]
	v_mfma_f32_16x16x32_bf16 v[76:79], v[132:135], v[226:229], v[76:79]
	v_mfma_f32_16x16x32_bf16 v[72:75], v[140:143], v[226:229], v[72:75]
	v_mfma_f32_16x16x32_bf16 v[116:119], v[166:169], v[198:201], v[116:119]
	v_mfma_f32_16x16x32_bf16 v[112:115], v[190:193], v[198:201], v[112:115]
	v_mfma_f32_16x16x32_bf16 v[100:103], v[166:169], v[206:209], v[100:103]
	v_mfma_f32_16x16x32_bf16 v[96:99], v[190:193], v[206:209], v[96:99]
	v_mfma_f32_16x16x32_bf16 v[84:87], v[166:169], v[214:217], v[84:87]
	v_mfma_f32_16x16x32_bf16 v[80:83], v[190:193], v[214:217], v[80:83]
	v_mfma_f32_16x16x32_bf16 v[68:71], v[166:169], v[222:225], v[68:71]
	v_mfma_f32_16x16x32_bf16 v[64:67], v[190:193], v[222:225], v[64:67]
	v_mfma_f32_16x16x32_bf16 v[116:119], v[170:173], v[202:205], v[116:119]
	v_mfma_f32_16x16x32_bf16 v[112:115], v[194:197], v[202:205], v[112:115]
	v_mfma_f32_16x16x32_bf16 v[100:103], v[170:173], v[210:213], v[100:103]
	v_mfma_f32_16x16x32_bf16 v[96:99], v[194:197], v[210:213], v[96:99]
	v_mfma_f32_16x16x32_bf16 v[84:87], v[170:173], v[218:221], v[84:87]
	v_mfma_f32_16x16x32_bf16 v[80:83], v[194:197], v[218:221], v[80:83]
	v_mfma_f32_16x16x32_bf16 v[68:71], v[170:173], v[226:229], v[68:71]
	v_mfma_f32_16x16x32_bf16 v[64:67], v[194:197], v[226:229], v[64:67]
	s_setprio 0
	s_barrier
; #define PG8_STAGE(bufoff, gbase, voff) do { _Pragma("unroll") for (int _i = 0; _i < 2; ++_i) \
;         __builtin_amdgcn_global_load_lds((const unsigned*)((const char*)(gbase) + (voff)[_i]), (PG8_LAS unsigned*)(lds + (bufoff) + ldsw + _i * 8192), 16, 0, 0); } while (0)
; #define PG8_LDA(dst, b, h) do { _Pragma("unroll") for (int m = 0; m < 4; ++m) _Pragma("unroll") for (int k = 0; k < 2; ++k) dst[m][k] = *(const PG8_LAS bf16x8*)(lds + PG8_SA(b, h) + aoff + m * 2048 + k * 1024); } while (0)
; #define PG8_MMA(ai, bj, At, Bt) do { __builtin_amdgcn_s_setprio(1); _Pragma("unroll") for (int m = 0; m < 4; ++m) _Pragma("unroll") for (int n = 0; n < 2; ++n) _Pragma("unroll") for (int k = 0; k < 2; ++k) \
;         acc[ai][bj][m][n] = __builtin_amdgcn_mfma_f32_16x16x32_bf16(Bt[n][k], At[m][k], acc[ai][bj][m][n], 0, 0, 0); __builtin_amdgcn_s_setprio(0); } while (0)
; #define PG8_WAIT_V(n) asm volatile("s_waitcnt vmcnt(" #n ")" ::: "memory")
; #define PG8_WAIT_L(n) asm volatile("s_waitcnt lgkmcnt(" #n ")" ::: "memory")
; #define PG8_BAR __builtin_amdgcn_s_barrier()
; #define PG8_SCHED __builtin_amdgcn_sched_barrier(0)
; template <class Epi, class Sched, bool ALIGN_EPI = false, bool SP2 = false>
; __device__ __forceinline__ void gemm_phase(PG8_LAS unsigned char* lds, const Gemm g, const Sched& S, const Epi& E) {
;     ...
;         for (int t = 0; t < nt; t += 2) {
;             const bool last = (t == nt - 2);
;     ...
;             PG8_LDA(At, 1, 1); PG8_STAGE(PG8_SB(1, 0), b3, voffB); PG8_STAGE(PG8_SB(1, 1), b3 + hstep, voffB); PG8_STAGE(PG8_SA(1, 0), a3, voffA);
;             PG8_WAIT_V(8); PG8_WAIT_L(0); PG8_BAR; PG8_MMA(1, 0, At, B0); PG8_MMA(1, 1, At, B1); PG8_BAR; PG8_SCHED;
	s_add_i32 s23, s23, s46
	v_lshl_add_u64 v[174:175], v[174:175], 0, s[10:11]
	s_mov_b32 m0, s23
	ds_read_b128 v[198:201], v181 offset:49152
	ds_read_b128 v[202:205], v181 offset:50176
	ds_read_b128 v[206:209], v181 offset:51200
	ds_read_b128 v[210:213], v181 offset:52224
	ds_read_b128 v[214:217], v181 offset:53248
	ds_read_b128 v[218:221], v181 offset:54272
	ds_read_b128 v[222:225], v181 offset:55296
	ds_read_b128 v[226:229], v181 offset:56320
	global_load_lds_dwordx4 v[174:175], off
	s_add_i32 m0, s23, 0x2000
	s_add_u32 s42, s42, 0x40080
	v_lshl_add_u64 v[174:175], v[186:187], 0, s[10:11]
	s_addc_u32 s43, s43, 0
	s_add_i32 s23, s54, s46
	global_load_lds_dwordx4 v[174:175], off
	v_lshl_add_u64 v[174:175], s[42:43], 0, v[146:147]
	s_mov_b32 m0, s23
	s_nop 0
	global_load_lds_dwordx4 v[174:175], off
	v_lshl_add_u64 v[174:175], s[42:43], 0, v[150:151]
	s_add_i32 m0, s23, 0x2000
	s_nop 0
	global_load_lds_dwordx4 v[174:175], off
	v_lshl_add_u64 v[174:175], v[230:231], 0, s[10:11]
	s_mov_b32 m0, s80
	s_nop 0
	global_load_lds_dwordx4 v[174:175], off
	v_lshl_add_u64 v[174:175], v[232:233], 0, s[10:11]
	s_mov_b32 m0, s81
	s_nop 0
	global_load_lds_dwordx4 v[174:175], off
	s_waitcnt vmcnt(8)
	s_waitcnt lgkmcnt(0)
	s_barrier
	s_setprio 1
	s_waitcnt lgkmcnt(0)
	v_mfma_f32_16x16x32_bf16 v[60:63], v[128:131], v[198:201], v[60:63]
	v_mfma_f32_16x16x32_bf16 v[56:59], v[136:139], v[198:201], v[56:59]
	v_mfma_f32_16x16x32_bf16 v[44:47], v[128:131], v[206:209], v[44:47]
	v_mfma_f32_16x16x32_bf16 v[40:43], v[136:139], v[206:209], v[40:43]
	v_mfma_f32_16x16x32_bf16 v[28:31], v[128:131], v[214:217], v[28:31]
	v_mfma_f32_16x16x32_bf16 v[24:27], v[136:139], v[214:217], v[24:27]
	v_mfma_f32_16x16x32_bf16 v[12:15], v[128:131], v[222:225], v[12:15]
	v_mfma_f32_16x16x32_bf16 v[8:11], v[136:139], v[222:225], v[8:11]
	v_mfma_f32_16x16x32_bf16 v[60:63], v[132:135], v[202:205], v[60:63]
	v_mfma_f32_16x16x32_bf16 v[56:59], v[140:143], v[202:205], v[56:59]
	v_mfma_f32_16x16x32_bf16 v[44:47], v[132:135], v[210:213], v[44:47]
	v_mfma_f32_16x16x32_bf16 v[40:43], v[140:143], v[210:213], v[40:43]
	v_mfma_f32_16x16x32_bf16 v[28:31], v[132:135], v[218:221], v[28:31]
	v_mfma_f32_16x16x32_bf16 v[24:27], v[140:143], v[218:221], v[24:27]
	v_mfma_f32_16x16x32_bf16 v[12:15], v[132:135], v[226:229], v[12:15]
	v_mfma_f32_16x16x32_bf16 v[8:11], v[140:143], v[226:229], v[8:11]
	v_mfma_f32_16x16x32_bf16 v[52:55], v[166:169], v[198:201], v[52:55]
	v_mfma_f32_16x16x32_bf16 v[48:51], v[190:193], v[198:201], v[48:51]
	v_mfma_f32_16x16x32_bf16 v[36:39], v[166:169], v[206:209], v[36:39]
	v_mfma_f32_16x16x32_bf16 v[32:35], v[190:193], v[206:209], v[32:35]
	v_mfma_f32_16x16x32_bf16 v[20:23], v[166:169], v[214:217], v[20:23]
	v_mfma_f32_16x16x32_bf16 v[16:19], v[190:193], v[214:217], v[16:19]
	v_mfma_f32_16x16x32_bf16 v[4:7], v[166:169], v[222:225], v[4:7]
	v_mfma_f32_16x16x32_bf16 v[0:3], v[190:193], v[222:225], v[0:3]
	v_mfma_f32_16x16x32_bf16 v[52:55], v[170:173], v[202:205], v[52:55]
	v_mfma_f32_16x16x32_bf16 v[48:51], v[194:197], v[202:205], v[48:51]
	v_mfma_f32_16x16x32_bf16 v[36:39], v[170:173], v[210:213], v[36:39]
	v_mfma_f32_16x16x32_bf16 v[32:35], v[194:197], v[210:213], v[32:35]
	v_mfma_f32_16x16x32_bf16 v[20:23], v[170:173], v[218:221], v[20:23]
	v_mfma_f32_16x16x32_bf16 v[16:19], v[194:197], v[218:221], v[16:19]
	v_mfma_f32_16x16x32_bf16 v[4:7], v[170:173], v[226:229], v[4:7]
	v_mfma_f32_16x16x32_bf16 v[0:3], v[194:197], v[226:229], v[0:3]
	s_setprio 0
	s_barrier
	s_add_i32 s25, s25, 2
	s_add_u32 s40, s40, 0x100
	s_addc_u32 s41, s41, 0
	s_add_u32 vcc_hi, vcc_hi, 0x100
	s_addc_u32 s24, s24, 0
	s_cmp_gt_u32 s25, 13
	s_cbranch_scc0 .LBB0_358
	s_and_b64 vcc, exec, s[12:13]
	s_cbranch_vccz .LBB0_361
	s_barrier

; #define PG8_STAGE(bufoff, gbase, voff) do { _Pragma("unroll") for (int _i = 0; _i < 2; ++_i) \
;         __builtin_amdgcn_global_load_lds((const unsigned*)((const char*)(gbase) + (voff)[_i]), (PG8_LAS unsigned*)(lds + (bufoff) + ldsw + _i * 8192), 16, 0, 0); } while (0)
; #define PG8_LDA(dst, b, h) do { _Pragma("unroll") for (int m = 0; m < 4; ++m) _Pragma("unroll") for (int k = 0; k < 2; ++k) dst[m][k] = *(const PG8_LAS bf16x8*)(lds + PG8_SA(b, h) + aoff + m * 2048 + k * 1024); } while (0)
; #define PG8_LDB(dst, b, h) do { _Pragma("unroll") for (int n = 0; n < 2; ++n) _Pragma("unroll") for (int k = 0; k < 2; ++k) dst[n][k] = *(const PG8_LAS bf16x8*)(lds + PG8_SB(b, h) + boff + n * 2048 + k * 1024); } while (0)
; #define PG8_MMA(ai, bj, At, Bt) do { __builtin_amdgcn_s_setprio(1); _Pragma("unroll") for (int m = 0; m < 4; ++m) _Pragma("unroll") for (int n = 0; n < 2; ++n) _Pragma("unroll") for (int k = 0; k < 2; ++k) \
;         acc[ai][bj][m][n] = __builtin_amdgcn_mfma_f32_16x16x32_bf16(Bt[n][k], At[m][k], acc[ai][bj][m][n], 0, 0, 0); __builtin_amdgcn_s_setprio(0); } while (0)
; #define PG8_WAIT_V(n) asm volatile("s_waitcnt vmcnt(" #n ")" ::: "memory")
; #define PG8_WAIT_L(n) asm volatile("s_waitcnt lgkmcnt(" #n ")" ::: "memory")
; #define PG8_BAR __builtin_amdgcn_s_barrier()
; template <class Epi, class Sched, bool ALIGN_EPI = false, bool SP2 = false>
; __device__ __forceinline__ void gemm_phase(PG8_LAS unsigned char* lds, const Gemm g, const Sched& S, const Epi& E) {
;     ...
;             const char* a1 = cA + (size_t)(t + 1) * kstep;
;             const char* a2 = last ? nA : cA + (size_t)(t + 2) * kstep; const char* b2 = last ? nB : cB + (size_t)(t + 2) * kstep;
;             const char* a3 = a2 + kstep; const char* b3 = b2 + kstep;
;             if (last && has_next) S.a_ready(nxt);
;             if constexpr (SP2) {
;             PG8_LDB(B0, 0, 0); PG8_LDB(B1, 0, 1); PG8_SCHED; PG8_LDA(At, 0, 0); PG8_STAGE(PG8_SA(1, 1), a1 + hstep, voffA);
;             PG8_WAIT_V(8); PG8_WAIT_L(0); PG8_BAR; PG8_MMA(0, 0, At, B0); PG8_MMA(0, 1, At, B1); PG8_BAR; PG8_SCHED;
;             PG8_LDA(At, 0, 1); PG8_STAGE(PG8_SB(0, 0), b2, voffB); PG8_STAGE(PG8_SB(0, 1), b2 + hstep, voffB); PG8_STAGE(PG8_SA(0, 0), a2, voffA);
;             PG8_WAIT_V(8); PG8_WAIT_L(0); PG8_BAR; PG8_MMA(1, 0, At, B0); PG8_MMA(1, 1, At, B1); PG8_BAR; PG8_SCHED;
.LBB0_684:
	ds_read_b128 v[128:131], v174
	ds_read_b128 v[132:135], v174 offset:1024
	ds_read_b128 v[136:139], v174 offset:2048
	ds_read_b128 v[140:143], v174 offset:3072
	ds_read_b128 v[162:165], v175
	ds_read_b128 v[166:169], v175 offset:1024
	ds_read_b128 v[180:183], v175 offset:2048
	ds_read_b128 v[184:187], v175 offset:3072
	s_add_u32 s8, s0, 0xfffc0080
	s_addc_u32 s9, s1, -1
	s_cmp_eq_u32 vcc_lo, 12
	s_cselect_b32 s43, s3, s9
	s_cselect_b32 s42, s94, s8
	s_cselect_b32 s41, s5, s97
	s_cselect_b32 s40, s95, s96
	s_add_i32 m0, s47, 0xc000
	ds_read_b128 v[190:193], v176
	ds_read_b128 v[194:197], v176 offset:1024
	ds_read_b128 v[198:201], v176 offset:2048
	ds_read_b128 v[202:205], v176 offset:3072
	ds_read_b128 v[206:209], v176 offset:4096
	ds_read_b128 v[210:213], v176 offset:5120
	ds_read_b128 v[214:217], v176 offset:6144
	ds_read_b128 v[218:221], v176 offset:7168
	global_load_lds_dwordx4 v158, s[0:1]
	s_add_i32 m0, s47, 0xe000
	s_nop 0
	global_load_lds_dwordx4 v160, s[0:1]
	s_waitcnt vmcnt(8)
	s_waitcnt lgkmcnt(0)
	s_barrier
	s_setprio 1
	s_waitcnt lgkmcnt(0)
	v_mfma_f32_16x16x32_bf16 v[124:127], v[128:131], v[190:193], v[124:127]
	v_mfma_f32_16x16x32_bf16 v[120:123], v[136:139], v[190:193], v[120:123]
	v_mfma_f32_16x16x32_bf16 v[108:111], v[128:131], v[198:201], v[108:111]
	v_mfma_f32_16x16x32_bf16 v[104:107], v[136:139], v[198:201], v[104:107]
	v_mfma_f32_16x16x32_bf16 v[92:95], v[128:131], v[206:209], v[92:95]
	v_mfma_f32_16x16x32_bf16 v[88:91], v[136:139], v[206:209], v[88:91]
	v_mfma_f32_16x16x32_bf16 v[76:79], v[128:131], v[214:217], v[76:79]
	v_mfma_f32_16x16x32_bf16 v[72:75], v[136:139], v[214:217], v[72:75]
	v_mfma_f32_16x16x32_bf16 v[124:127], v[132:135], v[194:197], v[124:127]
	v_mfma_f32_16x16x32_bf16 v[120:123], v[140:143], v[194:197], v[120:123]
	v_mfma_f32_16x16x32_bf16 v[108:111], v[132:135], v[202:205], v[108:111]
	v_mfma_f32_16x16x32_bf16 v[104:107], v[140:143], v[202:205], v[104:107]
	v_mfma_f32_16x16x32_bf16 v[92:95], v[132:135], v[210:213], v[92:95]
	v_mfma_f32_16x16x32_bf16 v[88:91], v[140:143], v[210:213], v[88:91]
	v_mfma_f32_16x16x32_bf16 v[76:79], v[132:135], v[218:221], v[76:79]
	v_mfma_f32_16x16x32_bf16 v[72:75], v[140:143], v[218:221], v[72:75]
	v_mfma_f32_16x16x32_bf16 v[116:119], v[162:165], v[190:193], v[116:119]
	v_mfma_f32_16x16x32_bf16 v[112:115], v[180:183], v[190:193], v[112:115]
	v_mfma_f32_16x16x32_bf16 v[100:103], v[162:165], v[198:201], v[100:103]
	v_mfma_f32_16x16x32_bf16 v[96:99], v[180:183], v[198:201], v[96:99]
	v_mfma_f32_16x16x32_bf16 v[84:87], v[162:165], v[206:209], v[84:87]
	v_mfma_f32_16x16x32_bf16 v[80:83], v[180:183], v[206:209], v[80:83]
	v_mfma_f32_16x16x32_bf16 v[68:71], v[162:165], v[214:217], v[68:71]
	v_mfma_f32_16x16x32_bf16 v[64:67], v[180:183], v[214:217], v[64:67]
	v_mfma_f32_16x16x32_bf16 v[116:119], v[166:169], v[194:197], v[116:119]
	v_mfma_f32_16x16x32_bf16 v[112:115], v[184:187], v[194:197], v[112:115]
	v_mfma_f32_16x16x32_bf16 v[100:103], v[166:169], v[202:205], v[100:103]
	v_mfma_f32_16x16x32_bf16 v[96:99], v[184:187], v[202:205], v[96:99]
	v_mfma_f32_16x16x32_bf16 v[84:87], v[166:169], v[210:213], v[84:87]
	v_mfma_f32_16x16x32_bf16 v[80:83], v[184:187], v[210:213], v[80:83]
	v_mfma_f32_16x16x32_bf16 v[68:71], v[166:169], v[218:221], v[68:71]
	v_mfma_f32_16x16x32_bf16 v[64:67], v[184:187], v[218:221], v[64:67]
	s_setprio 0
	s_barrier
	s_add_i32 s8, s76, s46
	v_lshl_add_u64 v[170:171], s[40:41], 0, v[146:147]
	s_mov_b32 m0, s8
	ds_read_b128 v[190:193], v176 offset:16384
	ds_read_b128 v[194:197], v176 offset:17408
	ds_read_b128 v[198:201], v176 offset:18432
	ds_read_b128 v[202:205], v176 offset:19456
	ds_read_b128 v[206:209], v176 offset:20480
	ds_read_b128 v[210:213], v176 offset:21504
	ds_read_b128 v[214:217], v176 offset:22528
	ds_read_b128 v[218:221], v176 offset:23552
	global_load_lds_dwordx4 v[170:171], off
	s_add_i32 m0, s8, 0x2000
	s_add_u32 s8, s40, 0x40000
	v_lshl_add_u64 v[222:223], s[40:41], 0, v[150:151]
	s_addc_u32 s9, s41, 0
	s_add_i32 s54, s77, s46
	global_load_lds_dwordx4 v[222:223], off
	s_mov_b32 m0, s54
	v_lshl_add_u64 v[226:227], s[42:43], 0, v[148:149]
	global_load_lds_dwordx4 v146, s[8:9]
	s_add_i32 m0, s54, 0x2000
	s_nop 0
	global_load_lds_dwordx4 v150, s[8:9]
	v_lshl_add_u64 v[224:225], s[42:43], 0, v[144:145]
	s_mov_b32 m0, s47
	s_nop 0
	global_load_lds_dwordx4 v[224:225], off
	s_mov_b32 m0, s48
	s_nop 0
	global_load_lds_dwordx4 v[226:227], off
	s_waitcnt vmcnt(8)
	s_waitcnt lgkmcnt(0)
	s_barrier
	s_setprio 1
	s_waitcnt lgkmcnt(0)
	v_mfma_f32_16x16x32_bf16 v[60:63], v[128:131], v[190:193], v[60:63]
	v_mfma_f32_16x16x32_bf16 v[56:59], v[136:139], v[190:193], v[56:59]
	v_mfma_f32_16x16x32_bf16 v[44:47], v[128:131], v[198:201], v[44:47]
	v_mfma_f32_16x16x32_bf16 v[40:43], v[136:139], v[198:201], v[40:43]
	v_mfma_f32_16x16x32_bf16 v[28:31], v[128:131], v[206:209], v[28:31]
	v_mfma_f32_16x16x32_bf16 v[24:27], v[136:139], v[206:209], v[24:27]
	v_mfma_f32_16x16x32_bf16 v[12:15], v[128:131], v[214:217], v[12:15]
	v_mfma_f32_16x16x32_bf16 v[8:11], v[136:139], v[214:217], v[8:11]
	v_mfma_f32_16x16x32_bf16 v[60:63], v[132:135], v[194:197], v[60:63]
	v_mfma_f32_16x16x32_bf16 v[56:59], v[140:143], v[194:197], v[56:59]
	v_mfma_f32_16x16x32_bf16 v[44:47], v[132:135], v[202:205], v[44:47]
	v_mfma_f32_16x16x32_bf16 v[40:43], v[140:143], v[202:205], v[40:43]
	v_mfma_f32_16x16x32_bf16 v[28:31], v[132:135], v[210:213], v[28:31]
	v_mfma_f32_16x16x32_bf16 v[24:27], v[140:143], v[210:213], v[24:27]
	v_mfma_f32_16x16x32_bf16 v[12:15], v[132:135], v[218:221], v[12:15]
	v_mfma_f32_16x16x32_bf16 v[8:11], v[140:143], v[218:221], v[8:11]
	v_mfma_f32_16x16x32_bf16 v[52:55], v[162:165], v[190:193], v[52:55]
	v_mfma_f32_16x16x32_bf16 v[48:51], v[180:183], v[190:193], v[48:51]
	v_mfma_f32_16x16x32_bf16 v[36:39], v[162:165], v[198:201], v[36:39]
	v_mfma_f32_16x16x32_bf16 v[32:35], v[180:183], v[198:201], v[32:35]
	v_mfma_f32_16x16x32_bf16 v[20:23], v[162:165], v[206:209], v[20:23]
	v_mfma_f32_16x16x32_bf16 v[16:19], v[180:183], v[206:209], v[16:19]
	v_mfma_f32_16x16x32_bf16 v[4:7], v[162:165], v[214:217], v[4:7]
	v_mfma_f32_16x16x32_bf16 v[0:3], v[180:183], v[214:217], v[0:3]
	v_mfma_f32_16x16x32_bf16 v[52:55], v[166:169], v[194:197], v[52:55]
	v_mfma_f32_16x16x32_bf16 v[48:51], v[184:187], v[194:197], v[48:51]
	v_mfma_f32_16x16x32_bf16 v[36:39], v[166:169], v[202:205], v[36:39]
	v_mfma_f32_16x16x32_bf16 v[32:35], v[184:187], v[202:205], v[32:35]
	v_mfma_f32_16x16x32_bf16 v[20:23], v[166:169], v[210:213], v[20:23]
	v_mfma_f32_16x16x32_bf16 v[16:19], v[184:187], v[210:213], v[16:19]
	v_mfma_f32_16x16x32_bf16 v[4:7], v[166:169], v[218:221], v[4:7]
	v_mfma_f32_16x16x32_bf16 v[0:3], v[184:187], v[218:221], v[0:3]
	s_setprio 0
	s_barrier
; #define PG8_STAGE(bufoff, gbase, voff) do { _Pragma("unroll") for (int _i = 0; _i < 2; ++_i) \
;         __builtin_amdgcn_global_load_lds((const unsigned*)((const char*)(gbase) + (voff)[_i]), (PG8_LAS unsigned*)(lds + (bufoff) + ldsw + _i * 8192), 16, 0, 0); } while (0)
; #define PG8_LDA(dst, b, h) do { _Pragma("unroll") for (int m = 0; m < 4; ++m) _Pragma("unroll") for (int k = 0; k < 2; ++k) dst[m][k] = *(const PG8_LAS bf16x8*)(lds + PG8_SA(b, h) + aoff + m * 2048 + k * 1024); } while (0)
; #define PG8_LDB(dst, b, h) do { _Pragma("unroll") for (int n = 0; n < 2; ++n) _Pragma("unroll") for (int k = 0; k < 2; ++k) dst[n][k] = *(const PG8_LAS bf16x8*)(lds + PG8_SB(b, h) + boff + n * 2048 + k * 1024); } while (0)
; #define PG8_MMA(ai, bj, At, Bt) do { __builtin_amdgcn_s_setprio(1); _Pragma("unroll") for (int m = 0; m < 4; ++m) _Pragma("unroll") for (int n = 0; n < 2; ++n) _Pragma("unroll") for (int k = 0; k < 2; ++k) \
;         acc[ai][bj][m][n] = __builtin_amdgcn_mfma_f32_16x16x32_bf16(Bt[n][k], At[m][k], acc[ai][bj][m][n], 0, 0, 0); __builtin_amdgcn_s_setprio(0); } while (0)
; #define PG8_WAIT_V(n) asm volatile("s_waitcnt vmcnt(" #n ")" ::: "memory")
; #define PG8_WAIT_L(n) asm volatile("s_waitcnt lgkmcnt(" #n ")" ::: "memory")
; #define PG8_BAR __builtin_amdgcn_s_barrier()
; #define PG8_SCHED __builtin_amdgcn_sched_barrier(0)
; template <class Epi, class Sched, bool ALIGN_EPI = false, bool SP2 = false>
; __device__ __forceinline__ void gemm_phase(PG8_LAS unsigned char* lds, const Gemm g, const Sched& S, const Epi& E) {
;     ...
;         for (int t = 0; t < nt; t += 2) {
;             const bool last = (t == nt - 2);
;     ...
;             PG8_LDB(B0, 1, 0); PG8_LDB(B1, 1, 1); PG8_SCHED; PG8_LDA(At, 1, 0); PG8_STAGE(PG8_SA(0, 1), a2 + hstep, voffA);
;             PG8_WAIT_V(8); PG8_WAIT_L(0); PG8_BAR; PG8_MMA(0, 0, At, B0); PG8_MMA(0, 1, At, B1); PG8_BAR; PG8_SCHED;
;             PG8_LDA(At, 1, 1); PG8_STAGE(PG8_SB(1, 0), b3, voffB); PG8_STAGE(PG8_SB(1, 1), b3 + hstep, voffB); PG8_STAGE(PG8_SA(1, 0), a3, voffA);
;             PG8_WAIT_V(8); PG8_WAIT_L(0); PG8_BAR; PG8_MMA(1, 0, At, B0); PG8_MMA(1, 1, At, B1); PG8_BAR; PG8_SCHED;
	s_add_i32 s54, 0, 0x18000
	s_add_i32 s55, 0, 0x1c000
	v_add_u32_e32 v140, s54, v172
	v_add_u32_e32 v152, s55, v172
	ds_read_b128 v[128:131], v140
	ds_read_b128 v[132:135], v140 offset:1024
	ds_read_b128 v[136:139], v140 offset:2048
	ds_read_b128 v[140:143], v140 offset:3072
	ds_read_b128 v[162:165], v152
	ds_read_b128 v[166:169], v152 offset:1024
	ds_read_b128 v[180:183], v152 offset:2048
	ds_read_b128 v[184:187], v152 offset:3072
	s_add_u32 s8, s42, 0x40000
	s_addc_u32 s9, s43, 0
	s_mov_b32 m0, s49
	ds_read_b128 v[190:193], v176 offset:32768
	ds_read_b128 v[194:197], v176 offset:33792
	ds_read_b128 v[198:201], v176 offset:34816
	ds_read_b128 v[202:205], v176 offset:35840
	ds_read_b128 v[206:209], v176 offset:36864
	ds_read_b128 v[210:213], v176 offset:37888
	ds_read_b128 v[214:217], v176 offset:38912
	ds_read_b128 v[218:221], v176 offset:39936
	global_load_lds_dwordx4 v144, s[8:9]
	s_mov_b32 m0, s51
	s_nop 0
	global_load_lds_dwordx4 v148, s[8:9]
	s_waitcnt vmcnt(8)
	s_waitcnt lgkmcnt(0)
	s_barrier
	s_setprio 1
	s_waitcnt lgkmcnt(0)
	v_mfma_f32_16x16x32_bf16 v[124:127], v[128:131], v[190:193], v[124:127]
	v_mfma_f32_16x16x32_bf16 v[120:123], v[136:139], v[190:193], v[120:123]
	v_mfma_f32_16x16x32_bf16 v[108:111], v[128:131], v[198:201], v[108:111]
	v_mfma_f32_16x16x32_bf16 v[104:107], v[136:139], v[198:201], v[104:107]
	v_mfma_f32_16x16x32_bf16 v[92:95], v[128:131], v[206:209], v[92:95]
	v_mfma_f32_16x16x32_bf16 v[88:91], v[136:139], v[206:209], v[88:91]
	v_mfma_f32_16x16x32_bf16 v[76:79], v[128:131], v[214:217], v[76:79]
	v_mfma_f32_16x16x32_bf16 v[72:75], v[136:139], v[214:217], v[72:75]
	v_mfma_f32_16x16x32_bf16 v[124:127], v[132:135], v[194:197], v[124:127]
	v_mfma_f32_16x16x32_bf16 v[120:123], v[140:143], v[194:197], v[120:123]
	v_mfma_f32_16x16x32_bf16 v[108:111], v[132:135], v[202:205], v[108:111]
	v_mfma_f32_16x16x32_bf16 v[104:107], v[140:143], v[202:205], v[104:107]
	v_mfma_f32_16x16x32_bf16 v[92:95], v[132:135], v[210:213], v[92:95]
	v_mfma_f32_16x16x32_bf16 v[88:91], v[140:143], v[210:213], v[88:91]
	v_mfma_f32_16x16x32_bf16 v[76:79], v[132:135], v[218:221], v[76:79]
	v_mfma_f32_16x16x32_bf16 v[72:75], v[140:143], v[218:221], v[72:75]
	v_mfma_f32_16x16x32_bf16 v[116:119], v[162:165], v[190:193], v[116:119]
	v_mfma_f32_16x16x32_bf16 v[112:115], v[180:183], v[190:193], v[112:115]
	v_mfma_f32_16x16x32_bf16 v[100:103], v[162:165], v[198:201], v[100:103]
	v_mfma_f32_16x16x32_bf16 v[96:99], v[180:183], v[198:201], v[96:99]
	v_mfma_f32_16x16x32_bf16 v[84:87], v[162:165], v[206:209], v[84:87]
	v_mfma_f32_16x16x32_bf16 v[80:83], v[180:183], v[206:209], v[80:83]
	v_mfma_f32_16x16x32_bf16 v[68:71], v[162:165], v[214:217], v[68:71]
	v_mfma_f32_16x16x32_bf16 v[64:67], v[180:183], v[214:217], v[64:67]
	v_mfma_f32_16x16x32_bf16 v[116:119], v[166:169], v[194:197], v[116:119]
	v_mfma_f32_16x16x32_bf16 v[112:115], v[184:187], v[194:197], v[112:115]
	v_mfma_f32_16x16x32_bf16 v[100:103], v[166:169], v[202:205], v[100:103]
	v_mfma_f32_16x16x32_bf16 v[96:99], v[184:187], v[202:205], v[96:99]
	v_mfma_f32_16x16x32_bf16 v[84:87], v[166:169], v[210:213], v[84:87]
	v_mfma_f32_16x16x32_bf16 v[80:83], v[184:187], v[210:213], v[80:83]
	v_mfma_f32_16x16x32_bf16 v[68:71], v[166:169], v[218:221], v[68:71]
	v_mfma_f32_16x16x32_bf16 v[64:67], v[184:187], v[218:221], v[64:67]
	s_setprio 0
	s_barrier
	s_add_i32 s8, s54, s46
	v_lshl_add_u64 v[170:171], v[170:171], 0, s[14:15]
	s_mov_b32 m0, s8
	ds_read_b128 v[190:193], v176 offset:49152
	ds_read_b128 v[194:197], v176 offset:50176
	ds_read_b128 v[198:201], v176 offset:51200
	ds_read_b128 v[202:205], v176 offset:52224
	ds_read_b128 v[206:209], v176 offset:53248
	ds_read_b128 v[210:213], v176 offset:54272
	ds_read_b128 v[214:217], v176 offset:55296
	ds_read_b128 v[218:221], v176 offset:56320
	global_load_lds_dwordx4 v[170:171], off
	s_add_i32 m0, s8, 0x2000
	s_add_u32 s8, s40, 0x40080
	v_lshl_add_u64 v[170:171], v[222:223], 0, s[14:15]
	s_addc_u32 s9, s41, 0
	s_add_i32 s40, s55, s46
	global_load_lds_dwordx4 v[170:171], off
	s_mov_b32 m0, s40
	s_nop 0
	global_load_lds_dwordx4 v146, s[8:9]
	s_add_i32 m0, s40, 0x2000
	s_nop 0
	global_load_lds_dwordx4 v150, s[8:9]
	v_lshl_add_u64 v[170:171], v[224:225], 0, s[14:15]
	s_mov_b32 m0, s66
	s_nop 0
	global_load_lds_dwordx4 v[170:171], off
	v_lshl_add_u64 v[170:171], v[226:227], 0, s[14:15]
	s_mov_b32 m0, s67
	s_nop 0
	global_load_lds_dwordx4 v[170:171], off
	s_waitcnt vmcnt(8)
	s_waitcnt lgkmcnt(0)
	s_barrier
	s_setprio 1
	s_waitcnt lgkmcnt(0)
	v_mfma_f32_16x16x32_bf16 v[60:63], v[128:131], v[190:193], v[60:63]
	v_mfma_f32_16x16x32_bf16 v[56:59], v[136:139], v[190:193], v[56:59]
	v_mfma_f32_16x16x32_bf16 v[44:47], v[128:131], v[198:201], v[44:47]
	v_mfma_f32_16x16x32_bf16 v[40:43], v[136:139], v[198:201], v[40:43]
	v_mfma_f32_16x16x32_bf16 v[28:31], v[128:131], v[206:209], v[28:31]
	v_mfma_f32_16x16x32_bf16 v[24:27], v[136:139], v[206:209], v[24:27]
	v_mfma_f32_16x16x32_bf16 v[12:15], v[128:131], v[214:217], v[12:15]
	v_mfma_f32_16x16x32_bf16 v[8:11], v[136:139], v[214:217], v[8:11]
	v_mfma_f32_16x16x32_bf16 v[60:63], v[132:135], v[194:197], v[60:63]
	v_mfma_f32_16x16x32_bf16 v[56:59], v[140:143], v[194:197], v[56:59]
	v_mfma_f32_16x16x32_bf16 v[44:47], v[132:135], v[202:205], v[44:47]
	v_mfma_f32_16x16x32_bf16 v[40:43], v[140:143], v[202:205], v[40:43]
	v_mfma_f32_16x16x32_bf16 v[28:31], v[132:135], v[210:213], v[28:31]
	v_mfma_f32_16x16x32_bf16 v[24:27], v[140:143], v[210:213], v[24:27]
	v_mfma_f32_16x16x32_bf16 v[12:15], v[132:135], v[218:221], v[12:15]
	v_mfma_f32_16x16x32_bf16 v[8:11], v[140:143], v[218:221], v[8:11]
	v_mfma_f32_16x16x32_bf16 v[52:55], v[162:165], v[190:193], v[52:55]
	v_mfma_f32_16x16x32_bf16 v[48:51], v[180:183], v[190:193], v[48:51]
	v_mfma_f32_16x16x32_bf16 v[36:39], v[162:165], v[198:201], v[36:39]
	v_mfma_f32_16x16x32_bf16 v[32:35], v[180:183], v[198:201], v[32:35]
	v_mfma_f32_16x16x32_bf16 v[20:23], v[162:165], v[206:209], v[20:23]
	v_mfma_f32_16x16x32_bf16 v[16:19], v[180:183], v[206:209], v[16:19]
	v_mfma_f32_16x16x32_bf16 v[4:7], v[162:165], v[214:217], v[4:7]
	v_mfma_f32_16x16x32_bf16 v[0:3], v[180:183], v[214:217], v[0:3]
	v_mfma_f32_16x16x32_bf16 v[52:55], v[166:169], v[194:197], v[52:55]
	v_mfma_f32_16x16x32_bf16 v[48:51], v[184:187], v[194:197], v[48:51]
	v_mfma_f32_16x16x32_bf16 v[36:39], v[166:169], v[202:205], v[36:39]
	v_mfma_f32_16x16x32_bf16 v[32:35], v[184:187], v[202:205], v[32:35]
	v_mfma_f32_16x16x32_bf16 v[20:23], v[166:169], v[210:213], v[20:23]
	v_mfma_f32_16x16x32_bf16 v[16:19], v[184:187], v[210:213], v[16:19]
	v_mfma_f32_16x16x32_bf16 v[4:7], v[166:169], v[218:221], v[4:7]
	v_mfma_f32_16x16x32_bf16 v[0:3], v[184:187], v[218:221], v[0:3]
	s_setprio 0
	s_barrier
	s_add_i32 vcc_lo, vcc_lo, 2
	s_add_u32 s0, s0, 0x100
	s_addc_u32 s1, s1, 0
	s_add_u32 s96, s96, 0x100
	s_addc_u32 s97, s97, 0
	s_cmp_gt_u32 vcc_lo, 13
	s_cbranch_scc0 .LBB0_684
	s_and_b64 vcc, exec, s[18:19]
	s_cbranch_vccz .LBB0_687
	s_barrier

; #define PG8_STAGE(bufoff, gbase, voff) do { _Pragma("unroll") for (int _i = 0; _i < 2; ++_i) \
;         __builtin_amdgcn_global_load_lds((const unsigned*)((const char*)(gbase) + (voff)[_i]), (PG8_LAS unsigned*)(lds + (bufoff) + ldsw + _i * 8192), 16, 0, 0); } while (0)
; #define PG8_LDA(dst, b, h) do { _Pragma("unroll") for (int m = 0; m < 4; ++m) _Pragma("unroll") for (int k = 0; k < 2; ++k) dst[m][k] = *(const PG8_LAS bf16x8*)(lds + PG8_SA(b, h) + aoff + m * 2048 + k * 1024); } while (0)
; #define PG8_LDB(dst, b, h) do { _Pragma("unroll") for (int n = 0; n < 2; ++n) _Pragma("unroll") for (int k = 0; k < 2; ++k) dst[n][k] = *(const PG8_LAS bf16x8*)(lds + PG8_SB(b, h) + boff + n * 2048 + k * 1024); } while (0)
; #define PG8_MMA(ai, bj, At, Bt) do { __builtin_amdgcn_s_setprio(1); _Pragma("unroll") for (int m = 0; m < 4; ++m) _Pragma("unroll") for (int n = 0; n < 2; ++n) _Pragma("unroll") for (int k = 0; k < 2; ++k) \
;         acc[ai][bj][m][n] = __builtin_amdgcn_mfma_f32_16x16x32_bf16(Bt[n][k], At[m][k], acc[ai][bj][m][n], 0, 0, 0); __builtin_amdgcn_s_setprio(0); } while (0)
; #define PG8_WAIT_V(n) asm volatile("s_waitcnt vmcnt(" #n ")" ::: "memory")
; #define PG8_WAIT_L(n) asm volatile("s_waitcnt lgkmcnt(" #n ")" ::: "memory")
; #define PG8_BAR __builtin_amdgcn_s_barrier()
; #define PG8_SCHED __builtin_amdgcn_sched_barrier(0)
; template <class Epi, class Sched, bool ALIGN_EPI = false, bool SP2 = false>
; __device__ __forceinline__ void gemm_phase(PG8_LAS unsigned char* lds, const Gemm g, const Sched& S, const Epi& E) {
;     ...
;             const char* a1 = cA + (size_t)(t + 1) * kstep;
;             const char* a2 = last ? nA : cA + (size_t)(t + 2) * kstep; const char* b2 = last ? nB : cB + (size_t)(t + 2) * kstep;
;             const char* a3 = a2 + kstep; const char* b3 = b2 + kstep;
;             if (last && has_next) S.a_ready(nxt);
;             if constexpr (SP2) {
;             PG8_LDB(B0, 0, 0); PG8_LDB(B1, 0, 1); PG8_SCHED; PG8_LDA(At, 0, 0); PG8_STAGE(PG8_SA(1, 1), a1 + hstep, voffA);
;             PG8_WAIT_V(8); PG8_WAIT_L(0); PG8_BAR; PG8_MMA(0, 0, At, B0); PG8_MMA(0, 1, At, B1); PG8_BAR; PG8_SCHED;
;             PG8_LDA(At, 0, 1); PG8_STAGE(PG8_SB(0, 0), b2, voffB); PG8_STAGE(PG8_SB(0, 1), b2 + hstep, voffB); PG8_STAGE(PG8_SA(0, 0), a2, voffA);
.LBB0_795:
	v_add_u32_e32 v162, s67, v186
	v_add_u32_e32 v178, s68, v186
	ds_read_b128 v[150:153], v162
	ds_read_b128 v[154:157], v162 offset:1024
	ds_read_b128 v[158:161], v162 offset:2048
	ds_read_b128 v[162:165], v162 offset:3072
	ds_read_b128 v[166:169], v178
	ds_read_b128 v[170:173], v178 offset:1024
	ds_read_b128 v[174:177], v178 offset:2048
	ds_read_b128 v[178:181], v178 offset:3072
	s_add_u32 s54, s46, 0xfff80080
	s_addc_u32 s55, s47, -1
	s_cmp_eq_u32 s82, 12
	s_cselect_b32 s57, s41, s55
	s_cselect_b32 s56, s78, s54
	s_cselect_b32 s55, s39, s81
	s_cselect_b32 s54, s79, s80
	s_add_i32 m0, s61, 0xc000
	ds_read_b128 v[182:185], v187
	ds_read_b128 v[190:193], v187 offset:1024
	ds_read_b128 v[194:197], v187 offset:2048
	ds_read_b128 v[198:201], v187 offset:3072
	ds_read_b128 v[202:205], v187 offset:4096
	ds_read_b128 v[206:209], v187 offset:5120
	ds_read_b128 v[210:213], v187 offset:6144
	ds_read_b128 v[214:217], v187 offset:7168
	global_load_lds_dwordx4 v142, s[46:47]
	s_add_i32 m0, s61, 0xe000
	s_nop 0
	global_load_lds_dwordx4 v144, s[46:47]
	s_waitcnt vmcnt(8)
	s_waitcnt lgkmcnt(0)
	s_barrier
	s_setprio 1
	s_waitcnt lgkmcnt(0)
	v_mfma_f32_16x16x32_bf16 v[124:127], v[150:153], v[182:185], v[124:127]
	v_mfma_f32_16x16x32_bf16 v[120:123], v[158:161], v[182:185], v[120:123]
	v_mfma_f32_16x16x32_bf16 v[116:119], v[150:153], v[194:197], v[116:119]
	v_mfma_f32_16x16x32_bf16 v[112:115], v[158:161], v[194:197], v[112:115]
	v_mfma_f32_16x16x32_bf16 v[108:111], v[150:153], v[202:205], v[108:111]
	v_mfma_f32_16x16x32_bf16 v[104:107], v[158:161], v[202:205], v[104:107]
	v_mfma_f32_16x16x32_bf16 v[100:103], v[150:153], v[210:213], v[100:103]
	v_mfma_f32_16x16x32_bf16 v[96:99], v[158:161], v[210:213], v[96:99]
	v_mfma_f32_16x16x32_bf16 v[124:127], v[154:157], v[190:193], v[124:127]
	v_mfma_f32_16x16x32_bf16 v[120:123], v[162:165], v[190:193], v[120:123]
	v_mfma_f32_16x16x32_bf16 v[116:119], v[154:157], v[198:201], v[116:119]
	v_mfma_f32_16x16x32_bf16 v[112:115], v[162:165], v[198:201], v[112:115]
	v_mfma_f32_16x16x32_bf16 v[108:111], v[154:157], v[206:209], v[108:111]
	v_mfma_f32_16x16x32_bf16 v[104:107], v[162:165], v[206:209], v[104:107]
	v_mfma_f32_16x16x32_bf16 v[100:103], v[154:157], v[214:217], v[100:103]
	v_mfma_f32_16x16x32_bf16 v[96:99], v[162:165], v[214:217], v[96:99]
	v_mfma_f32_16x16x32_bf16 v[92:95], v[166:169], v[182:185], v[92:95]
	v_mfma_f32_16x16x32_bf16 v[88:91], v[174:177], v[182:185], v[88:91]
	v_mfma_f32_16x16x32_bf16 v[84:87], v[166:169], v[194:197], v[84:87]
	v_mfma_f32_16x16x32_bf16 v[80:83], v[174:177], v[194:197], v[80:83]
	v_mfma_f32_16x16x32_bf16 v[76:79], v[166:169], v[202:205], v[76:79]
	v_mfma_f32_16x16x32_bf16 v[72:75], v[174:177], v[202:205], v[72:75]
	v_mfma_f32_16x16x32_bf16 v[68:71], v[166:169], v[210:213], v[68:71]
	v_mfma_f32_16x16x32_bf16 v[64:67], v[174:177], v[210:213], v[64:67]
	v_mfma_f32_16x16x32_bf16 v[92:95], v[170:173], v[190:193], v[92:95]
	v_mfma_f32_16x16x32_bf16 v[88:91], v[178:181], v[190:193], v[88:91]
	v_mfma_f32_16x16x32_bf16 v[84:87], v[170:173], v[198:201], v[84:87]
	v_mfma_f32_16x16x32_bf16 v[80:83], v[178:181], v[198:201], v[80:83]
	v_mfma_f32_16x16x32_bf16 v[76:79], v[170:173], v[206:209], v[76:79]
	v_mfma_f32_16x16x32_bf16 v[72:75], v[178:181], v[206:209], v[72:75]
	v_mfma_f32_16x16x32_bf16 v[68:71], v[170:173], v[214:217], v[68:71]
	v_mfma_f32_16x16x32_bf16 v[64:67], v[178:181], v[214:217], v[64:67]
	s_setprio 0
	s_barrier
	s_add_i32 s83, s67, s60
	v_lshl_add_u64 v[218:219], s[54:55], 0, v[130:131]
	s_mov_b32 m0, s83
	ds_read_b128 v[182:185], v187 offset:16384
	ds_read_b128 v[190:193], v187 offset:17408
	ds_read_b128 v[194:197], v187 offset:18432
	ds_read_b128 v[198:201], v187 offset:19456
	ds_read_b128 v[202:205], v187 offset:20480
	ds_read_b128 v[206:209], v187 offset:21504
	ds_read_b128 v[210:213], v187 offset:22528
	ds_read_b128 v[214:217], v187 offset:23552
	global_load_lds_dwordx4 v[218:219], off
	s_add_i32 m0, s83, 0x2000
	s_add_u32 s86, s54, 0x80000
	v_lshl_add_u64 v[220:221], s[54:55], 0, v[134:135]
	s_addc_u32 s87, s55, 0
	s_add_i32 s83, s68, s60
	global_load_lds_dwordx4 v[220:221], off
	s_mov_b32 m0, s83
	v_lshl_add_u64 v[224:225], s[56:57], 0, v[132:133]
	global_load_lds_dwordx4 v130, s[86:87]
	s_add_i32 m0, s83, 0x2000
	s_nop 0
	global_load_lds_dwordx4 v134, s[86:87]
	v_lshl_add_u64 v[222:223], s[56:57], 0, v[128:129]
	s_mov_b32 m0, s61
	s_nop 0
	global_load_lds_dwordx4 v[222:223], off
	s_mov_b32 m0, s62
	s_nop 0
	global_load_lds_dwordx4 v[224:225], off
	s_waitcnt vmcnt(8)
	s_waitcnt lgkmcnt(0)
	s_barrier
; #define PG8_STAGE(bufoff, gbase, voff) do { _Pragma("unroll") for (int _i = 0; _i < 2; ++_i) \
;         __builtin_amdgcn_global_load_lds((const unsigned*)((const char*)(gbase) + (voff)[_i]), (PG8_LAS unsigned*)(lds + (bufoff) + ldsw + _i * 8192), 16, 0, 0); } while (0)
; #define PG8_LDA(dst, b, h) do { _Pragma("unroll") for (int m = 0; m < 4; ++m) _Pragma("unroll") for (int k = 0; k < 2; ++k) dst[m][k] = *(const PG8_LAS bf16x8*)(lds + PG8_SA(b, h) + aoff + m * 2048 + k * 1024); } while (0)
; #define PG8_LDB(dst, b, h) do { _Pragma("unroll") for (int n = 0; n < 2; ++n) _Pragma("unroll") for (int k = 0; k < 2; ++k) dst[n][k] = *(const PG8_LAS bf16x8*)(lds + PG8_SB(b, h) + boff + n * 2048 + k * 1024); } while (0)
; #define PG8_MMA(ai, bj, At, Bt) do { __builtin_amdgcn_s_setprio(1); _Pragma("unroll") for (int m = 0; m < 4; ++m) _Pragma("unroll") for (int n = 0; n < 2; ++n) _Pragma("unroll") for (int k = 0; k < 2; ++k) \
;         acc[ai][bj][m][n] = __builtin_amdgcn_mfma_f32_16x16x32_bf16(Bt[n][k], At[m][k], acc[ai][bj][m][n], 0, 0, 0); __builtin_amdgcn_s_setprio(0); } while (0)
; #define PG8_WAIT_V(n) asm volatile("s_waitcnt vmcnt(" #n ")" ::: "memory")
; #define PG8_WAIT_L(n) asm volatile("s_waitcnt lgkmcnt(" #n ")" ::: "memory")
; #define PG8_BAR __builtin_amdgcn_s_barrier()
; #define PG8_SCHED __builtin_amdgcn_sched_barrier(0)
; template <class Epi, class Sched, bool ALIGN_EPI = false, bool SP2 = false>
; __device__ __forceinline__ void gemm_phase(PG8_LAS unsigned char* lds, const Gemm g, const Sched& S, const Epi& E) {
;     ...
;             PG8_WAIT_V(8); PG8_WAIT_L(0); PG8_BAR; PG8_MMA(1, 0, At, B0); PG8_MMA(1, 1, At, B1); PG8_BAR; PG8_SCHED;
;             PG8_LDB(B0, 1, 0); PG8_LDB(B1, 1, 1); PG8_SCHED; PG8_LDA(At, 1, 0); PG8_STAGE(PG8_SA(0, 1), a2 + hstep, voffA);
;             PG8_WAIT_V(8); PG8_WAIT_L(0); PG8_BAR; PG8_MMA(0, 0, At, B0); PG8_MMA(0, 1, At, B1); PG8_BAR; PG8_SCHED;
	s_setprio 1
	s_waitcnt lgkmcnt(0)
	v_mfma_f32_16x16x32_bf16 v[60:63], v[150:153], v[182:185], v[60:63]
	v_mfma_f32_16x16x32_bf16 v[56:59], v[158:161], v[182:185], v[56:59]
	v_mfma_f32_16x16x32_bf16 v[52:55], v[150:153], v[194:197], v[52:55]
	v_mfma_f32_16x16x32_bf16 v[48:51], v[158:161], v[194:197], v[48:51]
	v_mfma_f32_16x16x32_bf16 v[44:47], v[150:153], v[202:205], v[44:47]
	v_mfma_f32_16x16x32_bf16 v[40:43], v[158:161], v[202:205], v[40:43]
	v_mfma_f32_16x16x32_bf16 v[36:39], v[150:153], v[210:213], v[36:39]
	v_mfma_f32_16x16x32_bf16 v[32:35], v[158:161], v[210:213], v[32:35]
	v_mfma_f32_16x16x32_bf16 v[60:63], v[154:157], v[190:193], v[60:63]
	v_mfma_f32_16x16x32_bf16 v[56:59], v[162:165], v[190:193], v[56:59]
	v_mfma_f32_16x16x32_bf16 v[52:55], v[154:157], v[198:201], v[52:55]
	v_mfma_f32_16x16x32_bf16 v[48:51], v[162:165], v[198:201], v[48:51]
	v_mfma_f32_16x16x32_bf16 v[44:47], v[154:157], v[206:209], v[44:47]
	v_mfma_f32_16x16x32_bf16 v[40:43], v[162:165], v[206:209], v[40:43]
	v_mfma_f32_16x16x32_bf16 v[36:39], v[154:157], v[214:217], v[36:39]
	v_mfma_f32_16x16x32_bf16 v[32:35], v[162:165], v[214:217], v[32:35]
	v_mfma_f32_16x16x32_bf16 v[28:31], v[166:169], v[182:185], v[28:31]
	v_mfma_f32_16x16x32_bf16 v[24:27], v[174:177], v[182:185], v[24:27]
	v_mfma_f32_16x16x32_bf16 v[20:23], v[166:169], v[194:197], v[20:23]
	v_mfma_f32_16x16x32_bf16 v[16:19], v[174:177], v[194:197], v[16:19]
	v_mfma_f32_16x16x32_bf16 v[12:15], v[166:169], v[202:205], v[12:15]
	v_mfma_f32_16x16x32_bf16 v[8:11], v[174:177], v[202:205], v[8:11]
	v_mfma_f32_16x16x32_bf16 v[4:7], v[166:169], v[210:213], v[4:7]
	v_mfma_f32_16x16x32_bf16 v[0:3], v[174:177], v[210:213], v[0:3]
	v_mfma_f32_16x16x32_bf16 v[28:31], v[170:173], v[190:193], v[28:31]
	v_mfma_f32_16x16x32_bf16 v[24:27], v[178:181], v[190:193], v[24:27]
	v_mfma_f32_16x16x32_bf16 v[20:23], v[170:173], v[198:201], v[20:23]
	v_mfma_f32_16x16x32_bf16 v[16:19], v[178:181], v[198:201], v[16:19]
	v_mfma_f32_16x16x32_bf16 v[12:15], v[170:173], v[206:209], v[12:15]
	v_mfma_f32_16x16x32_bf16 v[8:11], v[178:181], v[206:209], v[8:11]
	v_mfma_f32_16x16x32_bf16 v[4:7], v[170:173], v[214:217], v[4:7]
	v_mfma_f32_16x16x32_bf16 v[0:3], v[178:181], v[214:217], v[0:3]
	s_setprio 0
	s_barrier
	s_add_i32 s83, 0, 0x18000
	s_add_i32 s86, 0, 0x1c000
	v_add_u32_e32 v162, s83, v186
	v_add_u32_e32 v178, s86, v186
	ds_read_b128 v[150:153], v162
	ds_read_b128 v[154:157], v162 offset:1024
	ds_read_b128 v[158:161], v162 offset:2048
	ds_read_b128 v[162:165], v162 offset:3072
	ds_read_b128 v[166:169], v178
	ds_read_b128 v[170:173], v178 offset:1024
	ds_read_b128 v[174:177], v178 offset:2048
	ds_read_b128 v[178:181], v178 offset:3072
	s_add_u32 s56, s56, 0x80000
	s_addc_u32 s57, s57, 0
	s_mov_b32 m0, s63
	ds_read_b128 v[182:185], v187 offset:32768
	ds_read_b128 v[190:193], v187 offset:33792
	ds_read_b128 v[194:197], v187 offset:34816
	ds_read_b128 v[198:201], v187 offset:35840
	ds_read_b128 v[202:205], v187 offset:36864
	ds_read_b128 v[206:209], v187 offset:37888
	ds_read_b128 v[210:213], v187 offset:38912
	ds_read_b128 v[214:217], v187 offset:39936
	global_load_lds_dwordx4 v128, s[56:57]
	s_mov_b32 m0, s64
	s_nop 0
	global_load_lds_dwordx4 v132, s[56:57]
	s_waitcnt vmcnt(8)
	s_waitcnt lgkmcnt(0)
	s_barrier
	s_setprio 1
	s_waitcnt lgkmcnt(0)
	v_mfma_f32_16x16x32_bf16 v[124:127], v[150:153], v[182:185], v[124:127]
	v_mfma_f32_16x16x32_bf16 v[120:123], v[158:161], v[182:185], v[120:123]
	v_mfma_f32_16x16x32_bf16 v[116:119], v[150:153], v[194:197], v[116:119]
	v_mfma_f32_16x16x32_bf16 v[112:115], v[158:161], v[194:197], v[112:115]
	v_mfma_f32_16x16x32_bf16 v[108:111], v[150:153], v[202:205], v[108:111]
	v_mfma_f32_16x16x32_bf16 v[104:107], v[158:161], v[202:205], v[104:107]
	v_mfma_f32_16x16x32_bf16 v[100:103], v[150:153], v[210:213], v[100:103]
	v_mfma_f32_16x16x32_bf16 v[96:99], v[158:161], v[210:213], v[96:99]
	v_mfma_f32_16x16x32_bf16 v[124:127], v[154:157], v[190:193], v[124:127]
	v_mfma_f32_16x16x32_bf16 v[120:123], v[162:165], v[190:193], v[120:123]
	v_mfma_f32_16x16x32_bf16 v[116:119], v[154:157], v[198:201], v[116:119]
	v_mfma_f32_16x16x32_bf16 v[112:115], v[162:165], v[198:201], v[112:115]
	v_mfma_f32_16x16x32_bf16 v[108:111], v[154:157], v[206:209], v[108:111]
	v_mfma_f32_16x16x32_bf16 v[104:107], v[162:165], v[206:209], v[104:107]
	v_mfma_f32_16x16x32_bf16 v[100:103], v[154:157], v[214:217], v[100:103]
	v_mfma_f32_16x16x32_bf16 v[96:99], v[162:165], v[214:217], v[96:99]
	v_mfma_f32_16x16x32_bf16 v[92:95], v[166:169], v[182:185], v[92:95]
	v_mfma_f32_16x16x32_bf16 v[88:91], v[174:177], v[182:185], v[88:91]
	v_mfma_f32_16x16x32_bf16 v[84:87], v[166:169], v[194:197], v[84:87]
	v_mfma_f32_16x16x32_bf16 v[80:83], v[174:177], v[194:197], v[80:83]
	v_mfma_f32_16x16x32_bf16 v[76:79], v[166:169], v[202:205], v[76:79]
	v_mfma_f32_16x16x32_bf16 v[72:75], v[174:177], v[202:205], v[72:75]
	v_mfma_f32_16x16x32_bf16 v[68:71], v[166:169], v[210:213], v[68:71]
	v_mfma_f32_16x16x32_bf16 v[64:67], v[174:177], v[210:213], v[64:67]
	v_mfma_f32_16x16x32_bf16 v[92:95], v[170:173], v[190:193], v[92:95]
	v_mfma_f32_16x16x32_bf16 v[88:91], v[178:181], v[190:193], v[88:91]
	v_mfma_f32_16x16x32_bf16 v[84:87], v[170:173], v[198:201], v[84:87]
	v_mfma_f32_16x16x32_bf16 v[80:83], v[178:181], v[198:201], v[80:83]
	v_mfma_f32_16x16x32_bf16 v[76:79], v[170:173], v[206:209], v[76:79]
	v_mfma_f32_16x16x32_bf16 v[72:75], v[178:181], v[206:209], v[72:75]
	v_mfma_f32_16x16x32_bf16 v[68:71], v[170:173], v[214:217], v[68:71]
	v_mfma_f32_16x16x32_bf16 v[64:67], v[178:181], v[214:217], v[64:67]
	s_setprio 0
	s_barrier
; #define PG8_STAGE(bufoff, gbase, voff) do { _Pragma("unroll") for (int _i = 0; _i < 2; ++_i) \
;         __builtin_amdgcn_global_load_lds((const unsigned*)((const char*)(gbase) + (voff)[_i]), (PG8_LAS unsigned*)(lds + (bufoff) + ldsw + _i * 8192), 16, 0, 0); } while (0)
; #define PG8_LDA(dst, b, h) do { _Pragma("unroll") for (int m = 0; m < 4; ++m) _Pragma("unroll") for (int k = 0; k < 2; ++k) dst[m][k] = *(const PG8_LAS bf16x8*)(lds + PG8_SA(b, h) + aoff + m * 2048 + k * 1024); } while (0)
; #define PG8_MMA(ai, bj, At, Bt) do { __builtin_amdgcn_s_setprio(1); _Pragma("unroll") for (int m = 0; m < 4; ++m) _Pragma("unroll") for (int n = 0; n < 2; ++n) _Pragma("unroll") for (int k = 0; k < 2; ++k) \
;         acc[ai][bj][m][n] = __builtin_amdgcn_mfma_f32_16x16x32_bf16(Bt[n][k], At[m][k], acc[ai][bj][m][n], 0, 0, 0); __builtin_amdgcn_s_setprio(0); } while (0)
; #define PG8_WAIT_V(n) asm volatile("s_waitcnt vmcnt(" #n ")" ::: "memory")
; #define PG8_WAIT_L(n) asm volatile("s_waitcnt lgkmcnt(" #n ")" ::: "memory")
; #define PG8_BAR __builtin_amdgcn_s_barrier()
; #define PG8_SCHED __builtin_amdgcn_sched_barrier(0)
; template <class Epi, class Sched, bool ALIGN_EPI = false, bool SP2 = false>
; __device__ __forceinline__ void gemm_phase(PG8_LAS unsigned char* lds, const Gemm g, const Sched& S, const Epi& E) {
;     ...
;         for (int t = 0; t < nt; t += 2) {
;             const bool last = (t == nt - 2);
;     ...
;             PG8_LDA(At, 1, 1); PG8_STAGE(PG8_SB(1, 0), b3, voffB); PG8_STAGE(PG8_SB(1, 1), b3 + hstep, voffB); PG8_STAGE(PG8_SA(1, 0), a3, voffA);
;             PG8_WAIT_V(8); PG8_WAIT_L(0); PG8_BAR; PG8_MMA(1, 0, At, B0); PG8_MMA(1, 1, At, B1); PG8_BAR; PG8_SCHED;
	s_add_i32 s56, s83, s60
	v_lshl_add_u64 v[218:219], v[218:219], 0, s[14:15]
	s_mov_b32 m0, s56
	ds_read_b128 v[182:185], v187 offset:49152
	ds_read_b128 v[190:193], v187 offset:50176
	ds_read_b128 v[194:197], v187 offset:51200
	ds_read_b128 v[198:201], v187 offset:52224
	ds_read_b128 v[202:205], v187 offset:53248
	ds_read_b128 v[206:209], v187 offset:54272
	ds_read_b128 v[210:213], v187 offset:55296
	ds_read_b128 v[214:217], v187 offset:56320
	global_load_lds_dwordx4 v[218:219], off
	s_add_i32 m0, s56, 0x2000
	s_add_u32 s54, s54, 0x80080
	v_lshl_add_u64 v[218:219], v[220:221], 0, s[14:15]
	s_addc_u32 s55, s55, 0
	s_add_i32 s56, s86, s60
	global_load_lds_dwordx4 v[218:219], off
	s_mov_b32 m0, s56
	s_nop 0
	global_load_lds_dwordx4 v130, s[54:55]
	s_add_i32 m0, s56, 0x2000
	s_nop 0
	global_load_lds_dwordx4 v134, s[54:55]
	v_lshl_add_u64 v[218:219], v[222:223], 0, s[14:15]
	s_mov_b32 m0, s65
	s_nop 0
	global_load_lds_dwordx4 v[218:219], off
	v_lshl_add_u64 v[218:219], v[224:225], 0, s[14:15]
	s_mov_b32 m0, s66
	s_nop 0
	global_load_lds_dwordx4 v[218:219], off
	s_waitcnt vmcnt(8)
	s_waitcnt lgkmcnt(0)
	s_barrier
	s_setprio 1
	s_waitcnt lgkmcnt(0)
	v_mfma_f32_16x16x32_bf16 v[60:63], v[150:153], v[182:185], v[60:63]
	v_mfma_f32_16x16x32_bf16 v[56:59], v[158:161], v[182:185], v[56:59]
	v_mfma_f32_16x16x32_bf16 v[52:55], v[150:153], v[194:197], v[52:55]
	v_mfma_f32_16x16x32_bf16 v[48:51], v[158:161], v[194:197], v[48:51]
	v_mfma_f32_16x16x32_bf16 v[44:47], v[150:153], v[202:205], v[44:47]
	v_mfma_f32_16x16x32_bf16 v[40:43], v[158:161], v[202:205], v[40:43]
	v_mfma_f32_16x16x32_bf16 v[36:39], v[150:153], v[210:213], v[36:39]
	v_mfma_f32_16x16x32_bf16 v[32:35], v[158:161], v[210:213], v[32:35]
	v_mfma_f32_16x16x32_bf16 v[60:63], v[154:157], v[190:193], v[60:63]
	v_mfma_f32_16x16x32_bf16 v[56:59], v[162:165], v[190:193], v[56:59]
	v_mfma_f32_16x16x32_bf16 v[52:55], v[154:157], v[198:201], v[52:55]
	v_mfma_f32_16x16x32_bf16 v[48:51], v[162:165], v[198:201], v[48:51]
	v_mfma_f32_16x16x32_bf16 v[44:47], v[154:157], v[206:209], v[44:47]
	v_mfma_f32_16x16x32_bf16 v[40:43], v[162:165], v[206:209], v[40:43]
	v_mfma_f32_16x16x32_bf16 v[36:39], v[154:157], v[214:217], v[36:39]
	v_mfma_f32_16x16x32_bf16 v[32:35], v[162:165], v[214:217], v[32:35]
	v_mfma_f32_16x16x32_bf16 v[28:31], v[166:169], v[182:185], v[28:31]
	v_mfma_f32_16x16x32_bf16 v[24:27], v[174:177], v[182:185], v[24:27]
	v_mfma_f32_16x16x32_bf16 v[20:23], v[166:169], v[194:197], v[20:23]
	v_mfma_f32_16x16x32_bf16 v[16:19], v[174:177], v[194:197], v[16:19]
	v_mfma_f32_16x16x32_bf16 v[12:15], v[166:169], v[202:205], v[12:15]
	v_mfma_f32_16x16x32_bf16 v[8:11], v[174:177], v[202:205], v[8:11]
	v_mfma_f32_16x16x32_bf16 v[4:7], v[166:169], v[210:213], v[4:7]
	v_mfma_f32_16x16x32_bf16 v[0:3], v[174:177], v[210:213], v[0:3]
	v_mfma_f32_16x16x32_bf16 v[28:31], v[170:173], v[190:193], v[28:31]
	v_mfma_f32_16x16x32_bf16 v[24:27], v[178:181], v[190:193], v[24:27]
	v_mfma_f32_16x16x32_bf16 v[20:23], v[170:173], v[198:201], v[20:23]
	v_mfma_f32_16x16x32_bf16 v[16:19], v[178:181], v[198:201], v[16:19]
	v_mfma_f32_16x16x32_bf16 v[12:15], v[170:173], v[206:209], v[12:15]
	v_mfma_f32_16x16x32_bf16 v[8:11], v[178:181], v[206:209], v[8:11]
	v_mfma_f32_16x16x32_bf16 v[4:7], v[170:173], v[214:217], v[4:7]
	v_mfma_f32_16x16x32_bf16 v[0:3], v[178:181], v[214:217], v[0:3]
	s_setprio 0
	s_barrier
	s_add_i32 s82, s82, 2
	s_add_u32 s46, s46, 0x100
	s_addc_u32 s47, s47, 0
	s_add_u32 s80, s80, 0x100
	s_addc_u32 s81, s81, 0
	s_cmp_gt_u32 s82, 13
	s_cbranch_scc0 .LBB0_795
	s_and_b64 vcc, exec, s[16:17]
	s_cbranch_vccz .LBB0_798
	s_barrier

; #define PG8_STAGE(bufoff, gbase, voff) do { _Pragma("unroll") for (int _i = 0; _i < 2; ++_i) \
;         __builtin_amdgcn_global_load_lds((const unsigned*)((const char*)(gbase) + (voff)[_i]), (PG8_LAS unsigned*)(lds + (bufoff) + ldsw + _i * 8192), 16, 0, 0); } while (0)
; #define PG8_LDA(dst, b, h) do { _Pragma("unroll") for (int m = 0; m < 4; ++m) _Pragma("unroll") for (int k = 0; k < 2; ++k) dst[m][k] = *(const PG8_LAS bf16x8*)(lds + PG8_SA(b, h) + aoff + m * 2048 + k * 1024); } while (0)
; #define PG8_LDB(dst, b, h) do { _Pragma("unroll") for (int n = 0; n < 2; ++n) _Pragma("unroll") for (int k = 0; k < 2; ++k) dst[n][k] = *(const PG8_LAS bf16x8*)(lds + PG8_SB(b, h) + boff + n * 2048 + k * 1024); } while (0)
; #define PG8_MMA(ai, bj, At, Bt) do { __builtin_amdgcn_s_setprio(1); _Pragma("unroll") for (int m = 0; m < 4; ++m) _Pragma("unroll") for (int n = 0; n < 2; ++n) _Pragma("unroll") for (int k = 0; k < 2; ++k) \
;         acc[ai][bj][m][n] = __builtin_amdgcn_mfma_f32_16x16x32_bf16(Bt[n][k], At[m][k], acc[ai][bj][m][n], 0, 0, 0); __builtin_amdgcn_s_setprio(0); } while (0)
; #define PG8_WAIT_V(n) asm volatile("s_waitcnt vmcnt(" #n ")" ::: "memory")
; #define PG8_WAIT_L(n) asm volatile("s_waitcnt lgkmcnt(" #n ")" ::: "memory")
; #define PG8_BAR __builtin_amdgcn_s_barrier()
; template <class Epi, class Sched, bool ALIGN_EPI = false, bool SP2 = false>
; __device__ __forceinline__ void gemm_phase(PG8_LAS unsigned char* lds, const Gemm g, const Sched& S, const Epi& E) {
;     ...
;             const char* a1 = cA + (size_t)(t + 1) * kstep;
;             const char* a2 = last ? nA : cA + (size_t)(t + 2) * kstep; const char* b2 = last ? nB : cB + (size_t)(t + 2) * kstep;
;             const char* a3 = a2 + kstep; const char* b3 = b2 + kstep;
;             if (last && has_next) S.a_ready(nxt);
;             if constexpr (SP2) {
;             PG8_LDB(B0, 0, 0); PG8_LDB(B1, 0, 1); PG8_SCHED; PG8_LDA(At, 0, 0); PG8_STAGE(PG8_SA(1, 1), a1 + hstep, voffA);
;             PG8_WAIT_V(8); PG8_WAIT_L(0); PG8_BAR; PG8_MMA(0, 0, At, B0); PG8_MMA(0, 1, At, B1); PG8_BAR; PG8_SCHED;
;             PG8_LDA(At, 0, 1); PG8_STAGE(PG8_SB(0, 0), b2, voffB); PG8_STAGE(PG8_SB(0, 1), b2 + hstep, voffB); PG8_STAGE(PG8_SA(0, 0), a2, voffA);
;             PG8_WAIT_V(8); PG8_WAIT_L(0); PG8_BAR; PG8_MMA(1, 0, At, B0); PG8_MMA(1, 1, At, B1); PG8_BAR; PG8_SCHED;
.LBB0_882:
	ds_read_b128 v[128:131], v173
	ds_read_b128 v[132:135], v173 offset:1024
	ds_read_b128 v[136:139], v173 offset:2048
	ds_read_b128 v[140:143], v173 offset:3072
	ds_read_b128 v[164:167], v174
	ds_read_b128 v[168:171], v174 offset:1024
	ds_read_b128 v[178:181], v174 offset:2048
	ds_read_b128 v[182:185], v174 offset:3072
	s_add_u32 s34, s30, 0xfffc0080
	s_addc_u32 s35, s31, -1
	s_cmp_eq_u32 s61, 12
	s_cselect_b32 s37, s23, s35
	s_cselect_b32 s36, s29, s34
	s_cselect_b32 s35, s21, s60
	s_cselect_b32 s34, s58, s59
	s_add_i32 m0, s43, 0xc000
	ds_read_b128 v[190:193], v175
	ds_read_b128 v[194:197], v175 offset:1024
	ds_read_b128 v[198:201], v175 offset:2048
	ds_read_b128 v[202:205], v175 offset:3072
	ds_read_b128 v[206:209], v175 offset:4096
	ds_read_b128 v[210:213], v175 offset:5120
	ds_read_b128 v[214:217], v175 offset:6144
	ds_read_b128 v[218:221], v175 offset:7168
	global_load_lds_dwordx4 v156, s[30:31]
	s_add_i32 m0, s43, 0xe000
	s_nop 0
	global_load_lds_dwordx4 v158, s[30:31]
	s_waitcnt vmcnt(8)
	s_waitcnt lgkmcnt(0)
	s_barrier
	s_setprio 1
	s_waitcnt lgkmcnt(0)
	v_mfma_f32_16x16x32_bf16 v[124:127], v[128:131], v[190:193], v[124:127]
	v_mfma_f32_16x16x32_bf16 v[120:123], v[136:139], v[190:193], v[120:123]
	v_mfma_f32_16x16x32_bf16 v[108:111], v[128:131], v[198:201], v[108:111]
	v_mfma_f32_16x16x32_bf16 v[104:107], v[136:139], v[198:201], v[104:107]
	v_mfma_f32_16x16x32_bf16 v[92:95], v[128:131], v[206:209], v[92:95]
	v_mfma_f32_16x16x32_bf16 v[88:91], v[136:139], v[206:209], v[88:91]
	v_mfma_f32_16x16x32_bf16 v[76:79], v[128:131], v[214:217], v[76:79]
	v_mfma_f32_16x16x32_bf16 v[72:75], v[136:139], v[214:217], v[72:75]
	v_mfma_f32_16x16x32_bf16 v[124:127], v[132:135], v[194:197], v[124:127]
	v_mfma_f32_16x16x32_bf16 v[120:123], v[140:143], v[194:197], v[120:123]
	v_mfma_f32_16x16x32_bf16 v[108:111], v[132:135], v[202:205], v[108:111]
	v_mfma_f32_16x16x32_bf16 v[104:107], v[140:143], v[202:205], v[104:107]
	v_mfma_f32_16x16x32_bf16 v[92:95], v[132:135], v[210:213], v[92:95]
	v_mfma_f32_16x16x32_bf16 v[88:91], v[140:143], v[210:213], v[88:91]
	v_mfma_f32_16x16x32_bf16 v[76:79], v[132:135], v[218:221], v[76:79]
	v_mfma_f32_16x16x32_bf16 v[72:75], v[140:143], v[218:221], v[72:75]
	v_mfma_f32_16x16x32_bf16 v[116:119], v[164:167], v[190:193], v[116:119]
	v_mfma_f32_16x16x32_bf16 v[112:115], v[178:181], v[190:193], v[112:115]
	v_mfma_f32_16x16x32_bf16 v[100:103], v[164:167], v[198:201], v[100:103]
	v_mfma_f32_16x16x32_bf16 v[96:99], v[178:181], v[198:201], v[96:99]
	v_mfma_f32_16x16x32_bf16 v[84:87], v[164:167], v[206:209], v[84:87]
	v_mfma_f32_16x16x32_bf16 v[80:83], v[178:181], v[206:209], v[80:83]
	v_mfma_f32_16x16x32_bf16 v[68:71], v[164:167], v[214:217], v[68:71]
	v_mfma_f32_16x16x32_bf16 v[64:67], v[178:181], v[214:217], v[64:67]
	v_mfma_f32_16x16x32_bf16 v[116:119], v[168:171], v[194:197], v[116:119]
	v_mfma_f32_16x16x32_bf16 v[112:115], v[182:185], v[194:197], v[112:115]
	v_mfma_f32_16x16x32_bf16 v[100:103], v[168:171], v[202:205], v[100:103]
	v_mfma_f32_16x16x32_bf16 v[96:99], v[182:185], v[202:205], v[96:99]
	v_mfma_f32_16x16x32_bf16 v[84:87], v[168:171], v[210:213], v[84:87]
	v_mfma_f32_16x16x32_bf16 v[80:83], v[182:185], v[210:213], v[80:83]
	v_mfma_f32_16x16x32_bf16 v[68:71], v[168:171], v[218:221], v[68:71]
	v_mfma_f32_16x16x32_bf16 v[64:67], v[182:185], v[218:221], v[64:67]
	s_setprio 0
	s_barrier
	s_add_i32 s62, s55, s42
	v_lshl_add_u64 v[186:187], s[34:35], 0, v[146:147]
	s_mov_b32 m0, s62
	ds_read_b128 v[190:193], v175 offset:16384
	ds_read_b128 v[194:197], v175 offset:17408
	ds_read_b128 v[198:201], v175 offset:18432
	ds_read_b128 v[202:205], v175 offset:19456
	ds_read_b128 v[206:209], v175 offset:20480
	ds_read_b128 v[210:213], v175 offset:21504
	ds_read_b128 v[214:217], v175 offset:22528
	ds_read_b128 v[218:221], v175 offset:23552
	global_load_lds_dwordx4 v[186:187], off
	s_add_i32 m0, s62, 0x2000
	s_add_u32 s62, s34, 0x40000
	v_lshl_add_u64 v[222:223], s[34:35], 0, v[150:151]
	s_addc_u32 s63, s35, 0
	s_add_i32 s64, s56, s42
	global_load_lds_dwordx4 v[222:223], off
	s_mov_b32 m0, s64
	v_lshl_add_u64 v[226:227], s[36:37], 0, v[148:149]
	global_load_lds_dwordx4 v146, s[62:63]
	s_add_i32 m0, s64, 0x2000
	s_nop 0
	global_load_lds_dwordx4 v150, s[62:63]
	v_lshl_add_u64 v[224:225], s[36:37], 0, v[144:145]
	s_mov_b32 m0, s43
	s_nop 0
	global_load_lds_dwordx4 v[224:225], off
	s_mov_b32 m0, s44
	s_nop 0
	global_load_lds_dwordx4 v[226:227], off
	s_waitcnt vmcnt(8)
	s_waitcnt lgkmcnt(0)
	s_barrier
	s_setprio 1
	s_waitcnt lgkmcnt(0)
	v_mfma_f32_16x16x32_bf16 v[60:63], v[128:131], v[190:193], v[60:63]
	v_mfma_f32_16x16x32_bf16 v[56:59], v[136:139], v[190:193], v[56:59]
	v_mfma_f32_16x16x32_bf16 v[44:47], v[128:131], v[198:201], v[44:47]
	v_mfma_f32_16x16x32_bf16 v[40:43], v[136:139], v[198:201], v[40:43]
	v_mfma_f32_16x16x32_bf16 v[28:31], v[128:131], v[206:209], v[28:31]
	v_mfma_f32_16x16x32_bf16 v[24:27], v[136:139], v[206:209], v[24:27]
	v_mfma_f32_16x16x32_bf16 v[12:15], v[128:131], v[214:217], v[12:15]
	v_mfma_f32_16x16x32_bf16 v[8:11], v[136:139], v[214:217], v[8:11]
	v_mfma_f32_16x16x32_bf16 v[60:63], v[132:135], v[194:197], v[60:63]
	v_mfma_f32_16x16x32_bf16 v[56:59], v[140:143], v[194:197], v[56:59]
	v_mfma_f32_16x16x32_bf16 v[44:47], v[132:135], v[202:205], v[44:47]
	v_mfma_f32_16x16x32_bf16 v[40:43], v[140:143], v[202:205], v[40:43]
	v_mfma_f32_16x16x32_bf16 v[28:31], v[132:135], v[210:213], v[28:31]
	v_mfma_f32_16x16x32_bf16 v[24:27], v[140:143], v[210:213], v[24:27]
	v_mfma_f32_16x16x32_bf16 v[12:15], v[132:135], v[218:221], v[12:15]
	v_mfma_f32_16x16x32_bf16 v[8:11], v[140:143], v[218:221], v[8:11]
	v_mfma_f32_16x16x32_bf16 v[52:55], v[164:167], v[190:193], v[52:55]
	v_mfma_f32_16x16x32_bf16 v[48:51], v[178:181], v[190:193], v[48:51]
	v_mfma_f32_16x16x32_bf16 v[36:39], v[164:167], v[198:201], v[36:39]
	v_mfma_f32_16x16x32_bf16 v[32:35], v[178:181], v[198:201], v[32:35]
	v_mfma_f32_16x16x32_bf16 v[20:23], v[164:167], v[206:209], v[20:23]
	v_mfma_f32_16x16x32_bf16 v[16:19], v[178:181], v[206:209], v[16:19]
	v_mfma_f32_16x16x32_bf16 v[4:7], v[164:167], v[214:217], v[4:7]
	v_mfma_f32_16x16x32_bf16 v[0:3], v[178:181], v[214:217], v[0:3]
	v_mfma_f32_16x16x32_bf16 v[52:55], v[168:171], v[194:197], v[52:55]
	v_mfma_f32_16x16x32_bf16 v[48:51], v[182:185], v[194:197], v[48:51]
	v_mfma_f32_16x16x32_bf16 v[36:39], v[168:171], v[202:205], v[36:39]
	v_mfma_f32_16x16x32_bf16 v[32:35], v[182:185], v[202:205], v[32:35]
	v_mfma_f32_16x16x32_bf16 v[20:23], v[168:171], v[210:213], v[20:23]
	v_mfma_f32_16x16x32_bf16 v[16:19], v[182:185], v[210:213], v[16:19]
	v_mfma_f32_16x16x32_bf16 v[4:7], v[168:171], v[218:221], v[4:7]
	v_mfma_f32_16x16x32_bf16 v[0:3], v[182:185], v[218:221], v[0:3]
	s_setprio 0
	s_barrier
; #define PG8_STAGE(bufoff, gbase, voff) do { _Pragma("unroll") for (int _i = 0; _i < 2; ++_i) \
;         __builtin_amdgcn_global_load_lds((const unsigned*)((const char*)(gbase) + (voff)[_i]), (PG8_LAS unsigned*)(lds + (bufoff) + ldsw + _i * 8192), 16, 0, 0); } while (0)
; #define PG8_LDA(dst, b, h) do { _Pragma("unroll") for (int m = 0; m < 4; ++m) _Pragma("unroll") for (int k = 0; k < 2; ++k) dst[m][k] = *(const PG8_LAS bf16x8*)(lds + PG8_SA(b, h) + aoff + m * 2048 + k * 1024); } while (0)
; #define PG8_LDB(dst, b, h) do { _Pragma("unroll") for (int n = 0; n < 2; ++n) _Pragma("unroll") for (int k = 0; k < 2; ++k) dst[n][k] = *(const PG8_LAS bf16x8*)(lds + PG8_SB(b, h) + boff + n * 2048 + k * 1024); } while (0)
; #define PG8_MMA(ai, bj, At, Bt) do { __builtin_amdgcn_s_setprio(1); _Pragma("unroll") for (int m = 0; m < 4; ++m) _Pragma("unroll") for (int n = 0; n < 2; ++n) _Pragma("unroll") for (int k = 0; k < 2; ++k) \
;         acc[ai][bj][m][n] = __builtin_amdgcn_mfma_f32_16x16x32_bf16(Bt[n][k], At[m][k], acc[ai][bj][m][n], 0, 0, 0); __builtin_amdgcn_s_setprio(0); } while (0)
; #define PG8_WAIT_V(n) asm volatile("s_waitcnt vmcnt(" #n ")" ::: "memory")
; #define PG8_WAIT_L(n) asm volatile("s_waitcnt lgkmcnt(" #n ")" ::: "memory")
; #define PG8_BAR __builtin_amdgcn_s_barrier()
; #define PG8_SCHED __builtin_amdgcn_sched_barrier(0)
; template <class Epi, class Sched, bool ALIGN_EPI = false, bool SP2 = false>
; __device__ __forceinline__ void gemm_phase(PG8_LAS unsigned char* lds, const Gemm g, const Sched& S, const Epi& E) {
;     ...
;         for (int t = 0; t < nt; t += 2) {
;             const bool last = (t == nt - 2);
;     ...
;             PG8_LDB(B0, 1, 0); PG8_LDB(B1, 1, 1); PG8_SCHED; PG8_LDA(At, 1, 0); PG8_STAGE(PG8_SA(0, 1), a2 + hstep, voffA);
;             PG8_WAIT_V(8); PG8_WAIT_L(0); PG8_BAR; PG8_MMA(0, 0, At, B0); PG8_MMA(0, 1, At, B1); PG8_BAR; PG8_SCHED;
;             PG8_LDA(At, 1, 1); PG8_STAGE(PG8_SB(1, 0), b3, voffB); PG8_STAGE(PG8_SB(1, 1), b3 + hstep, voffB); PG8_STAGE(PG8_SA(1, 0), a3, voffA);
;             PG8_WAIT_V(8); PG8_WAIT_L(0); PG8_BAR; PG8_MMA(1, 0, At, B0); PG8_MMA(1, 1, At, B1); PG8_BAR; PG8_SCHED;
	s_add_i32 s62, 0, 0x18000
	s_add_i32 s63, 0, 0x1c000
	v_add_u32_e32 v140, s62, v172
	v_add_u32_e32 v177, s63, v172
	ds_read_b128 v[128:131], v140
	ds_read_b128 v[132:135], v140 offset:1024
	ds_read_b128 v[136:139], v140 offset:2048
	ds_read_b128 v[140:143], v140 offset:3072
	ds_read_b128 v[164:167], v177
	ds_read_b128 v[168:171], v177 offset:1024
	ds_read_b128 v[178:181], v177 offset:2048
	ds_read_b128 v[182:185], v177 offset:3072
	s_add_u32 s36, s36, 0x40000
	s_addc_u32 s37, s37, 0
	s_mov_b32 m0, s45
	ds_read_b128 v[190:193], v175 offset:32768
	ds_read_b128 v[194:197], v175 offset:33792
	ds_read_b128 v[198:201], v175 offset:34816
	ds_read_b128 v[202:205], v175 offset:35840
	ds_read_b128 v[206:209], v175 offset:36864
	ds_read_b128 v[210:213], v175 offset:37888
	ds_read_b128 v[214:217], v175 offset:38912
	ds_read_b128 v[218:221], v175 offset:39936
	global_load_lds_dwordx4 v144, s[36:37]
	s_mov_b32 m0, s46
	s_nop 0
	global_load_lds_dwordx4 v148, s[36:37]
	s_waitcnt vmcnt(8)
	s_waitcnt lgkmcnt(0)
	s_barrier
	s_setprio 1
	s_waitcnt lgkmcnt(0)
	v_mfma_f32_16x16x32_bf16 v[124:127], v[128:131], v[190:193], v[124:127]
	v_mfma_f32_16x16x32_bf16 v[120:123], v[136:139], v[190:193], v[120:123]
	v_mfma_f32_16x16x32_bf16 v[108:111], v[128:131], v[198:201], v[108:111]
	v_mfma_f32_16x16x32_bf16 v[104:107], v[136:139], v[198:201], v[104:107]
	v_mfma_f32_16x16x32_bf16 v[92:95], v[128:131], v[206:209], v[92:95]
	v_mfma_f32_16x16x32_bf16 v[88:91], v[136:139], v[206:209], v[88:91]
	v_mfma_f32_16x16x32_bf16 v[76:79], v[128:131], v[214:217], v[76:79]
	v_mfma_f32_16x16x32_bf16 v[72:75], v[136:139], v[214:217], v[72:75]
	v_mfma_f32_16x16x32_bf16 v[124:127], v[132:135], v[194:197], v[124:127]
	v_mfma_f32_16x16x32_bf16 v[120:123], v[140:143], v[194:197], v[120:123]
	v_mfma_f32_16x16x32_bf16 v[108:111], v[132:135], v[202:205], v[108:111]
	v_mfma_f32_16x16x32_bf16 v[104:107], v[140:143], v[202:205], v[104:107]
	v_mfma_f32_16x16x32_bf16 v[92:95], v[132:135], v[210:213], v[92:95]
	v_mfma_f32_16x16x32_bf16 v[88:91], v[140:143], v[210:213], v[88:91]
	v_mfma_f32_16x16x32_bf16 v[76:79], v[132:135], v[218:221], v[76:79]
	v_mfma_f32_16x16x32_bf16 v[72:75], v[140:143], v[218:221], v[72:75]
	v_mfma_f32_16x16x32_bf16 v[116:119], v[164:167], v[190:193], v[116:119]
	v_mfma_f32_16x16x32_bf16 v[112:115], v[178:181], v[190:193], v[112:115]
	v_mfma_f32_16x16x32_bf16 v[100:103], v[164:167], v[198:201], v[100:103]
	v_mfma_f32_16x16x32_bf16 v[96:99], v[178:181], v[198:201], v[96:99]
	v_mfma_f32_16x16x32_bf16 v[84:87], v[164:167], v[206:209], v[84:87]
	v_mfma_f32_16x16x32_bf16 v[80:83], v[178:181], v[206:209], v[80:83]
	v_mfma_f32_16x16x32_bf16 v[68:71], v[164:167], v[214:217], v[68:71]
	v_mfma_f32_16x16x32_bf16 v[64:67], v[178:181], v[214:217], v[64:67]
	v_mfma_f32_16x16x32_bf16 v[116:119], v[168:171], v[194:197], v[116:119]
	v_mfma_f32_16x16x32_bf16 v[112:115], v[182:185], v[194:197], v[112:115]
	v_mfma_f32_16x16x32_bf16 v[100:103], v[168:171], v[202:205], v[100:103]
	v_mfma_f32_16x16x32_bf16 v[96:99], v[182:185], v[202:205], v[96:99]
	v_mfma_f32_16x16x32_bf16 v[84:87], v[168:171], v[210:213], v[84:87]
	v_mfma_f32_16x16x32_bf16 v[80:83], v[182:185], v[210:213], v[80:83]
	v_mfma_f32_16x16x32_bf16 v[68:71], v[168:171], v[218:221], v[68:71]
	v_mfma_f32_16x16x32_bf16 v[64:67], v[182:185], v[218:221], v[64:67]
	s_setprio 0
	s_barrier
	s_add_i32 s36, s62, s42
	v_lshl_add_u64 v[186:187], v[186:187], 0, s[16:17]
	s_mov_b32 m0, s36
	ds_read_b128 v[190:193], v175 offset:49152
	ds_read_b128 v[194:197], v175 offset:50176
	ds_read_b128 v[198:201], v175 offset:51200
	ds_read_b128 v[202:205], v175 offset:52224
	ds_read_b128 v[206:209], v175 offset:53248
	ds_read_b128 v[210:213], v175 offset:54272
	ds_read_b128 v[214:217], v175 offset:55296
	ds_read_b128 v[218:221], v175 offset:56320
	global_load_lds_dwordx4 v[186:187], off
	s_add_i32 m0, s36, 0x2000
	s_add_u32 s34, s34, 0x40080
	v_lshl_add_u64 v[186:187], v[222:223], 0, s[16:17]
	s_addc_u32 s35, s35, 0
	s_add_i32 s36, s63, s42
	global_load_lds_dwordx4 v[186:187], off
	s_mov_b32 m0, s36
	s_nop 0
	global_load_lds_dwordx4 v146, s[34:35]
	s_add_i32 m0, s36, 0x2000
	s_nop 0
	global_load_lds_dwordx4 v150, s[34:35]
	v_lshl_add_u64 v[186:187], v[224:225], 0, s[16:17]
	s_mov_b32 m0, s48
	s_nop 0
	global_load_lds_dwordx4 v[186:187], off
	v_lshl_add_u64 v[186:187], v[226:227], 0, s[16:17]
	s_mov_b32 m0, s49
	s_nop 0
	global_load_lds_dwordx4 v[186:187], off
	s_waitcnt vmcnt(8)
	s_waitcnt lgkmcnt(0)
	s_barrier
	s_setprio 1
	s_waitcnt lgkmcnt(0)
	v_mfma_f32_16x16x32_bf16 v[60:63], v[128:131], v[190:193], v[60:63]
	v_mfma_f32_16x16x32_bf16 v[56:59], v[136:139], v[190:193], v[56:59]
	v_mfma_f32_16x16x32_bf16 v[44:47], v[128:131], v[198:201], v[44:47]
	v_mfma_f32_16x16x32_bf16 v[40:43], v[136:139], v[198:201], v[40:43]
	v_mfma_f32_16x16x32_bf16 v[28:31], v[128:131], v[206:209], v[28:31]
	v_mfma_f32_16x16x32_bf16 v[24:27], v[136:139], v[206:209], v[24:27]
	v_mfma_f32_16x16x32_bf16 v[12:15], v[128:131], v[214:217], v[12:15]
	v_mfma_f32_16x16x32_bf16 v[8:11], v[136:139], v[214:217], v[8:11]
	v_mfma_f32_16x16x32_bf16 v[60:63], v[132:135], v[194:197], v[60:63]
	v_mfma_f32_16x16x32_bf16 v[56:59], v[140:143], v[194:197], v[56:59]
	v_mfma_f32_16x16x32_bf16 v[44:47], v[132:135], v[202:205], v[44:47]
	v_mfma_f32_16x16x32_bf16 v[40:43], v[140:143], v[202:205], v[40:43]
	v_mfma_f32_16x16x32_bf16 v[28:31], v[132:135], v[210:213], v[28:31]
	v_mfma_f32_16x16x32_bf16 v[24:27], v[140:143], v[210:213], v[24:27]
	v_mfma_f32_16x16x32_bf16 v[12:15], v[132:135], v[218:221], v[12:15]
	v_mfma_f32_16x16x32_bf16 v[8:11], v[140:143], v[218:221], v[8:11]
	v_mfma_f32_16x16x32_bf16 v[52:55], v[164:167], v[190:193], v[52:55]
	v_mfma_f32_16x16x32_bf16 v[48:51], v[178:181], v[190:193], v[48:51]
	v_mfma_f32_16x16x32_bf16 v[36:39], v[164:167], v[198:201], v[36:39]
	v_mfma_f32_16x16x32_bf16 v[32:35], v[178:181], v[198:201], v[32:35]
	v_mfma_f32_16x16x32_bf16 v[20:23], v[164:167], v[206:209], v[20:23]
	v_mfma_f32_16x16x32_bf16 v[16:19], v[178:181], v[206:209], v[16:19]
	v_mfma_f32_16x16x32_bf16 v[4:7], v[164:167], v[214:217], v[4:7]
	v_mfma_f32_16x16x32_bf16 v[0:3], v[178:181], v[214:217], v[0:3]
	v_mfma_f32_16x16x32_bf16 v[52:55], v[168:171], v[194:197], v[52:55]
	v_mfma_f32_16x16x32_bf16 v[48:51], v[182:185], v[194:197], v[48:51]
	v_mfma_f32_16x16x32_bf16 v[36:39], v[168:171], v[202:205], v[36:39]
	v_mfma_f32_16x16x32_bf16 v[32:35], v[182:185], v[202:205], v[32:35]
	v_mfma_f32_16x16x32_bf16 v[20:23], v[168:171], v[210:213], v[20:23]
	v_mfma_f32_16x16x32_bf16 v[16:19], v[182:185], v[210:213], v[16:19]
	v_mfma_f32_16x16x32_bf16 v[4:7], v[168:171], v[218:221], v[4:7]
	v_mfma_f32_16x16x32_bf16 v[0:3], v[182:185], v[218:221], v[0:3]
	s_setprio 0
	s_barrier
	s_add_i32 s61, s61, 2
	s_add_u32 s30, s30, 0x100
	s_addc_u32 s31, s31, 0
	s_add_u32 s59, s59, 0x100
	s_addc_u32 s60, s60, 0
	s_cmp_gt_u32 s61, 13
	s_cbranch_scc0 .LBB0_882
	s_and_b64 vcc, exec, s[18:19]
	s_cbranch_vccz .LBB0_885
	s_barrier

; #define PG8_STAGE(bufoff, gbase, voff) do { _Pragma("unroll") for (int _i = 0; _i < 2; ++_i) \
;         __builtin_amdgcn_global_load_lds((const unsigned*)((const char*)(gbase) + (voff)[_i]), (PG8_LAS unsigned*)(lds + (bufoff) + ldsw + _i * 8192), 16, 0, 0); } while (0)
; #define PG8_LDA(dst, b, h) do { _Pragma("unroll") for (int m = 0; m < 4; ++m) _Pragma("unroll") for (int k = 0; k < 2; ++k) dst[m][k] = *(const PG8_LAS bf16x8*)(lds + PG8_SA(b, h) + aoff + m * 2048 + k * 1024); } while (0)
; #define PG8_LDB(dst, b, h) do { _Pragma("unroll") for (int n = 0; n < 2; ++n) _Pragma("unroll") for (int k = 0; k < 2; ++k) dst[n][k] = *(const PG8_LAS bf16x8*)(lds + PG8_SB(b, h) + boff + n * 2048 + k * 1024); } while (0)
; #define PG8_MMA(ai, bj, At, Bt) do { __builtin_amdgcn_s_setprio(1); _Pragma("unroll") for (int m = 0; m < 4; ++m) _Pragma("unroll") for (int n = 0; n < 2; ++n) _Pragma("unroll") for (int k = 0; k < 2; ++k) \
;         acc[ai][bj][m][n] = __builtin_amdgcn_mfma_f32_16x16x32_bf16(Bt[n][k], At[m][k], acc[ai][bj][m][n], 0, 0, 0); __builtin_amdgcn_s_setprio(0); } while (0)
; #define PG8_WAIT_V(n) asm volatile("s_waitcnt vmcnt(" #n ")" ::: "memory")
; #define PG8_WAIT_L(n) asm volatile("s_waitcnt lgkmcnt(" #n ")" ::: "memory")
; #define PG8_BAR __builtin_amdgcn_s_barrier()
; template <class Epi, class Sched, bool ALIGN_EPI = false, bool SP2 = false>
; __device__ __forceinline__ void gemm_phase(PG8_LAS unsigned char* lds, const Gemm g, const Sched& S, const Epi& E) {
;     ...
;             const char* a1 = cA + (size_t)(t + 1) * kstep;
;             const char* a2 = last ? nA : cA + (size_t)(t + 2) * kstep; const char* b2 = last ? nB : cB + (size_t)(t + 2) * kstep;
;             const char* a3 = a2 + kstep; const char* b3 = b2 + kstep;
;             if (last && has_next) S.a_ready(nxt);
;             if constexpr (SP2) {
;             PG8_LDB(B0, 0, 0); PG8_LDB(B1, 0, 1); PG8_SCHED; PG8_LDA(At, 0, 0); PG8_STAGE(PG8_SA(1, 1), a1 + hstep, voffA);
;             PG8_WAIT_V(8); PG8_WAIT_L(0); PG8_BAR; PG8_MMA(0, 0, At, B0); PG8_MMA(0, 1, At, B1); PG8_BAR; PG8_SCHED;
;             PG8_LDA(At, 0, 1); PG8_STAGE(PG8_SB(0, 0), b2, voffB); PG8_STAGE(PG8_SB(0, 1), b2 + hstep, voffB); PG8_STAGE(PG8_SA(0, 0), a2, voffA);
;             PG8_WAIT_V(8); PG8_WAIT_L(0); PG8_BAR; PG8_MMA(1, 0, At, B0); PG8_MMA(1, 1, At, B1); PG8_BAR; PG8_SCHED;
.LBB0_969:
	ds_read_b128 v[128:131], v191
	ds_read_b128 v[132:135], v191 offset:1024
	ds_read_b128 v[136:139], v191 offset:2048
	ds_read_b128 v[140:143], v191 offset:3072
	ds_read_b128 v[144:147], v192
	ds_read_b128 v[148:151], v192 offset:1024
	ds_read_b128 v[172:175], v192 offset:2048
	ds_read_b128 v[176:179], v192 offset:3072
	s_add_u32 s26, s24, 0xfffc0080
	s_addc_u32 s27, s25, -1
	s_cmp_eq_u32 s57, 12
	s_cselect_b32 s29, s17, s27
	s_cselect_b32 s28, s51, s26
	s_cselect_b32 s27, s15, s56
	s_cselect_b32 s26, s54, s55
	s_add_i32 m0, s39, 0xc000
	ds_read_b128 v[180:183], v193
	ds_read_b128 v[184:187], v193 offset:1024
	ds_read_b128 v[196:199], v193 offset:2048
	ds_read_b128 v[200:203], v193 offset:3072
	ds_read_b128 v[204:207], v193 offset:4096
	ds_read_b128 v[208:211], v193 offset:5120
	ds_read_b128 v[212:215], v193 offset:6144
	ds_read_b128 v[216:219], v193 offset:7168
	global_load_lds_dwordx4 v164, s[24:25]
	s_add_i32 m0, s39, 0xe000
	s_nop 0
	global_load_lds_dwordx4 v166, s[24:25]
	s_waitcnt vmcnt(8)
	s_waitcnt lgkmcnt(0)
	s_barrier
	s_setprio 1
	s_waitcnt lgkmcnt(0)
	v_mfma_f32_16x16x32_bf16 v[124:127], v[128:131], v[180:183], v[124:127]
	v_mfma_f32_16x16x32_bf16 v[120:123], v[136:139], v[180:183], v[120:123]
	v_mfma_f32_16x16x32_bf16 v[108:111], v[128:131], v[196:199], v[108:111]
	v_mfma_f32_16x16x32_bf16 v[104:107], v[136:139], v[196:199], v[104:107]
	v_mfma_f32_16x16x32_bf16 v[92:95], v[128:131], v[204:207], v[92:95]
	v_mfma_f32_16x16x32_bf16 v[84:87], v[136:139], v[204:207], v[84:87]
	v_mfma_f32_16x16x32_bf16 v[76:79], v[128:131], v[212:215], v[76:79]
	v_mfma_f32_16x16x32_bf16 v[72:75], v[136:139], v[212:215], v[72:75]
	v_mfma_f32_16x16x32_bf16 v[124:127], v[132:135], v[184:187], v[124:127]
	v_mfma_f32_16x16x32_bf16 v[120:123], v[140:143], v[184:187], v[120:123]
	v_mfma_f32_16x16x32_bf16 v[108:111], v[132:135], v[200:203], v[108:111]
	v_mfma_f32_16x16x32_bf16 v[104:107], v[140:143], v[200:203], v[104:107]
	v_mfma_f32_16x16x32_bf16 v[92:95], v[132:135], v[208:211], v[92:95]
	v_mfma_f32_16x16x32_bf16 v[84:87], v[140:143], v[208:211], v[84:87]
	v_mfma_f32_16x16x32_bf16 v[76:79], v[132:135], v[216:219], v[76:79]
	v_mfma_f32_16x16x32_bf16 v[72:75], v[140:143], v[216:219], v[72:75]
	v_mfma_f32_16x16x32_bf16 v[116:119], v[144:147], v[180:183], v[116:119]
	v_mfma_f32_16x16x32_bf16 v[112:115], v[172:175], v[180:183], v[112:115]
	v_mfma_f32_16x16x32_bf16 v[100:103], v[144:147], v[196:199], v[100:103]
	v_mfma_f32_16x16x32_bf16 v[96:99], v[172:175], v[196:199], v[96:99]
	v_mfma_f32_16x16x32_bf16 v[88:91], v[144:147], v[204:207], v[88:91]
	v_mfma_f32_16x16x32_bf16 v[80:83], v[172:175], v[204:207], v[80:83]
	v_mfma_f32_16x16x32_bf16 v[68:71], v[144:147], v[212:215], v[68:71]
	v_mfma_f32_16x16x32_bf16 v[64:67], v[172:175], v[212:215], v[64:67]
	v_mfma_f32_16x16x32_bf16 v[116:119], v[148:151], v[184:187], v[116:119]
	v_mfma_f32_16x16x32_bf16 v[112:115], v[176:179], v[184:187], v[112:115]
	v_mfma_f32_16x16x32_bf16 v[100:103], v[148:151], v[200:203], v[100:103]
	v_mfma_f32_16x16x32_bf16 v[96:99], v[176:179], v[200:203], v[96:99]
	v_mfma_f32_16x16x32_bf16 v[88:91], v[148:151], v[208:211], v[88:91]
	v_mfma_f32_16x16x32_bf16 v[80:83], v[176:179], v[208:211], v[80:83]
	v_mfma_f32_16x16x32_bf16 v[68:71], v[148:151], v[216:219], v[68:71]
	v_mfma_f32_16x16x32_bf16 v[64:67], v[176:179], v[216:219], v[64:67]
	s_setprio 0
	s_barrier
	s_add_i32 s58, s47, s36
	v_lshl_add_u64 v[220:221], s[26:27], 0, v[156:157]
	s_mov_b32 m0, s58
	ds_read_b128 v[180:183], v193 offset:16384
	ds_read_b128 v[184:187], v193 offset:17408
	ds_read_b128 v[196:199], v193 offset:18432
	ds_read_b128 v[200:203], v193 offset:19456
	ds_read_b128 v[204:207], v193 offset:20480
	ds_read_b128 v[208:211], v193 offset:21504
	ds_read_b128 v[212:215], v193 offset:22528
	ds_read_b128 v[216:219], v193 offset:23552
	global_load_lds_dwordx4 v[220:221], off
	s_add_i32 m0, s58, 0x2000
	s_add_u32 s58, s26, 0x40000
	v_lshl_add_u64 v[222:223], s[26:27], 0, v[152:153]
	s_addc_u32 s59, s27, 0
	s_add_i32 s60, s48, s36
	global_load_lds_dwordx4 v[222:223], off
	s_mov_b32 m0, s60
	v_lshl_add_u64 v[226:227], s[28:29], 0, v[154:155]
	global_load_lds_dwordx4 v156, s[58:59]
	s_add_i32 m0, s60, 0x2000
	s_nop 0
	global_load_lds_dwordx4 v152, s[58:59]
	v_lshl_add_u64 v[224:225], s[28:29], 0, v[158:159]
	s_mov_b32 m0, s39
	s_nop 0
	global_load_lds_dwordx4 v[224:225], off
	s_mov_b32 m0, s40
	s_nop 0
	global_load_lds_dwordx4 v[226:227], off
	s_waitcnt vmcnt(8)
	s_waitcnt lgkmcnt(0)
	s_barrier
	s_setprio 1
	s_waitcnt lgkmcnt(0)
	v_mfma_f32_16x16x32_bf16 v[60:63], v[128:131], v[180:183], v[60:63]
	v_mfma_f32_16x16x32_bf16 v[52:55], v[136:139], v[180:183], v[52:55]
	v_mfma_f32_16x16x32_bf16 v[44:47], v[128:131], v[196:199], v[44:47]
	v_mfma_f32_16x16x32_bf16 v[40:43], v[136:139], v[196:199], v[40:43]
	v_mfma_f32_16x16x32_bf16 v[28:31], v[128:131], v[204:207], v[28:31]
	v_mfma_f32_16x16x32_bf16 v[20:23], v[136:139], v[204:207], v[20:23]
	v_mfma_f32_16x16x32_bf16 v[12:15], v[128:131], v[212:215], v[12:15]
	v_mfma_f32_16x16x32_bf16 v[8:11], v[136:139], v[212:215], v[8:11]
	v_mfma_f32_16x16x32_bf16 v[60:63], v[132:135], v[184:187], v[60:63]
	v_mfma_f32_16x16x32_bf16 v[52:55], v[140:143], v[184:187], v[52:55]
	v_mfma_f32_16x16x32_bf16 v[44:47], v[132:135], v[200:203], v[44:47]
	v_mfma_f32_16x16x32_bf16 v[40:43], v[140:143], v[200:203], v[40:43]
	v_mfma_f32_16x16x32_bf16 v[28:31], v[132:135], v[208:211], v[28:31]
	v_mfma_f32_16x16x32_bf16 v[20:23], v[140:143], v[208:211], v[20:23]
	v_mfma_f32_16x16x32_bf16 v[12:15], v[132:135], v[216:219], v[12:15]
	v_mfma_f32_16x16x32_bf16 v[8:11], v[140:143], v[216:219], v[8:11]
	v_mfma_f32_16x16x32_bf16 v[56:59], v[144:147], v[180:183], v[56:59]
	v_mfma_f32_16x16x32_bf16 v[48:51], v[172:175], v[180:183], v[48:51]
	v_mfma_f32_16x16x32_bf16 v[36:39], v[144:147], v[196:199], v[36:39]
	v_mfma_f32_16x16x32_bf16 v[32:35], v[172:175], v[196:199], v[32:35]
	v_mfma_f32_16x16x32_bf16 v[24:27], v[144:147], v[204:207], v[24:27]
	v_mfma_f32_16x16x32_bf16 v[16:19], v[172:175], v[204:207], v[16:19]
	v_mfma_f32_16x16x32_bf16 v[4:7], v[144:147], v[212:215], v[4:7]
	v_mfma_f32_16x16x32_bf16 v[0:3], v[172:175], v[212:215], v[0:3]
	v_mfma_f32_16x16x32_bf16 v[56:59], v[148:151], v[184:187], v[56:59]
	v_mfma_f32_16x16x32_bf16 v[48:51], v[176:179], v[184:187], v[48:51]
	v_mfma_f32_16x16x32_bf16 v[36:39], v[148:151], v[200:203], v[36:39]
	v_mfma_f32_16x16x32_bf16 v[32:35], v[176:179], v[200:203], v[32:35]
	v_mfma_f32_16x16x32_bf16 v[24:27], v[148:151], v[208:211], v[24:27]
	v_mfma_f32_16x16x32_bf16 v[16:19], v[176:179], v[208:211], v[16:19]
	v_mfma_f32_16x16x32_bf16 v[4:7], v[148:151], v[216:219], v[4:7]
	v_mfma_f32_16x16x32_bf16 v[0:3], v[176:179], v[216:219], v[0:3]
	s_setprio 0
	s_barrier
; #define PG8_STAGE(bufoff, gbase, voff) do { _Pragma("unroll") for (int _i = 0; _i < 2; ++_i) \
;         __builtin_amdgcn_global_load_lds((const unsigned*)((const char*)(gbase) + (voff)[_i]), (PG8_LAS unsigned*)(lds + (bufoff) + ldsw + _i * 8192), 16, 0, 0); } while (0)
; #define PG8_LDA(dst, b, h) do { _Pragma("unroll") for (int m = 0; m < 4; ++m) _Pragma("unroll") for (int k = 0; k < 2; ++k) dst[m][k] = *(const PG8_LAS bf16x8*)(lds + PG8_SA(b, h) + aoff + m * 2048 + k * 1024); } while (0)
; #define PG8_LDB(dst, b, h) do { _Pragma("unroll") for (int n = 0; n < 2; ++n) _Pragma("unroll") for (int k = 0; k < 2; ++k) dst[n][k] = *(const PG8_LAS bf16x8*)(lds + PG8_SB(b, h) + boff + n * 2048 + k * 1024); } while (0)
; #define PG8_MMA(ai, bj, At, Bt) do { __builtin_amdgcn_s_setprio(1); _Pragma("unroll") for (int m = 0; m < 4; ++m) _Pragma("unroll") for (int n = 0; n < 2; ++n) _Pragma("unroll") for (int k = 0; k < 2; ++k) \
;         acc[ai][bj][m][n] = __builtin_amdgcn_mfma_f32_16x16x32_bf16(Bt[n][k], At[m][k], acc[ai][bj][m][n], 0, 0, 0); __builtin_amdgcn_s_setprio(0); } while (0)
; #define PG8_WAIT_V(n) asm volatile("s_waitcnt vmcnt(" #n ")" ::: "memory")
; #define PG8_WAIT_L(n) asm volatile("s_waitcnt lgkmcnt(" #n ")" ::: "memory")
; #define PG8_BAR __builtin_amdgcn_s_barrier()
; #define PG8_SCHED __builtin_amdgcn_sched_barrier(0)
; template <class Epi, class Sched, bool ALIGN_EPI = false, bool SP2 = false>
; __device__ __forceinline__ void gemm_phase(PG8_LAS unsigned char* lds, const Gemm g, const Sched& S, const Epi& E) {
;     ...
;         for (int t = 0; t < nt; t += 2) {
;             const bool last = (t == nt - 2);
;     ...
;             PG8_LDB(B0, 1, 0); PG8_LDB(B1, 1, 1); PG8_SCHED; PG8_LDA(At, 1, 0); PG8_STAGE(PG8_SA(0, 1), a2 + hstep, voffA);
;             PG8_WAIT_V(8); PG8_WAIT_L(0); PG8_BAR; PG8_MMA(0, 0, At, B0); PG8_MMA(0, 1, At, B1); PG8_BAR; PG8_SCHED;
;             PG8_LDA(At, 1, 1); PG8_STAGE(PG8_SB(1, 0), b3, voffB); PG8_STAGE(PG8_SB(1, 1), b3 + hstep, voffB); PG8_STAGE(PG8_SA(1, 0), a3, voffA);
;             PG8_WAIT_V(8); PG8_WAIT_L(0); PG8_BAR; PG8_MMA(1, 0, At, B0); PG8_MMA(1, 1, At, B1); PG8_BAR; PG8_SCHED;
	s_add_i32 s58, 0, 0x18000
	s_add_i32 s59, 0, 0x1c000
	v_add_u32_e32 v140, s58, v190
	v_add_u32_e32 v176, s59, v190
	ds_read_b128 v[128:131], v140
	ds_read_b128 v[132:135], v140 offset:1024
	ds_read_b128 v[136:139], v140 offset:2048
	ds_read_b128 v[140:143], v140 offset:3072
	ds_read_b128 v[144:147], v176
	ds_read_b128 v[148:151], v176 offset:1024
	ds_read_b128 v[172:175], v176 offset:2048
	ds_read_b128 v[176:179], v176 offset:3072
	s_add_u32 s28, s28, 0x40000
	s_addc_u32 s29, s29, 0
	s_mov_b32 m0, s41
	ds_read_b128 v[180:183], v193 offset:32768
	ds_read_b128 v[184:187], v193 offset:33792
	ds_read_b128 v[196:199], v193 offset:34816
	ds_read_b128 v[200:203], v193 offset:35840
	ds_read_b128 v[204:207], v193 offset:36864
	ds_read_b128 v[208:211], v193 offset:37888
	ds_read_b128 v[212:215], v193 offset:38912
	ds_read_b128 v[216:219], v193 offset:39936
	global_load_lds_dwordx4 v158, s[28:29]
	s_mov_b32 m0, s42
	s_nop 0
	global_load_lds_dwordx4 v154, s[28:29]
	s_waitcnt vmcnt(8)
	s_waitcnt lgkmcnt(0)
	s_barrier
	s_setprio 1
	s_waitcnt lgkmcnt(0)
	v_mfma_f32_16x16x32_bf16 v[124:127], v[128:131], v[180:183], v[124:127]
	v_mfma_f32_16x16x32_bf16 v[120:123], v[136:139], v[180:183], v[120:123]
	v_mfma_f32_16x16x32_bf16 v[108:111], v[128:131], v[196:199], v[108:111]
	v_mfma_f32_16x16x32_bf16 v[104:107], v[136:139], v[196:199], v[104:107]
	v_mfma_f32_16x16x32_bf16 v[92:95], v[128:131], v[204:207], v[92:95]
	v_mfma_f32_16x16x32_bf16 v[84:87], v[136:139], v[204:207], v[84:87]
	v_mfma_f32_16x16x32_bf16 v[76:79], v[128:131], v[212:215], v[76:79]
	v_mfma_f32_16x16x32_bf16 v[72:75], v[136:139], v[212:215], v[72:75]
	v_mfma_f32_16x16x32_bf16 v[124:127], v[132:135], v[184:187], v[124:127]
	v_mfma_f32_16x16x32_bf16 v[120:123], v[140:143], v[184:187], v[120:123]
	v_mfma_f32_16x16x32_bf16 v[108:111], v[132:135], v[200:203], v[108:111]
	v_mfma_f32_16x16x32_bf16 v[104:107], v[140:143], v[200:203], v[104:107]
	v_mfma_f32_16x16x32_bf16 v[92:95], v[132:135], v[208:211], v[92:95]
	v_mfma_f32_16x16x32_bf16 v[84:87], v[140:143], v[208:211], v[84:87]
	v_mfma_f32_16x16x32_bf16 v[76:79], v[132:135], v[216:219], v[76:79]
	v_mfma_f32_16x16x32_bf16 v[72:75], v[140:143], v[216:219], v[72:75]
	v_mfma_f32_16x16x32_bf16 v[116:119], v[144:147], v[180:183], v[116:119]
	v_mfma_f32_16x16x32_bf16 v[112:115], v[172:175], v[180:183], v[112:115]
	v_mfma_f32_16x16x32_bf16 v[100:103], v[144:147], v[196:199], v[100:103]
	v_mfma_f32_16x16x32_bf16 v[96:99], v[172:175], v[196:199], v[96:99]
	v_mfma_f32_16x16x32_bf16 v[88:91], v[144:147], v[204:207], v[88:91]
	v_mfma_f32_16x16x32_bf16 v[80:83], v[172:175], v[204:207], v[80:83]
	v_mfma_f32_16x16x32_bf16 v[68:71], v[144:147], v[212:215], v[68:71]
	v_mfma_f32_16x16x32_bf16 v[64:67], v[172:175], v[212:215], v[64:67]
	v_mfma_f32_16x16x32_bf16 v[116:119], v[148:151], v[184:187], v[116:119]
	v_mfma_f32_16x16x32_bf16 v[112:115], v[176:179], v[184:187], v[112:115]
	v_mfma_f32_16x16x32_bf16 v[100:103], v[148:151], v[200:203], v[100:103]
	v_mfma_f32_16x16x32_bf16 v[96:99], v[176:179], v[200:203], v[96:99]
	v_mfma_f32_16x16x32_bf16 v[88:91], v[148:151], v[208:211], v[88:91]
	v_mfma_f32_16x16x32_bf16 v[80:83], v[176:179], v[208:211], v[80:83]
	v_mfma_f32_16x16x32_bf16 v[68:71], v[148:151], v[216:219], v[68:71]
	v_mfma_f32_16x16x32_bf16 v[64:67], v[176:179], v[216:219], v[64:67]
	s_setprio 0
	s_barrier
	s_add_i32 s28, s58, s36
	v_lshl_add_u64 v[220:221], v[220:221], 0, s[10:11]
	s_mov_b32 m0, s28
	ds_read_b128 v[180:183], v193 offset:49152
	ds_read_b128 v[184:187], v193 offset:50176
	ds_read_b128 v[196:199], v193 offset:51200
	ds_read_b128 v[200:203], v193 offset:52224
	ds_read_b128 v[204:207], v193 offset:53248
	ds_read_b128 v[208:211], v193 offset:54272
	ds_read_b128 v[212:215], v193 offset:55296
	ds_read_b128 v[216:219], v193 offset:56320
	global_load_lds_dwordx4 v[220:221], off
	s_add_i32 m0, s28, 0x2000
	s_add_u32 s26, s26, 0x40080
	v_lshl_add_u64 v[220:221], v[222:223], 0, s[10:11]
	s_addc_u32 s27, s27, 0
	s_add_i32 s28, s59, s36
	global_load_lds_dwordx4 v[220:221], off
	s_mov_b32 m0, s28
	s_nop 0
	global_load_lds_dwordx4 v156, s[26:27]
	s_add_i32 m0, s28, 0x2000
	s_nop 0
	global_load_lds_dwordx4 v152, s[26:27]
	v_lshl_add_u64 v[220:221], v[224:225], 0, s[10:11]
	s_mov_b32 m0, s43
	s_nop 0
	global_load_lds_dwordx4 v[220:221], off
	v_lshl_add_u64 v[220:221], v[226:227], 0, s[10:11]
	s_mov_b32 m0, s44
	s_nop 0
	global_load_lds_dwordx4 v[220:221], off
	s_waitcnt vmcnt(8)
	s_waitcnt lgkmcnt(0)
	s_barrier
	s_setprio 1
	s_waitcnt lgkmcnt(0)
	v_mfma_f32_16x16x32_bf16 v[60:63], v[128:131], v[180:183], v[60:63]
	v_mfma_f32_16x16x32_bf16 v[52:55], v[136:139], v[180:183], v[52:55]
	v_mfma_f32_16x16x32_bf16 v[44:47], v[128:131], v[196:199], v[44:47]
	v_mfma_f32_16x16x32_bf16 v[40:43], v[136:139], v[196:199], v[40:43]
	v_mfma_f32_16x16x32_bf16 v[28:31], v[128:131], v[204:207], v[28:31]
	v_mfma_f32_16x16x32_bf16 v[20:23], v[136:139], v[204:207], v[20:23]
	v_mfma_f32_16x16x32_bf16 v[12:15], v[128:131], v[212:215], v[12:15]
	v_mfma_f32_16x16x32_bf16 v[8:11], v[136:139], v[212:215], v[8:11]
	v_mfma_f32_16x16x32_bf16 v[60:63], v[132:135], v[184:187], v[60:63]
	v_mfma_f32_16x16x32_bf16 v[52:55], v[140:143], v[184:187], v[52:55]
	v_mfma_f32_16x16x32_bf16 v[44:47], v[132:135], v[200:203], v[44:47]
	v_mfma_f32_16x16x32_bf16 v[40:43], v[140:143], v[200:203], v[40:43]
	v_mfma_f32_16x16x32_bf16 v[28:31], v[132:135], v[208:211], v[28:31]
	v_mfma_f32_16x16x32_bf16 v[20:23], v[140:143], v[208:211], v[20:23]
	v_mfma_f32_16x16x32_bf16 v[12:15], v[132:135], v[216:219], v[12:15]
	v_mfma_f32_16x16x32_bf16 v[8:11], v[140:143], v[216:219], v[8:11]
	v_mfma_f32_16x16x32_bf16 v[56:59], v[144:147], v[180:183], v[56:59]
	v_mfma_f32_16x16x32_bf16 v[48:51], v[172:175], v[180:183], v[48:51]
	v_mfma_f32_16x16x32_bf16 v[36:39], v[144:147], v[196:199], v[36:39]
	v_mfma_f32_16x16x32_bf16 v[32:35], v[172:175], v[196:199], v[32:35]
	v_mfma_f32_16x16x32_bf16 v[24:27], v[144:147], v[204:207], v[24:27]
	v_mfma_f32_16x16x32_bf16 v[16:19], v[172:175], v[204:207], v[16:19]
	v_mfma_f32_16x16x32_bf16 v[4:7], v[144:147], v[212:215], v[4:7]
	v_mfma_f32_16x16x32_bf16 v[0:3], v[172:175], v[212:215], v[0:3]
	v_mfma_f32_16x16x32_bf16 v[56:59], v[148:151], v[184:187], v[56:59]
	v_mfma_f32_16x16x32_bf16 v[48:51], v[176:179], v[184:187], v[48:51]
	v_mfma_f32_16x16x32_bf16 v[36:39], v[148:151], v[200:203], v[36:39]
	v_mfma_f32_16x16x32_bf16 v[32:35], v[176:179], v[200:203], v[32:35]
	v_mfma_f32_16x16x32_bf16 v[24:27], v[148:151], v[208:211], v[24:27]
	v_mfma_f32_16x16x32_bf16 v[16:19], v[176:179], v[208:211], v[16:19]
	v_mfma_f32_16x16x32_bf16 v[4:7], v[148:151], v[216:219], v[4:7]
	v_mfma_f32_16x16x32_bf16 v[0:3], v[176:179], v[216:219], v[0:3]
	s_setprio 0
	s_barrier
	s_add_i32 s57, s57, 2
	s_add_u32 s24, s24, 0x100
	s_addc_u32 s25, s25, 0
	s_add_u32 s55, s55, 0x100
	s_addc_u32 s56, s56, 0
	s_cmp_gt_u32 s57, 13
	s_cbranch_scc0 .LBB0_969
	s_and_b64 vcc, exec, s[12:13]
	s_cbranch_vccz .LBB0_972
	s_barrier

; #define PG8_STAGE(bufoff, gbase, voff) do { _Pragma("unroll") for (int _i = 0; _i < 2; ++_i) \
;         __builtin_amdgcn_global_load_lds((const unsigned*)((const char*)(gbase) + (voff)[_i]), (PG8_LAS unsigned*)(lds + (bufoff) + ldsw + _i * 8192), 16, 0, 0); } while (0)
; #define PG8_LDA(dst, b, h) do { _Pragma("unroll") for (int m = 0; m < 4; ++m) _Pragma("unroll") for (int k = 0; k < 2; ++k) dst[m][k] = *(const PG8_LAS bf16x8*)(lds + PG8_SA(b, h) + aoff + m * 2048 + k * 1024); } while (0)
; #define PG8_LDB(dst, b, h) do { _Pragma("unroll") for (int n = 0; n < 2; ++n) _Pragma("unroll") for (int k = 0; k < 2; ++k) dst[n][k] = *(const PG8_LAS bf16x8*)(lds + PG8_SB(b, h) + boff + n * 2048 + k * 1024); } while (0)
; #define PG8_MMA(ai, bj, At, Bt) do { __builtin_amdgcn_s_setprio(1); _Pragma("unroll") for (int m = 0; m < 4; ++m) _Pragma("unroll") for (int n = 0; n < 2; ++n) _Pragma("unroll") for (int k = 0; k < 2; ++k) \
;         acc[ai][bj][m][n] = __builtin_amdgcn_mfma_f32_16x16x32_bf16(Bt[n][k], At[m][k], acc[ai][bj][m][n], 0, 0, 0); __builtin_amdgcn_s_setprio(0); } while (0)
; #define PG8_WAIT_V(n) asm volatile("s_waitcnt vmcnt(" #n ")" ::: "memory")
; #define PG8_WAIT_L(n) asm volatile("s_waitcnt lgkmcnt(" #n ")" ::: "memory")
; #define PG8_BAR __builtin_amdgcn_s_barrier()
; template <class Epi, class Sched, bool ALIGN_EPI = false, bool SP2 = false>
; __device__ __forceinline__ void gemm_phase(PG8_LAS unsigned char* lds, const Gemm g, const Sched& S, const Epi& E) {
;     ...
;             const char* a1 = cA + (size_t)(t + 1) * kstep;
;             const char* a2 = last ? nA : cA + (size_t)(t + 2) * kstep; const char* b2 = last ? nB : cB + (size_t)(t + 2) * kstep;
;             const char* a3 = a2 + kstep; const char* b3 = b2 + kstep;
;             if (last && has_next) S.a_ready(nxt);
;             if constexpr (SP2) {
;             PG8_LDB(B0, 0, 0); PG8_LDB(B1, 0, 1); PG8_SCHED; PG8_LDA(At, 0, 0); PG8_STAGE(PG8_SA(1, 1), a1 + hstep, voffA);
;             PG8_WAIT_V(8); PG8_WAIT_L(0); PG8_BAR; PG8_MMA(0, 0, At, B0); PG8_MMA(0, 1, At, B1); PG8_BAR; PG8_SCHED;
;             PG8_LDA(At, 0, 1); PG8_STAGE(PG8_SB(0, 0), b2, voffB); PG8_STAGE(PG8_SB(0, 1), b2 + hstep, voffB); PG8_STAGE(PG8_SA(0, 0), a2, voffA);
;             PG8_WAIT_V(8); PG8_WAIT_L(0); PG8_BAR; PG8_MMA(1, 0, At, B0); PG8_MMA(1, 1, At, B1); PG8_BAR; PG8_SCHED;
.LBB0_1052:
	ds_read_b128 v[146:149], v153
	ds_read_b128 v[156:159], v153 offset:1024
	ds_read_b128 v[160:163], v153 offset:2048
	ds_read_b128 v[164:167], v153 offset:3072
	ds_read_b128 v[168:171], v154
	ds_read_b128 v[172:175], v154 offset:1024
	ds_read_b128 v[176:179], v154 offset:2048
	ds_read_b128 v[180:183], v154 offset:3072
	s_add_u32 s24, s22, 0x100
	s_addc_u32 s25, s23, 0
	s_cmp_eq_u32 s56, 40
	s_cselect_b32 s29, s3, s25
	s_cselect_b32 s28, s2, s24
	s_cselect_b32 s27, s21, s55
	s_cselect_b32 s26, s20, s54
	s_add_i32 m0, s38, 0xc000
	ds_read_b128 v[184:187], v155
	ds_read_b128 v[188:191], v155 offset:1024
	ds_read_b128 v[192:195], v155 offset:2048
	ds_read_b128 v[196:199], v155 offset:3072
	ds_read_b128 v[200:203], v155 offset:4096
	ds_read_b128 v[204:207], v155 offset:5120
	ds_read_b128 v[208:211], v155 offset:6144
	ds_read_b128 v[212:215], v155 offset:7168
	global_load_lds_dwordx4 v138, s[22:23]
	s_add_i32 m0, s38, 0xe000
	s_nop 0
	global_load_lds_dwordx4 v140, s[22:23]
	s_waitcnt vmcnt(8)
	s_waitcnt lgkmcnt(0)
	s_barrier
	s_setprio 1
	s_waitcnt lgkmcnt(0)
	v_mfma_f32_16x16x32_bf16 v[124:127], v[146:149], v[184:187], v[124:127]
	v_mfma_f32_16x16x32_bf16 v[120:123], v[160:163], v[184:187], v[120:123]
	v_mfma_f32_16x16x32_bf16 v[116:119], v[146:149], v[192:195], v[116:119]
	v_mfma_f32_16x16x32_bf16 v[112:115], v[160:163], v[192:195], v[112:115]
	v_mfma_f32_16x16x32_bf16 v[92:95], v[146:149], v[200:203], v[92:95]
	v_mfma_f32_16x16x32_bf16 v[88:91], v[160:163], v[200:203], v[88:91]
	v_mfma_f32_16x16x32_bf16 v[76:79], v[146:149], v[208:211], v[76:79]
	v_mfma_f32_16x16x32_bf16 v[72:75], v[160:163], v[208:211], v[72:75]
	v_mfma_f32_16x16x32_bf16 v[124:127], v[156:159], v[188:191], v[124:127]
	v_mfma_f32_16x16x32_bf16 v[120:123], v[164:167], v[188:191], v[120:123]
	v_mfma_f32_16x16x32_bf16 v[116:119], v[156:159], v[196:199], v[116:119]
	v_mfma_f32_16x16x32_bf16 v[112:115], v[164:167], v[196:199], v[112:115]
	v_mfma_f32_16x16x32_bf16 v[92:95], v[156:159], v[204:207], v[92:95]
	v_mfma_f32_16x16x32_bf16 v[88:91], v[164:167], v[204:207], v[88:91]
	v_mfma_f32_16x16x32_bf16 v[76:79], v[156:159], v[212:215], v[76:79]
	v_mfma_f32_16x16x32_bf16 v[72:75], v[164:167], v[212:215], v[72:75]
	v_mfma_f32_16x16x32_bf16 v[108:111], v[168:171], v[184:187], v[108:111]
	v_mfma_f32_16x16x32_bf16 v[104:107], v[176:179], v[184:187], v[104:107]
	v_mfma_f32_16x16x32_bf16 v[100:103], v[168:171], v[192:195], v[100:103]
	v_mfma_f32_16x16x32_bf16 v[96:99], v[176:179], v[192:195], v[96:99]
	v_mfma_f32_16x16x32_bf16 v[84:87], v[168:171], v[200:203], v[84:87]
	v_mfma_f32_16x16x32_bf16 v[80:83], v[176:179], v[200:203], v[80:83]
	v_mfma_f32_16x16x32_bf16 v[68:71], v[168:171], v[208:211], v[68:71]
	v_mfma_f32_16x16x32_bf16 v[64:67], v[176:179], v[208:211], v[64:67]
	v_mfma_f32_16x16x32_bf16 v[108:111], v[172:175], v[188:191], v[108:111]
	v_mfma_f32_16x16x32_bf16 v[104:107], v[180:183], v[188:191], v[104:107]
	v_mfma_f32_16x16x32_bf16 v[100:103], v[172:175], v[196:199], v[100:103]
	v_mfma_f32_16x16x32_bf16 v[96:99], v[180:183], v[196:199], v[96:99]
	v_mfma_f32_16x16x32_bf16 v[84:87], v[172:175], v[204:207], v[84:87]
	v_mfma_f32_16x16x32_bf16 v[80:83], v[180:183], v[204:207], v[80:83]
	v_mfma_f32_16x16x32_bf16 v[68:71], v[172:175], v[212:215], v[68:71]
	v_mfma_f32_16x16x32_bf16 v[64:67], v[180:183], v[212:215], v[64:67]
	s_setprio 0
	s_barrier
	s_add_i32 s22, s46, s37
	v_lshl_add_u64 v[150:151], s[26:27], 0, v[130:131]
	s_mov_b32 m0, s22
	ds_read_b128 v[184:187], v155 offset:16384
	ds_read_b128 v[188:191], v155 offset:17408
	ds_read_b128 v[192:195], v155 offset:18432
	ds_read_b128 v[196:199], v155 offset:19456
	ds_read_b128 v[200:203], v155 offset:20480
	ds_read_b128 v[204:207], v155 offset:21504
	ds_read_b128 v[208:211], v155 offset:22528
	ds_read_b128 v[212:215], v155 offset:23552
	global_load_lds_dwordx4 v[150:151], off
	s_add_i32 m0, s22, 0x2000
	s_add_u32 s22, s26, 0xb0000
	v_lshl_add_u64 v[216:217], s[26:27], 0, v[134:135]
	s_addc_u32 s23, s27, 0
	s_add_i32 s57, s47, s37
	global_load_lds_dwordx4 v[216:217], off
	s_mov_b32 m0, s57
	v_lshl_add_u64 v[220:221], s[28:29], 0, v[132:133]
	global_load_lds_dwordx4 v130, s[22:23]
	s_add_i32 m0, s57, 0x2000
	s_nop 0
	global_load_lds_dwordx4 v134, s[22:23]
	v_lshl_add_u64 v[218:219], s[28:29], 0, v[128:129]
	s_mov_b32 m0, s38
	s_nop 0
	global_load_lds_dwordx4 v[218:219], off
	s_mov_b32 m0, s39
	s_nop 0
	global_load_lds_dwordx4 v[220:221], off
	s_waitcnt vmcnt(8)
	s_waitcnt lgkmcnt(0)
	s_barrier
	s_setprio 1
	s_waitcnt lgkmcnt(0)
	v_mfma_f32_16x16x32_bf16 v[60:63], v[146:149], v[184:187], v[60:63]
	v_mfma_f32_16x16x32_bf16 v[56:59], v[160:163], v[184:187], v[56:59]
	v_mfma_f32_16x16x32_bf16 v[44:47], v[146:149], v[192:195], v[44:47]
	v_mfma_f32_16x16x32_bf16 v[40:43], v[160:163], v[192:195], v[40:43]
	v_mfma_f32_16x16x32_bf16 v[28:31], v[146:149], v[200:203], v[28:31]
	v_mfma_f32_16x16x32_bf16 v[24:27], v[160:163], v[200:203], v[24:27]
	v_mfma_f32_16x16x32_bf16 v[12:15], v[146:149], v[208:211], v[12:15]
	v_mfma_f32_16x16x32_bf16 v[8:11], v[160:163], v[208:211], v[8:11]
	v_mfma_f32_16x16x32_bf16 v[60:63], v[156:159], v[188:191], v[60:63]
	v_mfma_f32_16x16x32_bf16 v[56:59], v[164:167], v[188:191], v[56:59]
	v_mfma_f32_16x16x32_bf16 v[44:47], v[156:159], v[196:199], v[44:47]
	v_mfma_f32_16x16x32_bf16 v[40:43], v[164:167], v[196:199], v[40:43]
	v_mfma_f32_16x16x32_bf16 v[28:31], v[156:159], v[204:207], v[28:31]
	v_mfma_f32_16x16x32_bf16 v[24:27], v[164:167], v[204:207], v[24:27]
	v_mfma_f32_16x16x32_bf16 v[12:15], v[156:159], v[212:215], v[12:15]
	v_mfma_f32_16x16x32_bf16 v[8:11], v[164:167], v[212:215], v[8:11]
	v_mfma_f32_16x16x32_bf16 v[52:55], v[168:171], v[184:187], v[52:55]
	v_mfma_f32_16x16x32_bf16 v[48:51], v[176:179], v[184:187], v[48:51]
	v_mfma_f32_16x16x32_bf16 v[36:39], v[168:171], v[192:195], v[36:39]
	v_mfma_f32_16x16x32_bf16 v[32:35], v[176:179], v[192:195], v[32:35]
	v_mfma_f32_16x16x32_bf16 v[20:23], v[168:171], v[200:203], v[20:23]
	v_mfma_f32_16x16x32_bf16 v[16:19], v[176:179], v[200:203], v[16:19]
	v_mfma_f32_16x16x32_bf16 v[4:7], v[168:171], v[208:211], v[4:7]
	v_mfma_f32_16x16x32_bf16 v[0:3], v[176:179], v[208:211], v[0:3]
	v_mfma_f32_16x16x32_bf16 v[52:55], v[172:175], v[188:191], v[52:55]
	v_mfma_f32_16x16x32_bf16 v[48:51], v[180:183], v[188:191], v[48:51]
	v_mfma_f32_16x16x32_bf16 v[36:39], v[172:175], v[196:199], v[36:39]
	v_mfma_f32_16x16x32_bf16 v[32:35], v[180:183], v[196:199], v[32:35]
	v_mfma_f32_16x16x32_bf16 v[20:23], v[172:175], v[204:207], v[20:23]
	v_mfma_f32_16x16x32_bf16 v[16:19], v[180:183], v[204:207], v[16:19]
	v_mfma_f32_16x16x32_bf16 v[4:7], v[172:175], v[212:215], v[4:7]
	v_mfma_f32_16x16x32_bf16 v[0:3], v[180:183], v[212:215], v[0:3]
	s_setprio 0
	s_barrier
; #define PG8_STAGE(bufoff, gbase, voff) do { _Pragma("unroll") for (int _i = 0; _i < 2; ++_i) \
;         __builtin_amdgcn_global_load_lds((const unsigned*)((const char*)(gbase) + (voff)[_i]), (PG8_LAS unsigned*)(lds + (bufoff) + ldsw + _i * 8192), 16, 0, 0); } while (0)
; #define PG8_LDA(dst, b, h) do { _Pragma("unroll") for (int m = 0; m < 4; ++m) _Pragma("unroll") for (int k = 0; k < 2; ++k) dst[m][k] = *(const PG8_LAS bf16x8*)(lds + PG8_SA(b, h) + aoff + m * 2048 + k * 1024); } while (0)
; #define PG8_LDB(dst, b, h) do { _Pragma("unroll") for (int n = 0; n < 2; ++n) _Pragma("unroll") for (int k = 0; k < 2; ++k) dst[n][k] = *(const PG8_LAS bf16x8*)(lds + PG8_SB(b, h) + boff + n * 2048 + k * 1024); } while (0)
; #define PG8_MMA(ai, bj, At, Bt) do { __builtin_amdgcn_s_setprio(1); _Pragma("unroll") for (int m = 0; m < 4; ++m) _Pragma("unroll") for (int n = 0; n < 2; ++n) _Pragma("unroll") for (int k = 0; k < 2; ++k) \
;         acc[ai][bj][m][n] = __builtin_amdgcn_mfma_f32_16x16x32_bf16(Bt[n][k], At[m][k], acc[ai][bj][m][n], 0, 0, 0); __builtin_amdgcn_s_setprio(0); } while (0)
; #define PG8_WAIT_V(n) asm volatile("s_waitcnt vmcnt(" #n ")" ::: "memory")
; #define PG8_WAIT_L(n) asm volatile("s_waitcnt lgkmcnt(" #n ")" ::: "memory")
; #define PG8_BAR __builtin_amdgcn_s_barrier()
; #define PG8_SCHED __builtin_amdgcn_sched_barrier(0)
; template <class Epi, class Sched, bool ALIGN_EPI = false, bool SP2 = false>
; __device__ __forceinline__ void gemm_phase(PG8_LAS unsigned char* lds, const Gemm g, const Sched& S, const Epi& E) {
;     ...
;         for (int t = 0; t < nt; t += 2) {
;             const bool last = (t == nt - 2);
;     ...
;             PG8_LDB(B0, 1, 0); PG8_LDB(B1, 1, 1); PG8_SCHED; PG8_LDA(At, 1, 0); PG8_STAGE(PG8_SA(0, 1), a2 + hstep, voffA);
;             PG8_WAIT_V(8); PG8_WAIT_L(0); PG8_BAR; PG8_MMA(0, 0, At, B0); PG8_MMA(0, 1, At, B1); PG8_BAR; PG8_SCHED;
;             PG8_LDA(At, 1, 1); PG8_STAGE(PG8_SB(1, 0), b3, voffB); PG8_STAGE(PG8_SB(1, 1), b3 + hstep, voffB); PG8_STAGE(PG8_SA(1, 0), a3, voffA);
;             PG8_WAIT_V(8); PG8_WAIT_L(0); PG8_BAR; PG8_MMA(1, 0, At, B0); PG8_MMA(1, 1, At, B1); PG8_BAR; PG8_SCHED;
	s_add_i32 s57, 0, 0x18000
	s_add_i32 s58, 0, 0x1c000
	v_add_u32_e32 v164, s57, v152
	v_add_u32_e32 v180, s58, v152
	ds_read_b128 v[146:149], v164
	ds_read_b128 v[156:159], v164 offset:1024
	ds_read_b128 v[160:163], v164 offset:2048
	ds_read_b128 v[164:167], v164 offset:3072
	ds_read_b128 v[168:171], v180
	ds_read_b128 v[172:175], v180 offset:1024
	ds_read_b128 v[176:179], v180 offset:2048
	ds_read_b128 v[180:183], v180 offset:3072
	s_add_u32 s22, s28, 0xb0000
	s_addc_u32 s23, s29, 0
	s_mov_b32 m0, s40
	ds_read_b128 v[184:187], v155 offset:32768
	ds_read_b128 v[188:191], v155 offset:33792
	ds_read_b128 v[192:195], v155 offset:34816
	ds_read_b128 v[196:199], v155 offset:35840
	ds_read_b128 v[200:203], v155 offset:36864
	ds_read_b128 v[204:207], v155 offset:37888
	ds_read_b128 v[208:211], v155 offset:38912
	ds_read_b128 v[212:215], v155 offset:39936
	global_load_lds_dwordx4 v128, s[22:23]
	s_mov_b32 m0, s41
	s_nop 0
	global_load_lds_dwordx4 v132, s[22:23]
	s_waitcnt vmcnt(8)
	s_waitcnt lgkmcnt(0)
	s_barrier
	s_setprio 1
	s_waitcnt lgkmcnt(0)
	v_mfma_f32_16x16x32_bf16 v[124:127], v[146:149], v[184:187], v[124:127]
	v_mfma_f32_16x16x32_bf16 v[120:123], v[160:163], v[184:187], v[120:123]
	v_mfma_f32_16x16x32_bf16 v[116:119], v[146:149], v[192:195], v[116:119]
	v_mfma_f32_16x16x32_bf16 v[112:115], v[160:163], v[192:195], v[112:115]
	v_mfma_f32_16x16x32_bf16 v[92:95], v[146:149], v[200:203], v[92:95]
	v_mfma_f32_16x16x32_bf16 v[88:91], v[160:163], v[200:203], v[88:91]
	v_mfma_f32_16x16x32_bf16 v[76:79], v[146:149], v[208:211], v[76:79]
	v_mfma_f32_16x16x32_bf16 v[72:75], v[160:163], v[208:211], v[72:75]
	v_mfma_f32_16x16x32_bf16 v[124:127], v[156:159], v[188:191], v[124:127]
	v_mfma_f32_16x16x32_bf16 v[120:123], v[164:167], v[188:191], v[120:123]
	v_mfma_f32_16x16x32_bf16 v[116:119], v[156:159], v[196:199], v[116:119]
	v_mfma_f32_16x16x32_bf16 v[112:115], v[164:167], v[196:199], v[112:115]
	v_mfma_f32_16x16x32_bf16 v[92:95], v[156:159], v[204:207], v[92:95]
	v_mfma_f32_16x16x32_bf16 v[88:91], v[164:167], v[204:207], v[88:91]
	v_mfma_f32_16x16x32_bf16 v[76:79], v[156:159], v[212:215], v[76:79]
	v_mfma_f32_16x16x32_bf16 v[72:75], v[164:167], v[212:215], v[72:75]
	v_mfma_f32_16x16x32_bf16 v[108:111], v[168:171], v[184:187], v[108:111]
	v_mfma_f32_16x16x32_bf16 v[104:107], v[176:179], v[184:187], v[104:107]
	v_mfma_f32_16x16x32_bf16 v[100:103], v[168:171], v[192:195], v[100:103]
	v_mfma_f32_16x16x32_bf16 v[96:99], v[176:179], v[192:195], v[96:99]
	v_mfma_f32_16x16x32_bf16 v[84:87], v[168:171], v[200:203], v[84:87]
	v_mfma_f32_16x16x32_bf16 v[80:83], v[176:179], v[200:203], v[80:83]
	v_mfma_f32_16x16x32_bf16 v[68:71], v[168:171], v[208:211], v[68:71]
	v_mfma_f32_16x16x32_bf16 v[64:67], v[176:179], v[208:211], v[64:67]
	v_mfma_f32_16x16x32_bf16 v[108:111], v[172:175], v[188:191], v[108:111]
	v_mfma_f32_16x16x32_bf16 v[104:107], v[180:183], v[188:191], v[104:107]
	v_mfma_f32_16x16x32_bf16 v[100:103], v[172:175], v[196:199], v[100:103]
	v_mfma_f32_16x16x32_bf16 v[96:99], v[180:183], v[196:199], v[96:99]
	v_mfma_f32_16x16x32_bf16 v[84:87], v[172:175], v[204:207], v[84:87]
	v_mfma_f32_16x16x32_bf16 v[80:83], v[180:183], v[204:207], v[80:83]
	v_mfma_f32_16x16x32_bf16 v[68:71], v[172:175], v[212:215], v[68:71]
	v_mfma_f32_16x16x32_bf16 v[64:67], v[180:183], v[212:215], v[64:67]
	s_setprio 0
	s_barrier
	s_add_i32 s22, s57, s37
	v_lshl_add_u64 v[150:151], v[150:151], 0, s[8:9]
	s_mov_b32 m0, s22
	ds_read_b128 v[184:187], v155 offset:49152
	ds_read_b128 v[188:191], v155 offset:50176
	ds_read_b128 v[192:195], v155 offset:51200
	ds_read_b128 v[196:199], v155 offset:52224
	ds_read_b128 v[200:203], v155 offset:53248
	ds_read_b128 v[204:207], v155 offset:54272
	ds_read_b128 v[208:211], v155 offset:55296
	ds_read_b128 v[212:215], v155 offset:56320
	global_load_lds_dwordx4 v[150:151], off
	s_add_i32 m0, s22, 0x2000
	s_add_u32 s22, s26, 0xb0080
	v_lshl_add_u64 v[150:151], v[216:217], 0, s[8:9]
	s_addc_u32 s23, s27, 0
	s_add_i32 s26, s58, s37
	global_load_lds_dwordx4 v[150:151], off
	s_mov_b32 m0, s26
	s_nop 0
	global_load_lds_dwordx4 v130, s[22:23]
	s_add_i32 m0, s26, 0x2000
	s_nop 0
	global_load_lds_dwordx4 v134, s[22:23]
	v_lshl_add_u64 v[150:151], v[218:219], 0, s[8:9]
	s_mov_b32 m0, s43
	s_nop 0
	global_load_lds_dwordx4 v[150:151], off
	v_lshl_add_u64 v[150:151], v[220:221], 0, s[8:9]
	s_mov_b32 m0, s44
	s_nop 0
	global_load_lds_dwordx4 v[150:151], off
	s_waitcnt vmcnt(8)
	s_waitcnt lgkmcnt(0)
	s_barrier
	s_setprio 1
	s_waitcnt lgkmcnt(0)
	v_mfma_f32_16x16x32_bf16 v[60:63], v[146:149], v[184:187], v[60:63]
	v_mfma_f32_16x16x32_bf16 v[56:59], v[160:163], v[184:187], v[56:59]
	v_mfma_f32_16x16x32_bf16 v[44:47], v[146:149], v[192:195], v[44:47]
	v_mfma_f32_16x16x32_bf16 v[40:43], v[160:163], v[192:195], v[40:43]
	v_mfma_f32_16x16x32_bf16 v[28:31], v[146:149], v[200:203], v[28:31]
	v_mfma_f32_16x16x32_bf16 v[24:27], v[160:163], v[200:203], v[24:27]
	v_mfma_f32_16x16x32_bf16 v[12:15], v[146:149], v[208:211], v[12:15]
	v_mfma_f32_16x16x32_bf16 v[8:11], v[160:163], v[208:211], v[8:11]
	v_mfma_f32_16x16x32_bf16 v[60:63], v[156:159], v[188:191], v[60:63]
	v_mfma_f32_16x16x32_bf16 v[56:59], v[164:167], v[188:191], v[56:59]
	v_mfma_f32_16x16x32_bf16 v[44:47], v[156:159], v[196:199], v[44:47]
	v_mfma_f32_16x16x32_bf16 v[40:43], v[164:167], v[196:199], v[40:43]
	v_mfma_f32_16x16x32_bf16 v[28:31], v[156:159], v[204:207], v[28:31]
	v_mfma_f32_16x16x32_bf16 v[24:27], v[164:167], v[204:207], v[24:27]
	v_mfma_f32_16x16x32_bf16 v[12:15], v[156:159], v[212:215], v[12:15]
	v_mfma_f32_16x16x32_bf16 v[8:11], v[164:167], v[212:215], v[8:11]
	v_mfma_f32_16x16x32_bf16 v[52:55], v[168:171], v[184:187], v[52:55]
	v_mfma_f32_16x16x32_bf16 v[48:51], v[176:179], v[184:187], v[48:51]
	v_mfma_f32_16x16x32_bf16 v[36:39], v[168:171], v[192:195], v[36:39]
	v_mfma_f32_16x16x32_bf16 v[32:35], v[176:179], v[192:195], v[32:35]
	v_mfma_f32_16x16x32_bf16 v[20:23], v[168:171], v[200:203], v[20:23]
	v_mfma_f32_16x16x32_bf16 v[16:19], v[176:179], v[200:203], v[16:19]
	v_mfma_f32_16x16x32_bf16 v[4:7], v[168:171], v[208:211], v[4:7]
	v_mfma_f32_16x16x32_bf16 v[0:3], v[176:179], v[208:211], v[0:3]
	v_mfma_f32_16x16x32_bf16 v[52:55], v[172:175], v[188:191], v[52:55]
	v_mfma_f32_16x16x32_bf16 v[48:51], v[180:183], v[188:191], v[48:51]
	v_mfma_f32_16x16x32_bf16 v[36:39], v[172:175], v[196:199], v[36:39]
	v_mfma_f32_16x16x32_bf16 v[32:35], v[180:183], v[196:199], v[32:35]
	v_mfma_f32_16x16x32_bf16 v[20:23], v[172:175], v[204:207], v[20:23]
	v_mfma_f32_16x16x32_bf16 v[16:19], v[180:183], v[204:207], v[16:19]
	v_mfma_f32_16x16x32_bf16 v[4:7], v[172:175], v[212:215], v[4:7]
	v_mfma_f32_16x16x32_bf16 v[0:3], v[180:183], v[212:215], v[0:3]
	s_setprio 0
	s_barrier
	s_add_i32 s56, s56, 2
	s_add_u32 s54, s54, 0x100
	s_addc_u32 s55, s55, 0
	s_cmp_gt_u32 s56, 41
	s_mov_b64 s[22:23], s[24:25]
	s_cbranch_scc0 .LBB0_1052
	s_and_b64 vcc, exec, s[10:11]
	s_cbranch_vccz .LBB0_1055
	s_barrier
